# mlstm seq-loop counted vmcnt + v83 temp rename; GEMM K-loop: drop mid-SP setprio flip pair and redundant post-barrier lgkmcnt(0)
# baseline (speedup 1.0000x reference)
; #define PG8_STAGE(bufoff, gbase, voff) do { _Pragma("unroll") for (int _i = 0; _i < 2; ++_i) \
;         __builtin_amdgcn_global_load_lds((const unsigned*)((const char*)(gbase) + (voff)[_i]), (PG8_LAS unsigned*)(lds + (bufoff) + ldsw + _i * 8192), 16, 0, 0); } while (0)
; #define PG8_LDA(dst, b, h) do { _Pragma("unroll") for (int m = 0; m < 4; ++m) _Pragma("unroll") for (int k = 0; k < 2; ++k) dst[m][k] = *(const PG8_LAS bf16x8*)(lds + PG8_SA(b, h) + aoff + m * 2048 + k * 1024); } while (0)
; #define PG8_LDB(dst, b, h) do { _Pragma("unroll") for (int n = 0; n < 2; ++n) _Pragma("unroll") for (int k = 0; k < 2; ++k) dst[n][k] = *(const PG8_LAS bf16x8*)(lds + PG8_SB(b, h) + boff + n * 2048 + k * 1024); } while (0)
; #define PG8_MMA(ai, bj, At, Bt) do { __builtin_amdgcn_s_setprio(1); _Pragma("unroll") for (int m = 0; m < 4; ++m) _Pragma("unroll") for (int n = 0; n < 2; ++n) _Pragma("unroll") for (int k = 0; k < 2; ++k) \
;         acc[ai][bj][m][n] = __builtin_amdgcn_mfma_f32_16x16x32_bf16(Bt[n][k], At[m][k], acc[ai][bj][m][n], 0, 0, 0); __builtin_amdgcn_s_setprio(0); } while (0)
; #define PG8_WAIT_V(n) asm volatile("s_waitcnt vmcnt(" #n ")" ::: "memory")
; #define PG8_BAR __builtin_amdgcn_s_barrier()
; template <class Epi, class Sched, bool ALIGN_EPI = false, bool SP2 = false>
; __device__ __forceinline__ void gemm_phase(PG8_LAS unsigned char* lds, const Gemm g, const Sched& S, const Epi& E) {
;     ...
;         for (int t = 0; t < nt; t += 2) {
;             const bool last = (t == nt - 2);
;             const char* a1 = cA + (size_t)(t + 1) * kstep;
;             const char* a2 = last ? nA : cA + (size_t)(t + 2) * kstep; const char* b2 = last ? nB : cB + (size_t)(t + 2) * kstep;
;             const char* a3 = a2 + kstep; const char* b3 = b2 + kstep;
;             if (last && has_next) S.a_ready(nxt);
;             if constexpr (SP2) {
;             PG8_LDB(B0, 0, 0); PG8_LDB(B1, 0, 1); PG8_SCHED; PG8_LDA(At, 0, 0); PG8_STAGE(PG8_SA(1, 1), a1 + hstep, voffA);
;             PG8_WAIT_V(8); PG8_WAIT_L(0); PG8_BAR; PG8_MMA(0, 0, At, B0); PG8_MMA(0, 1, At, B1); PG8_BAR; PG8_SCHED;
;             PG8_LDA(At, 0, 1); PG8_STAGE(PG8_SB(0, 0), b2, voffB); PG8_STAGE(PG8_SB(0, 1), b2 + hstep, voffB); PG8_STAGE(PG8_SA(0, 0), a2, voffA);
;             PG8_WAIT_V(8); PG8_WAIT_L(0); PG8_BAR; PG8_MMA(1, 0, At, B0); PG8_MMA(1, 1, At, B1); PG8_BAR; PG8_SCHED;
.LBB0_173:
	s_add_u32 s8, s6, 0xfffc0080
	s_addc_u32 s9, s7, -1
	s_add_i32 s29, 0, 0x10000
	s_cmp_eq_u32 s28, 12
	s_cselect_b32 s23, s17, s9
	s_cselect_b32 s22, s24, s8
	v_add_u32_e32 v158, s29, v174
	s_cselect_b32 s9, s15, s27
	s_cselect_b32 s8, s25, s26
	s_add_i32 s33, 0, 0x14000
	ds_read_b128 v[128:131], v158
	ds_read_b128 v[150:153], v158 offset:1024
	ds_read_b128 v[154:157], v158 offset:2048
	ds_read_b128 v[162:165], v158 offset:3072
	v_add_u32_e32 v158, s33, v174
	ds_read_b128 v[166:169], v158
	ds_read_b128 v[170:173], v158 offset:1024
	ds_read_b128 v[180:183], v158 offset:2048
	ds_read_b128 v[184:187], v158 offset:3072
	v_lshl_add_u64 v[158:159], s[6:7], 0, v[146:147]
	s_add_i32 m0, s31, 0xc000
	ds_read_b128 v[200:203], v179
	ds_read_b128 v[204:207], v179 offset:1024
	ds_read_b128 v[208:211], v179 offset:2048
	ds_read_b128 v[212:215], v179 offset:3072
	ds_read_b128 v[228:231], v179 offset:4096
	ds_read_b128 v[232:235], v179 offset:5120
	ds_read_b128 v[242:245], v179 offset:6144
	ds_read_b128 v[246:249], v179 offset:7168
	global_load_lds_dwordx4 v[158:159], off
	v_lshl_add_u64 v[158:159], s[6:7], 0, v[148:149]
	s_add_i32 m0, s31, 0xe000
	s_nop 0
	global_load_lds_dwordx4 v[158:159], off
	s_waitcnt vmcnt(8)
	s_waitcnt lgkmcnt(0)
	s_barrier
	s_setprio 1
	v_mfma_f32_16x16x32_bf16 v[72:75], v[128:131], v[200:203], v[72:75]
	v_mfma_f32_16x16x32_bf16 v[124:127], v[154:157], v[200:203], v[124:127]
	v_mfma_f32_16x16x32_bf16 v[56:59], v[128:131], v[208:211], v[56:59]
	v_mfma_f32_16x16x32_bf16 v[120:123], v[154:157], v[208:211], v[120:123]
	v_mfma_f32_16x16x32_bf16 v[32:35], v[128:131], v[228:231], v[32:35]
	v_mfma_f32_16x16x32_bf16 v[108:111], v[154:157], v[228:231], v[108:111]
	v_mfma_f32_16x16x32_bf16 v[16:19], v[128:131], v[242:245], v[16:19]
	v_mfma_f32_16x16x32_bf16 v[96:99], v[154:157], v[242:245], v[96:99]
	v_mfma_f32_16x16x32_bf16 v[72:75], v[150:153], v[204:207], v[72:75]
	v_mfma_f32_16x16x32_bf16 v[124:127], v[162:165], v[204:207], v[124:127]
	v_mfma_f32_16x16x32_bf16 v[56:59], v[150:153], v[212:215], v[56:59]
	v_mfma_f32_16x16x32_bf16 v[120:123], v[162:165], v[212:215], v[120:123]
	v_mfma_f32_16x16x32_bf16 v[32:35], v[150:153], v[232:235], v[32:35]
	v_mfma_f32_16x16x32_bf16 v[108:111], v[162:165], v[232:235], v[108:111]
	v_mfma_f32_16x16x32_bf16 v[16:19], v[150:153], v[246:249], v[16:19]
	v_mfma_f32_16x16x32_bf16 v[96:99], v[162:165], v[246:249], v[96:99]
	v_mfma_f32_16x16x32_bf16 v[116:119], v[166:169], v[200:203], v[116:119]
	v_mfma_f32_16x16x32_bf16 v[112:115], v[180:183], v[200:203], v[112:115]
	v_mfma_f32_16x16x32_bf16 v[104:107], v[166:169], v[208:211], v[104:107]
	v_mfma_f32_16x16x32_bf16 v[100:103], v[180:183], v[208:211], v[100:103]
	v_mfma_f32_16x16x32_bf16 v[92:95], v[166:169], v[228:231], v[92:95]
	v_mfma_f32_16x16x32_bf16 v[88:91], v[180:183], v[228:231], v[88:91]
	v_mfma_f32_16x16x32_bf16 v[84:87], v[166:169], v[242:245], v[84:87]
	v_mfma_f32_16x16x32_bf16 v[80:83], v[180:183], v[242:245], v[80:83]
	v_mfma_f32_16x16x32_bf16 v[116:119], v[170:173], v[204:207], v[116:119]
	v_mfma_f32_16x16x32_bf16 v[112:115], v[184:187], v[204:207], v[112:115]
	v_mfma_f32_16x16x32_bf16 v[104:107], v[170:173], v[212:215], v[104:107]
	v_mfma_f32_16x16x32_bf16 v[100:103], v[184:187], v[212:215], v[100:103]
	v_mfma_f32_16x16x32_bf16 v[92:95], v[170:173], v[232:235], v[92:95]
	v_mfma_f32_16x16x32_bf16 v[88:91], v[184:187], v[232:235], v[88:91]
	v_mfma_f32_16x16x32_bf16 v[84:87], v[170:173], v[246:249], v[84:87]
	v_mfma_f32_16x16x32_bf16 v[80:83], v[184:187], v[246:249], v[80:83]
	s_setprio 0
	s_barrier
	s_add_i32 s29, s29, s30
	v_lshl_add_u64 v[158:159], s[8:9], 0, v[136:137]
	s_mov_b32 m0, s29
	ds_read_b128 v[200:203], v179 offset:16384
	ds_read_b128 v[204:207], v179 offset:17408
	ds_read_b128 v[208:211], v179 offset:18432
	ds_read_b128 v[212:215], v179 offset:19456
	ds_read_b128 v[228:231], v179 offset:20480
	ds_read_b128 v[232:235], v179 offset:21504
	ds_read_b128 v[242:245], v179 offset:22528
	ds_read_b128 v[246:249], v179 offset:23552
	global_load_lds_dwordx4 v[158:159], off
	s_add_i32 m0, s29, 0x2000
	s_add_u32 s46, s8, 0x40000
	v_lshl_add_u64 v[188:189], s[8:9], 0, v[132:133]
	s_addc_u32 s47, s9, 0
	s_add_i32 s29, s33, s30
	global_load_lds_dwordx4 v[188:189], off
	v_lshl_add_u64 v[190:191], s[46:47], 0, v[136:137]
	s_mov_b32 m0, s29
	v_lshl_add_u64 v[192:193], s[22:23], 0, v[134:135]
	global_load_lds_dwordx4 v[190:191], off
	v_lshl_add_u64 v[190:191], s[46:47], 0, v[132:133]
	s_add_i32 m0, s29, 0x2000
	s_nop 0
	global_load_lds_dwordx4 v[190:191], off
	v_lshl_add_u64 v[190:191], s[22:23], 0, v[138:139]
	s_mov_b32 m0, s31
	s_nop 0
	global_load_lds_dwordx4 v[190:191], off
	s_mov_b32 m0, s34
	s_nop 0
	global_load_lds_dwordx4 v[192:193], off
	s_waitcnt vmcnt(8)
	s_waitcnt lgkmcnt(0)
	s_barrier
; #define PG8_STAGE(bufoff, gbase, voff) do { _Pragma("unroll") for (int _i = 0; _i < 2; ++_i) \
;         __builtin_amdgcn_global_load_lds((const unsigned*)((const char*)(gbase) + (voff)[_i]), (PG8_LAS unsigned*)(lds + (bufoff) + ldsw + _i * 8192), 16, 0, 0); } while (0)
; #define PG8_LDA(dst, b, h) do { _Pragma("unroll") for (int m = 0; m < 4; ++m) _Pragma("unroll") for (int k = 0; k < 2; ++k) dst[m][k] = *(const PG8_LAS bf16x8*)(lds + PG8_SA(b, h) + aoff + m * 2048 + k * 1024); } while (0)
; #define PG8_LDB(dst, b, h) do { _Pragma("unroll") for (int n = 0; n < 2; ++n) _Pragma("unroll") for (int k = 0; k < 2; ++k) dst[n][k] = *(const PG8_LAS bf16x8*)(lds + PG8_SB(b, h) + boff + n * 2048 + k * 1024); } while (0)
; #define PG8_MMA(ai, bj, At, Bt) do { __builtin_amdgcn_s_setprio(1); _Pragma("unroll") for (int m = 0; m < 4; ++m) _Pragma("unroll") for (int n = 0; n < 2; ++n) _Pragma("unroll") for (int k = 0; k < 2; ++k) \
;         acc[ai][bj][m][n] = __builtin_amdgcn_mfma_f32_16x16x32_bf16(Bt[n][k], At[m][k], acc[ai][bj][m][n], 0, 0, 0); __builtin_amdgcn_s_setprio(0); } while (0)
; #define PG8_WAIT_V(n) asm volatile("s_waitcnt vmcnt(" #n ")" ::: "memory")
; #define PG8_WAIT_L(n) asm volatile("s_waitcnt lgkmcnt(" #n ")" ::: "memory")
; #define PG8_BAR __builtin_amdgcn_s_barrier()
; #define PG8_SCHED __builtin_amdgcn_sched_barrier(0)
; template <class Epi, class Sched, bool ALIGN_EPI = false, bool SP2 = false>
; __device__ __forceinline__ void gemm_phase(PG8_LAS unsigned char* lds, const Gemm g, const Sched& S, const Epi& E) {
;     ...
;             PG8_WAIT_V(8); PG8_WAIT_L(0); PG8_BAR; PG8_MMA(1, 0, At, B0); PG8_MMA(1, 1, At, B1); PG8_BAR; PG8_SCHED;
;             PG8_LDB(B0, 1, 0); PG8_LDB(B1, 1, 1); PG8_SCHED; PG8_LDA(At, 1, 0); PG8_STAGE(PG8_SA(0, 1), a2 + hstep, voffA);
;             PG8_WAIT_V(8); PG8_WAIT_L(0); PG8_BAR; PG8_MMA(0, 0, At, B0); PG8_MMA(0, 1, At, B1); PG8_BAR; PG8_SCHED;
	s_setprio 1
	v_mfma_f32_16x16x32_bf16 v[12:15], v[128:131], v[200:203], v[12:15]
	v_mfma_f32_16x16x32_bf16 v[76:79], v[154:157], v[200:203], v[76:79]
	v_mfma_f32_16x16x32_bf16 v[8:11], v[128:131], v[208:211], v[8:11]
	v_mfma_f32_16x16x32_bf16 v[68:71], v[154:157], v[208:211], v[68:71]
	v_mfma_f32_16x16x32_bf16 v[4:7], v[128:131], v[228:231], v[4:7]
	v_mfma_f32_16x16x32_bf16 v[52:55], v[154:157], v[228:231], v[52:55]
	v_mfma_f32_16x16x32_bf16 v[0:3], v[128:131], v[242:245], v[0:3]
	v_mfma_f32_16x16x32_bf16 v[40:43], v[154:157], v[242:245], v[40:43]
	v_mfma_f32_16x16x32_bf16 v[12:15], v[150:153], v[204:207], v[12:15]
	v_mfma_f32_16x16x32_bf16 v[76:79], v[162:165], v[204:207], v[76:79]
	v_mfma_f32_16x16x32_bf16 v[8:11], v[150:153], v[212:215], v[8:11]
	v_mfma_f32_16x16x32_bf16 v[68:71], v[162:165], v[212:215], v[68:71]
	v_mfma_f32_16x16x32_bf16 v[4:7], v[150:153], v[232:235], v[4:7]
	v_mfma_f32_16x16x32_bf16 v[52:55], v[162:165], v[232:235], v[52:55]
	v_mfma_f32_16x16x32_bf16 v[0:3], v[150:153], v[246:249], v[0:3]
	v_mfma_f32_16x16x32_bf16 v[40:43], v[162:165], v[246:249], v[40:43]
	v_mfma_f32_16x16x32_bf16 v[64:67], v[166:169], v[200:203], v[64:67]
	v_mfma_f32_16x16x32_bf16 v[60:63], v[180:183], v[200:203], v[60:63]
	v_mfma_f32_16x16x32_bf16 v[48:51], v[166:169], v[208:211], v[48:51]
	v_mfma_f32_16x16x32_bf16 v[44:47], v[180:183], v[208:211], v[44:47]
	v_mfma_f32_16x16x32_bf16 v[36:39], v[166:169], v[228:231], v[36:39]
	v_mfma_f32_16x16x32_bf16 v[28:31], v[180:183], v[228:231], v[28:31]
	v_mfma_f32_16x16x32_bf16 v[24:27], v[166:169], v[242:245], v[24:27]
	v_mfma_f32_16x16x32_bf16 v[20:23], v[180:183], v[242:245], v[20:23]
	v_mfma_f32_16x16x32_bf16 v[64:67], v[170:173], v[204:207], v[64:67]
	v_mfma_f32_16x16x32_bf16 v[60:63], v[184:187], v[204:207], v[60:63]
	v_mfma_f32_16x16x32_bf16 v[48:51], v[170:173], v[212:215], v[48:51]
	v_mfma_f32_16x16x32_bf16 v[44:47], v[184:187], v[212:215], v[44:47]
	v_mfma_f32_16x16x32_bf16 v[36:39], v[170:173], v[232:235], v[36:39]
	v_mfma_f32_16x16x32_bf16 v[28:31], v[184:187], v[232:235], v[28:31]
	v_mfma_f32_16x16x32_bf16 v[24:27], v[170:173], v[246:249], v[24:27]
	v_mfma_f32_16x16x32_bf16 v[20:23], v[184:187], v[246:249], v[20:23]
	s_setprio 0
	s_barrier
	s_add_i32 s29, 0, 0x18000
	v_add_u32_e32 v160, s29, v174
	s_add_i32 s33, 0, 0x1c000
	ds_read_b128 v[128:131], v160
	ds_read_b128 v[150:153], v160 offset:1024
	ds_read_b128 v[154:157], v160 offset:2048
	ds_read_b128 v[162:165], v160 offset:3072
	v_add_u32_e32 v160, s33, v174
	ds_read_b128 v[166:169], v160
	ds_read_b128 v[170:173], v160 offset:1024
	ds_read_b128 v[180:183], v160 offset:2048
	ds_read_b128 v[184:187], v160 offset:3072
	s_add_u32 s22, s22, 0x40000
	s_addc_u32 s23, s23, 0
	s_mov_b32 m0, s35
	v_lshl_add_u64 v[196:197], s[22:23], 0, v[138:139]
	ds_read_b128 v[200:203], v179 offset:32768
	ds_read_b128 v[204:207], v179 offset:33792
	ds_read_b128 v[208:211], v179 offset:34816
	ds_read_b128 v[212:215], v179 offset:35840
	ds_read_b128 v[228:231], v179 offset:36864
	ds_read_b128 v[232:235], v179 offset:37888
	ds_read_b128 v[242:245], v179 offset:38912
	ds_read_b128 v[246:249], v179 offset:39936
	global_load_lds_dwordx4 v[196:197], off
	v_lshl_add_u64 v[196:197], s[22:23], 0, v[134:135]
	s_mov_b32 m0, s36
	s_nop 0
	global_load_lds_dwordx4 v[196:197], off
	s_waitcnt vmcnt(8)
	s_waitcnt lgkmcnt(0)
	s_barrier
	s_setprio 1
	v_mfma_f32_16x16x32_bf16 v[72:75], v[128:131], v[200:203], v[72:75]
	v_mfma_f32_16x16x32_bf16 v[124:127], v[154:157], v[200:203], v[124:127]
	v_mfma_f32_16x16x32_bf16 v[56:59], v[128:131], v[208:211], v[56:59]
	v_mfma_f32_16x16x32_bf16 v[120:123], v[154:157], v[208:211], v[120:123]
	v_mfma_f32_16x16x32_bf16 v[32:35], v[128:131], v[228:231], v[32:35]
	v_mfma_f32_16x16x32_bf16 v[108:111], v[154:157], v[228:231], v[108:111]
	v_mfma_f32_16x16x32_bf16 v[16:19], v[128:131], v[242:245], v[16:19]
	v_mfma_f32_16x16x32_bf16 v[96:99], v[154:157], v[242:245], v[96:99]
	v_mfma_f32_16x16x32_bf16 v[72:75], v[150:153], v[204:207], v[72:75]
	v_mfma_f32_16x16x32_bf16 v[124:127], v[162:165], v[204:207], v[124:127]
	v_mfma_f32_16x16x32_bf16 v[56:59], v[150:153], v[212:215], v[56:59]
	v_mfma_f32_16x16x32_bf16 v[120:123], v[162:165], v[212:215], v[120:123]
	v_mfma_f32_16x16x32_bf16 v[32:35], v[150:153], v[232:235], v[32:35]
	v_mfma_f32_16x16x32_bf16 v[108:111], v[162:165], v[232:235], v[108:111]
	v_mfma_f32_16x16x32_bf16 v[16:19], v[150:153], v[246:249], v[16:19]
	v_mfma_f32_16x16x32_bf16 v[96:99], v[162:165], v[246:249], v[96:99]
	v_mfma_f32_16x16x32_bf16 v[116:119], v[166:169], v[200:203], v[116:119]
	v_mfma_f32_16x16x32_bf16 v[112:115], v[180:183], v[200:203], v[112:115]
	v_mfma_f32_16x16x32_bf16 v[104:107], v[166:169], v[208:211], v[104:107]
	v_mfma_f32_16x16x32_bf16 v[100:103], v[180:183], v[208:211], v[100:103]
	v_mfma_f32_16x16x32_bf16 v[92:95], v[166:169], v[228:231], v[92:95]
	v_mfma_f32_16x16x32_bf16 v[88:91], v[180:183], v[228:231], v[88:91]
	v_mfma_f32_16x16x32_bf16 v[84:87], v[166:169], v[242:245], v[84:87]
	v_mfma_f32_16x16x32_bf16 v[80:83], v[180:183], v[242:245], v[80:83]
	v_mfma_f32_16x16x32_bf16 v[116:119], v[170:173], v[204:207], v[116:119]
	v_mfma_f32_16x16x32_bf16 v[112:115], v[184:187], v[204:207], v[112:115]
	v_mfma_f32_16x16x32_bf16 v[104:107], v[170:173], v[212:215], v[104:107]
	v_mfma_f32_16x16x32_bf16 v[100:103], v[184:187], v[212:215], v[100:103]
	v_mfma_f32_16x16x32_bf16 v[92:95], v[170:173], v[232:235], v[92:95]
	v_mfma_f32_16x16x32_bf16 v[88:91], v[184:187], v[232:235], v[88:91]
	v_mfma_f32_16x16x32_bf16 v[84:87], v[170:173], v[246:249], v[84:87]
	v_mfma_f32_16x16x32_bf16 v[80:83], v[184:187], v[246:249], v[80:83]
	s_setprio 0
	s_barrier
; #define PG8_STAGE(bufoff, gbase, voff) do { _Pragma("unroll") for (int _i = 0; _i < 2; ++_i) \
;         __builtin_amdgcn_global_load_lds((const unsigned*)((const char*)(gbase) + (voff)[_i]), (PG8_LAS unsigned*)(lds + (bufoff) + ldsw + _i * 8192), 16, 0, 0); } while (0)
; #define PG8_LDA(dst, b, h) do { _Pragma("unroll") for (int m = 0; m < 4; ++m) _Pragma("unroll") for (int k = 0; k < 2; ++k) dst[m][k] = *(const PG8_LAS bf16x8*)(lds + PG8_SA(b, h) + aoff + m * 2048 + k * 1024); } while (0)
; #define PG8_MMA(ai, bj, At, Bt) do { __builtin_amdgcn_s_setprio(1); _Pragma("unroll") for (int m = 0; m < 4; ++m) _Pragma("unroll") for (int n = 0; n < 2; ++n) _Pragma("unroll") for (int k = 0; k < 2; ++k) \
;         acc[ai][bj][m][n] = __builtin_amdgcn_mfma_f32_16x16x32_bf16(Bt[n][k], At[m][k], acc[ai][bj][m][n], 0, 0, 0); __builtin_amdgcn_s_setprio(0); } while (0)
; #define PG8_WAIT_V(n) asm volatile("s_waitcnt vmcnt(" #n ")" ::: "memory")
; #define PG8_WAIT_L(n) asm volatile("s_waitcnt lgkmcnt(" #n ")" ::: "memory")
; #define PG8_BAR __builtin_amdgcn_s_barrier()
; #define PG8_SCHED __builtin_amdgcn_sched_barrier(0)
; template <class Epi, class Sched, bool ALIGN_EPI = false, bool SP2 = false>
; __device__ __forceinline__ void gemm_phase(PG8_LAS unsigned char* lds, const Gemm g, const Sched& S, const Epi& E) {
;     ...
;             PG8_LDA(At, 1, 1); PG8_STAGE(PG8_SB(1, 0), b3, voffB); PG8_STAGE(PG8_SB(1, 1), b3 + hstep, voffB); PG8_STAGE(PG8_SA(1, 0), a3, voffA);
;             PG8_WAIT_V(8); PG8_WAIT_L(0); PG8_BAR; PG8_MMA(1, 0, At, B0); PG8_MMA(1, 1, At, B1); PG8_BAR; PG8_SCHED;
	s_add_i32 s22, s29, s30
	v_lshl_add_u64 v[158:159], v[158:159], 0, s[42:43]
	s_mov_b32 m0, s22
	ds_read_b128 v[200:203], v179 offset:49152
	ds_read_b128 v[204:207], v179 offset:50176
	ds_read_b128 v[208:211], v179 offset:51200
	ds_read_b128 v[212:215], v179 offset:52224
	ds_read_b128 v[228:231], v179 offset:53248
	ds_read_b128 v[232:235], v179 offset:54272
	ds_read_b128 v[242:245], v179 offset:55296
	ds_read_b128 v[246:249], v179 offset:56320
	global_load_lds_dwordx4 v[158:159], off
	s_add_i32 m0, s22, 0x2000
	s_add_u32 s8, s8, 0x40080
	v_lshl_add_u64 v[158:159], v[188:189], 0, s[42:43]
	s_addc_u32 s9, s9, 0
	s_add_i32 s22, s33, s30
	global_load_lds_dwordx4 v[158:159], off
	v_lshl_add_u64 v[158:159], s[8:9], 0, v[136:137]
	s_mov_b32 m0, s22
	s_nop 0
	global_load_lds_dwordx4 v[158:159], off
	v_lshl_add_u64 v[158:159], s[8:9], 0, v[132:133]
	s_add_i32 m0, s22, 0x2000
	s_nop 0
	global_load_lds_dwordx4 v[158:159], off
	v_lshl_add_u64 v[158:159], v[190:191], 0, s[42:43]
	s_mov_b32 m0, s37
	s_nop 0
	global_load_lds_dwordx4 v[158:159], off
	v_lshl_add_u64 v[158:159], v[192:193], 0, s[42:43]
	s_mov_b32 m0, s38
	s_nop 0
	global_load_lds_dwordx4 v[158:159], off
	s_waitcnt vmcnt(8)
	s_waitcnt lgkmcnt(0)
	s_barrier
	s_setprio 1
	v_mfma_f32_16x16x32_bf16 v[12:15], v[128:131], v[200:203], v[12:15]
	v_mfma_f32_16x16x32_bf16 v[76:79], v[154:157], v[200:203], v[76:79]
	v_mfma_f32_16x16x32_bf16 v[8:11], v[128:131], v[208:211], v[8:11]
	v_mfma_f32_16x16x32_bf16 v[68:71], v[154:157], v[208:211], v[68:71]
	v_mfma_f32_16x16x32_bf16 v[4:7], v[128:131], v[228:231], v[4:7]
	v_mfma_f32_16x16x32_bf16 v[52:55], v[154:157], v[228:231], v[52:55]
	v_mfma_f32_16x16x32_bf16 v[0:3], v[128:131], v[242:245], v[0:3]
	v_mfma_f32_16x16x32_bf16 v[40:43], v[154:157], v[242:245], v[40:43]
	v_mfma_f32_16x16x32_bf16 v[12:15], v[150:153], v[204:207], v[12:15]
	v_mfma_f32_16x16x32_bf16 v[76:79], v[162:165], v[204:207], v[76:79]
	v_mfma_f32_16x16x32_bf16 v[8:11], v[150:153], v[212:215], v[8:11]
	v_mfma_f32_16x16x32_bf16 v[68:71], v[162:165], v[212:215], v[68:71]
	v_mfma_f32_16x16x32_bf16 v[4:7], v[150:153], v[232:235], v[4:7]
	v_mfma_f32_16x16x32_bf16 v[52:55], v[162:165], v[232:235], v[52:55]
	v_mfma_f32_16x16x32_bf16 v[0:3], v[150:153], v[246:249], v[0:3]
	v_mfma_f32_16x16x32_bf16 v[40:43], v[162:165], v[246:249], v[40:43]
	v_mfma_f32_16x16x32_bf16 v[64:67], v[166:169], v[200:203], v[64:67]
	v_mfma_f32_16x16x32_bf16 v[60:63], v[180:183], v[200:203], v[60:63]
	v_mfma_f32_16x16x32_bf16 v[48:51], v[166:169], v[208:211], v[48:51]
	v_mfma_f32_16x16x32_bf16 v[44:47], v[180:183], v[208:211], v[44:47]
	v_mfma_f32_16x16x32_bf16 v[36:39], v[166:169], v[228:231], v[36:39]
	v_mfma_f32_16x16x32_bf16 v[28:31], v[180:183], v[228:231], v[28:31]
	v_mfma_f32_16x16x32_bf16 v[24:27], v[166:169], v[242:245], v[24:27]
	v_mfma_f32_16x16x32_bf16 v[20:23], v[180:183], v[242:245], v[20:23]
	v_mfma_f32_16x16x32_bf16 v[64:67], v[170:173], v[204:207], v[64:67]
	v_mfma_f32_16x16x32_bf16 v[60:63], v[184:187], v[204:207], v[60:63]
	v_mfma_f32_16x16x32_bf16 v[48:51], v[170:173], v[212:215], v[48:51]
	v_mfma_f32_16x16x32_bf16 v[44:47], v[184:187], v[212:215], v[44:47]
	v_mfma_f32_16x16x32_bf16 v[36:39], v[170:173], v[232:235], v[36:39]
	v_mfma_f32_16x16x32_bf16 v[28:31], v[184:187], v[232:235], v[28:31]
	v_mfma_f32_16x16x32_bf16 v[24:27], v[170:173], v[246:249], v[24:27]
	v_mfma_f32_16x16x32_bf16 v[20:23], v[184:187], v[246:249], v[20:23]
	s_setprio 0
	s_barrier
	s_add_i32 s28, s28, 2
	s_add_u32 s6, s6, 0x100
	s_addc_u32 s7, s7, 0
	s_add_u32 s26, s26, 0x100
	s_addc_u32 s27, s27, 0
	s_cmp_gt_u32 s28, 13
	s_cbranch_scc0 .LBB0_173
	s_and_b64 vcc, exec, s[10:11]
	s_cbranch_vccz .LBB0_176
	s_barrier

; #define LAS __attribute__((address_space(3)))
; __device__ __forceinline__ float fast_exp(float x) { return __builtin_amdgcn_exp2f(x * 1.4426950408889634f); }
; __device__ __forceinline__ void mlstm_unit(const Params& p, int l, int b, int h, LAS unsigned char* lds) {
;     ...
;     const int tok = g ? 63 - lane : lane;
;     f32x16 Cacc;
; #pragma unroll
;     for (int i = 0; i < 16; ++i) Cacc[i] = 0.f;
;     float nreg = 0.f, mstate = 0.f;
;     u32x4 rq0, rq1, rk0, rk1, rt0, rt1, rv0, rv1; f32x4 rsc;
;     ...
;     ML_PREFETCH(0);
;     ...
;             const int t = 32 * tblk + r32; const float At = tb[T_BIGA / 4 + t];
;             float dsum = 0.f;
; #pragma unroll
;             for (int ig = 0; ig < 4; ++ig) { const int s0 = 32 * sblk + 8 * ig + 4 * hi; const f32x4 a4 = *(const LAS f32x4*)(L + ML_TAB + T_A + s0 * 4);
;                 float w[4];
; #pragma unroll
;                 for (int e = 0; e < 4; ++e) { const int s = s0 + e; const bool valid = g ? (s >= t) : (s <= t); const float ex = fast_exp(fminf(a4[e] - At, 0.f)); w[e] = valid ? st[4 * ig + e] * ex : 0.f; dsum += w[e]; }
.LBB0_455:
	s_cmpk_gt_u32 s2, 0xff
	s_mul_hi_u32 s4, s22, 0x88000
	s_mul_i32 s22, s22, 0x88000
	v_readlane_b32 s6, v252, 53
	s_cselect_b64 s[0:1], -1, 0
	v_readlane_b32 s7, v252, 54
	s_add_u32 s8, s6, s22
	s_addc_u32 s9, s7, s4
	s_and_b32 s12, s26, 3
	s_add_u32 s6, s14, 0x88000
	s_addc_u32 s7, s15, 0
	s_cmpk_lt_u32 s2, 0x100
	s_cselect_b64 s[4:5], -1, 0
	s_and_b64 s[10:11], s[4:5], exec
	s_cselect_b32 s13, 0, 0xc0
	v_lshrrev_b32_e32 v111, 2, v11
	v_cndmask_b32_e64 v9, v0, v10, s[4:5]
	v_or_b32_e32 v0, s13, v111
	v_lshlrev_b32_e32 v160, 7, v0
	v_lshlrev_b32_e32 v2, 5, v110
	v_lshl_add_u64 v[0:1], s[14:15], 0, v[160:161]
	v_and_b32_e32 v2, 0x60, v2
	v_mov_b32_e32 v3, v161
	v_lshl_add_u64 v[0:1], v[0:1], 0, v[2:3]
	s_waitcnt vmcnt(0)
	s_waitcnt lgkmcnt(0)
	s_barrier
	global_load_dwordx4 v[48:51], v[0:1], off offset:16
	global_load_dwordx4 v[52:55], v[0:1], off
	v_lshl_add_u64 v[0:1], s[6:7], 0, v[160:161]
	v_lshl_add_u64 v[0:1], v[0:1], 0, v[2:3]
	s_mov_b32 s10, 0x4400000
	global_load_dwordx4 v[56:59], v[0:1], off offset:16
	global_load_dwordx4 v[60:63], v[0:1], off
	v_mul_u32_u24_e32 v0, 0x1100, v111
	s_cselect_b32 s10, s10, 0x5500000
	v_lshlrev_b32_e32 v160, 1, v0
	s_add_u32 s16, s60, s10
	v_lshl_add_u64 v[0:1], s[14:15], 0, v[160:161]
	s_mov_b64 s[10:11], 0x110000
	s_addc_u32 s17, s61, 0
	v_lshl_add_u64 v[0:1], v[0:1], 0, s[10:11]
	s_lshl_b32 s64, s13, 1
	v_lshl_add_u64 v[4:5], v[0:1], 0, s[64:65]
	v_lshl_add_u64 v[4:5], v[4:5], 0, v[2:3]
	global_load_dwordx4 v[64:67], v[4:5], off offset:16
	global_load_dwordx4 v[68:71], v[4:5], off
	v_lshl_add_u64 v[4:5], s[8:9], 0, v[160:161]
	s_mul_hi_i32 s9, s25, 0x11000
	s_mul_i32 s25, s25, 0x11000
	s_add_u32 s8, s20, s25
	s_addc_u32 s9, s21, s9
	s_lshl_b32 s10, s13, 4
	s_add_u32 s10, s8, s10
	s_addc_u32 s11, s9, 0
	s_cmp_eq_u32 s12, 0
	s_cselect_b64 s[70:71], -1, 0
	s_cmp_lg_u32 s12, 0
	v_lshlrev_b32_e32 v160, 4, v9
	s_cselect_b64 s[72:73], -1, 0
	v_lshl_add_u64 v[90:91], s[6:7], 0, v[2:3]
	s_bfe_u32 s2, s2, 0x10006
	s_lshl_b32 s7, s26, 4
	v_lshl_add_u64 v[96:97], s[8:9], 0, v[160:161]
	s_lshl_b32 s6, s2, 5
	s_and_b32 s8, s7, 32
	v_lshl_add_u64 v[6:7], v[4:5], 0, s[64:65]
	v_lshl_add_u32 v114, v9, 2, s85
	v_and_b32_e32 v9, 64, v224
	s_cmp_eq_u32 s2, 0
	s_movk_i32 s9, 0x500
	v_and_b32_e32 v8, 31, v110
	v_lshl_add_u64 v[6:7], v[6:7], 0, v[2:3]
	v_lshl_add_u64 v[94:95], v[4:5], 0, v[2:3]
	v_xor_b32_e32 v4, 32, v224
	v_add_u32_e32 v112, 64, v9
	s_cselect_b32 s9, s9, 0x600
	v_lshrrev_b32_e32 v12, 5, v10
	global_load_dwordx4 v[72:75], v[6:7], off offset:16
	global_load_dwordx4 v[76:79], v[6:7], off
	v_mad_u32_u24 v6, v111, s92, v2
	v_lshl_add_u64 v[88:89], s[14:15], 0, v[2:3]
	v_lshl_add_u64 v[92:93], v[0:1], 0, v[2:3]
	v_mov_b32_e32 v0, s85
	v_or_b32_e32 v1, s6, v8
	v_or_b32_e32 v2, s8, v8
	v_cmp_lt_i32_e32 vcc, v4, v112
	s_add_i32 s64, s85, s9
	s_lshl_b32 s2, s2, 6
	v_mad_u32_u24 v1, v1, s92, v0
	v_mad_u32_u24 v5, v2, s92, v0
	v_lshl_or_b32 v0, v12, 2, s6
	v_cndmask_b32_e32 v4, v224, v4, vcc
	s_cmp_eq_u32 s12, 1
	v_lshlrev_b32_e32 v117, 2, v4
	v_lshlrev_b32_e32 v4, 3, v12
	s_cselect_b64 s[74:75], -1, 0
	s_add_i32 s67, s85, 0x10300
	s_lshl_b32 s45, s91, 1
	v_cmp_le_u32_e32 vcc, v0, v2
	v_add3_u32 v118, v5, s2, v4
	s_add_u32 s2, s16, s45
	v_cndmask_b32_e64 v4, 0, 1, vcc
	v_cmp_ge_u32_e32 vcc, v0, v2
	global_load_dwordx4 v[80:83], v160, s[10:11]
	s_addc_u32 s9, s17, 0
	s_lshl_b32 s8, s8, 1
	v_lshlrev_b32_e32 v160, 1, v8
	v_cndmask_b32_e64 v8, 0, 1, vcc
	s_add_u32 s8, s2, s8
	v_cndmask_b32_e64 v4, v8, v4, s[4:5]
	s_addc_u32 s9, s9, 0
	v_and_b32_e32 v4, 1, v4
	v_lshl_add_u64 v[98:99], s[8:9], 0, v[160:161]
	v_cmp_eq_u32_e64 s[8:9], 1, v4
	v_or_b32_e32 v4, 1, v0
	v_cmp_lt_u32_e32 vcc, v0, v2
	v_cmp_gt_u32_e64 s[6:7], 32, v10
	v_mul_u32_u24_e32 v119, 0x90, v10
	v_cndmask_b32_e64 v8, 0, 1, vcc
	v_cmp_ge_u32_e32 vcc, v4, v2
	v_lshlrev_b32_e32 v120, 2, v10
	v_lshlrev_b32_e32 v3, 4, v12
	v_cndmask_b32_e64 v4, 0, 1, vcc
	v_cndmask_b32_e64 v4, v4, v8, s[4:5]
	v_and_b32_e32 v4, 1, v4
	v_cmp_eq_u32_e64 s[10:11], 1, v4
	v_or_b32_e32 v4, 2, v0
	v_cmp_le_u32_e32 vcc, v4, v2
	v_mul_i32_i24_e32 v7, 0xffffff74, v2
	v_lshlrev_b32_e32 v9, 2, v2
	v_cndmask_b32_e64 v8, 0, 1, vcc
	v_cmp_ge_u32_e32 vcc, v4, v2
	v_and_b32_e32 v11, 32, v110
	v_lshlrev_b32_e32 v122, 2, v0
	v_cndmask_b32_e64 v4, 0, 1, vcc
	v_cndmask_b32_e64 v4, v4, v8, s[4:5]
	v_and_b32_e32 v4, 1, v4
	v_cmp_eq_u32_e64 s[12:13], 1, v4
	v_or_b32_e32 v4, 3, v0
	v_cmp_le_u32_e32 vcc, v4, v2
	v_mov_b32_e32 v130, 0
	s_mov_b32 s44, 0
	v_cndmask_b32_e64 v8, 0, 1, vcc
	v_cmp_ge_u32_e32 vcc, v4, v2
	v_lshl_or_b32 v113, v224, 2, v227
	v_add_u32_e32 v115, 0xfc00, v114
	v_cndmask_b32_e64 v4, 0, 1, vcc
	v_cndmask_b32_e64 v4, v4, v8, s[4:5]
	v_and_b32_e32 v4, 1, v4
	v_cmp_eq_u32_e64 s[14:15], 1, v4
	v_or_b32_e32 v4, 8, v0
	v_cmp_le_u32_e32 vcc, v4, v2
	v_lshlrev_b32_e32 v8, 1, v0
	v_lshlrev_b32_e32 v123, 2, v4
	v_cndmask_b32_e64 v10, 0, 1, vcc
	v_cmp_ge_u32_e32 vcc, v4, v2
	v_add_u32_e32 v116, v5, v3
	v_add_u32_e32 v121, s85, v120
	v_cndmask_b32_e64 v12, 0, 1, vcc
	v_cndmask_b32_e64 v10, v12, v10, s[4:5]
	v_and_b32_e32 v10, 1, v10
	v_cmp_eq_u32_e64 s[16:17], 1, v10
	v_or_b32_e32 v10, 9, v0
	v_cmp_le_u32_e32 vcc, v10, v2
	s_add_i32 s46, s85, 0x10100
	s_add_i32 s2, s85, 0x10200
	v_cndmask_b32_e64 v12, 0, 1, vcc
	v_cmp_ge_u32_e32 vcc, v10, v2
	s_add_i32 s33, s85, 0x10000
	v_mov_b32_e32 v101, v161
	v_cndmask_b32_e64 v10, 0, 1, vcc
	v_cndmask_b32_e64 v10, v10, v12, s[4:5]
	v_and_b32_e32 v10, 1, v10
	v_cmp_eq_u32_e64 s[18:19], 1, v10
	v_or_b32_e32 v10, 10, v0
	v_cmp_le_u32_e32 vcc, v10, v2
	s_movk_i32 s47, 0x46
	v_add_u32_e32 v126, s85, v6
	v_cndmask_b32_e64 v12, 0, 1, vcc
; #define LAS __attribute__((address_space(3)))
; __device__ __forceinline__ float fast_exp(float x) { return __builtin_amdgcn_exp2f(x * 1.4426950408889634f); }
; #define MFMA32(a, b, c) __builtin_amdgcn_mfma_f32_32x32x16_bf16((a), (b), (c), 0, 0, 0)
; __device__ __forceinline__ void mlstm_unit(const Params& p, int l, int b, int h, LAS unsigned char* lds) {
;     ...
;             for (int ig = 0; ig < 4; ++ig) { const int s0 = 32 * sblk + 8 * ig + 4 * hi; const f32x4 a4 = *(const LAS f32x4*)(L + ML_TAB + T_A + s0 * 4);
;                 float w[4];
; #pragma unroll
;                 for (int e = 0; e < 4; ++e) { const int s = s0 + e; const bool valid = g ? (s >= t) : (s <= t); const float ex = fast_exp(fminf(a4[e] - At, 0.f)); w[e] = valid ? st[4 * ig + e] * ex : 0.f; dsum += w[e]; }
;     ...
;         {
;             const int tblk = w4 & 1, vblk = w4 >> 1;
;             f32x16 a1, a2;
; #pragma unroll
;             for (int i = 0; i < 16; ++i) { a1[i] = 0.f; a2[i] = 0.f; }
; #pragma unroll
;             for (int c = 0; c < 4; ++c) { const bf16x8 bv = lds_rd16(L + ML_VT + (32 * vblk + r32) * 144 + hi * 16 + c * 32), as = lds_rd16(L + ML_SW + (32 * tblk + r32) * 144 + hi * 16 + c * 32);
;                 const bf16x8 aq = lds_rd16(L + ML_QS + (32 * tblk + r32) * 144 + hi * 16 + c * 32), bc2 = lds_rd16(CTc + (32 * vblk + r32) * 144 + hi * 16 + c * 32);
;                 a1 = MFMA32(as, bv, a1); a2 = MFMA32(aq, bc2, a2); }
;             const int tau0 = cidx * 64; const size_t rowc = tau0 < CTX ? (size_t)(ctxrow0 + tau0) : (size_t)(latrow0 + tau0 - CTX);
;             bf16_t* hp = HX + rowc * 256 + h * 64 + 32 * vblk + r32;
	v_cmp_ge_u32_e32 vcc, v10, v2
	v_add_u32_e32 v127, v5, v7
	v_add_u32_e32 v128, v5, v8
	v_cndmask_b32_e64 v10, 0, 1, vcc
	v_cndmask_b32_e64 v10, v10, v12, s[4:5]
	v_and_b32_e32 v10, 1, v10
	v_cmp_eq_u32_e64 s[20:21], 1, v10
	v_or_b32_e32 v10, 11, v0
	v_cmp_le_u32_e32 vcc, v10, v2
	v_add_u32_e32 v133, s64, v9
	v_add_u32_e32 v134, s85, v11
	v_cndmask_b32_e64 v12, 0, 1, vcc
	v_cmp_ge_u32_e32 vcc, v10, v2
	v_add_u32_e32 v135, v1, v3
	v_mov_b32_e32 v136, 0
	v_cndmask_b32_e64 v10, 0, 1, vcc
	v_cndmask_b32_e64 v10, v10, v12, s[4:5]
	v_or_b32_e32 v12, 16, v0
	v_cmp_le_u32_e32 vcc, v12, v2
	v_and_b32_e32 v10, 1, v10
	v_cmp_eq_u32_e64 s[22:23], 1, v10
	v_cndmask_b32_e64 v13, 0, 1, vcc
	v_cmp_ge_u32_e32 vcc, v12, v2
	v_lshlrev_b32_e32 v10, 1, v4
	v_lshlrev_b32_e32 v124, 2, v12
	v_cndmask_b32_e64 v14, 0, 1, vcc
	v_cndmask_b32_e64 v13, v14, v13, s[4:5]
	v_and_b32_e32 v13, 1, v13
	v_cmp_eq_u32_e64 s[24:25], 1, v13
	v_or_b32_e32 v13, 17, v0
	v_cmp_le_u32_e32 vcc, v13, v2
	v_add_u32_e32 v129, v5, v10
	s_mov_b32 s90, 0
	v_cndmask_b32_e64 v14, 0, 1, vcc
	v_cmp_ge_u32_e32 vcc, v13, v2
	v_mov_b32_e32 v1, v130
	v_mov_b32_e32 v3, v130
	v_cndmask_b32_e64 v13, 0, 1, vcc
	v_cndmask_b32_e64 v13, v13, v14, s[4:5]
	v_and_b32_e32 v13, 1, v13
	v_cmp_eq_u32_e64 s[26:27], 1, v13
	v_or_b32_e32 v13, 18, v0
	v_cmp_le_u32_e32 vcc, v13, v2
	v_mov_b32_e32 v6, v130
	v_mov_b32_e32 v7, v130
	v_cndmask_b32_e64 v14, 0, 1, vcc
	v_cmp_ge_u32_e32 vcc, v13, v2
	v_mov_b32_e32 v8, v130
	v_mov_b32_e32 v9, v130
	v_cndmask_b32_e64 v13, 0, 1, vcc
	v_cndmask_b32_e64 v13, v13, v14, s[4:5]
	v_and_b32_e32 v13, 1, v13
	v_cmp_eq_u32_e64 s[28:29], 1, v13
	v_or_b32_e32 v13, 19, v0
	v_cmp_le_u32_e32 vcc, v13, v2
	v_mov_b32_e32 v10, v130
	v_mov_b32_e32 v11, v130
	v_cndmask_b32_e64 v14, 0, 1, vcc
	v_cmp_ge_u32_e32 vcc, v13, v2
	s_nop 1
	v_cndmask_b32_e64 v13, 0, 1, vcc
	v_cndmask_b32_e64 v13, v13, v14, s[4:5]
	v_or_b32_e32 v14, 24, v0
	v_cmp_le_u32_e32 vcc, v14, v2
	v_and_b32_e32 v13, 1, v13
	v_cmp_eq_u32_e64 s[30:31], 1, v13
	v_cndmask_b32_e64 v15, 0, 1, vcc
	v_cmp_ge_u32_e32 vcc, v14, v2
	v_lshlrev_b32_e32 v13, 1, v12
	v_lshlrev_b32_e32 v125, 2, v14
	v_cndmask_b32_e64 v16, 0, 1, vcc
	v_cndmask_b32_e64 v15, v16, v15, s[4:5]
	v_and_b32_e32 v15, 1, v15
	v_cmp_eq_u32_e64 s[34:35], 1, v15
	v_or_b32_e32 v15, 25, v0
	v_cmp_le_u32_e32 vcc, v15, v2
	v_lshlrev_b32_e32 v100, 8, v14
	v_add_u32_e32 v131, v5, v13
	v_cndmask_b32_e64 v16, 0, 1, vcc
	v_cmp_ge_u32_e32 vcc, v15, v2
	v_mov_b32_e32 v13, v130
	s_nop 0
	v_cndmask_b32_e64 v15, 0, 1, vcc
	v_cndmask_b32_e64 v15, v15, v16, s[4:5]
	v_and_b32_e32 v15, 1, v15
	v_cmp_eq_u32_e64 s[36:37], 1, v15
	v_or_b32_e32 v15, 26, v0
	v_cmp_le_u32_e32 vcc, v15, v2
	s_nop 1
	v_cndmask_b32_e64 v16, 0, 1, vcc
	v_cmp_ge_u32_e32 vcc, v15, v2
	s_nop 1
	v_cndmask_b32_e64 v15, 0, 1, vcc
	v_cndmask_b32_e64 v15, v15, v16, s[4:5]
	v_and_b32_e32 v15, 1, v15
	v_cmp_eq_u32_e64 s[38:39], 1, v15
	v_or_b32_e32 v15, 27, v0
	v_cmp_le_u32_e32 vcc, v15, v2
	v_lshlrev_b32_e32 v0, 8, v0
	v_lshlrev_b32_e32 v160, 1, v0
	v_cndmask_b32_e64 v16, 0, 1, vcc
	v_cmp_ge_u32_e32 vcc, v15, v2
	v_lshlrev_b32_e32 v15, 1, v14
	v_add_u32_e32 v132, v5, v15
	v_cndmask_b32_e64 v2, 0, 1, vcc
	v_cndmask_b32_e64 v2, v2, v16, s[4:5]
	v_and_b32_e32 v2, 1, v2
	v_cmp_eq_u32_e64 s[40:41], 1, v2
	v_lshlrev_b32_e32 v2, 8, v4
	v_lshlrev_b32_e32 v4, 8, v12
	v_lshlrev_b32_e32 v102, 1, v2
	v_lshlrev_b32_e32 v104, 1, v4
	v_mov_b32_e32 v0, 0
	v_mov_b32_e32 v2, v130
	v_mov_b32_e32 v4, v130
	v_mov_b32_e32 v5, v130
	v_mov_b32_e32 v12, v130
	v_mov_b32_e32 v14, v130
	v_mov_b32_e32 v15, v130
	s_waitcnt vmcnt(0)
	s_branch .LBB0_457
.LBB0_456:
	s_and_b64 s[76:77], s[76:77], exec
	s_waitcnt lgkmcnt(0)
	s_barrier
	s_cselect_b32 s78, s88, 0xd800
	ds_read_b128 v[16:19], v135 offset:36864
	ds_read_b128 v[20:23], v116 offset:27648
	ds_read_b128 v[106:109], v116 offset:27680
	v_add_f32_e32 v136, v32, v33
	v_add_u32_e32 v85, s78, v116
	ds_read_b128 v[32:35], v135
	ds_read_b128 v[138:141], v135 offset:32
	ds_read_b128 v[36:39], v85
	ds_read_b128 v[142:145], v85 offset:32
	ds_read_b128 v[146:149], v135 offset:36896
	s_waitcnt lgkmcnt(6)
	v_mfma_f32_32x32x16_bf16 v[16:31], v[16:19], v[20:23], 0
	s_cmp_gt_u32 s90, 3
	s_cselect_b32 s64, 0x47, 3
	s_add_i32 s64, s64, s47
	s_addk_i32 s64, 0xffba
	s_and_b64 s[76:77], s[4:5], exec
	s_cselect_b32 s64, s90, s64
	s_lshl_b32 s76, s64, 6
	s_waitcnt lgkmcnt(2)
	v_mfma_f32_32x32x16_bf16 v[32:47], v[32:35], v[36:39], 0
	s_add_i32 s78, s76, s66
	s_ashr_i32 s77, s78, 31
	s_add_i32 s76, s76, s84
	s_cmp_lt_i32 s64, 4
	s_cselect_b32 s77, s77, 0
	s_cselect_b32 s76, s78, s76
	s_lshl_b64 s[76:77], s[76:77], 9
	s_waitcnt lgkmcnt(0)
	v_mfma_f32_32x32x16_bf16 v[16:31], v[146:149], v[106:109], v[16:31]
	s_movk_i32 s64, 0x1000
	s_xor_b32 s44, s44, 1
	s_add_i32 s47, s47, -1
	s_cmp_eq_u32 s47, 2
	s_mov_b32 s90, s92
	v_mfma_f32_32x32x16_bf16 v[32:47], v[138:141], v[142:145], v[32:47]
	ds_read_b128 v[106:109], v116 offset:27712
	ds_read_b128 v[138:141], v135 offset:36928
	ds_read_b128 v[142:145], v135 offset:64
	ds_read_b128 v[146:149], v85 offset:64
	s_waitcnt lgkmcnt(2)
	v_mfma_f32_32x32x16_bf16 v[16:31], v[138:141], v[106:109], v[16:31]
	s_waitcnt lgkmcnt(0)
	v_mfma_f32_32x32x16_bf16 v[32:47], v[142:145], v[146:149], v[32:47]
	ds_read_b128 v[106:109], v116 offset:27744
	ds_read_b128 v[138:141], v135 offset:36960
	ds_read_b128 v[142:145], v135 offset:96
	ds_read_b128 v[146:149], v85 offset:96
	v_add_u32_e32 v85, s46, v122
	s_waitcnt lgkmcnt(2)
	v_mfma_f32_32x32x16_bf16 v[16:31], v[138:141], v[106:109], v[16:31]
	ds_read_b128 v[138:141], v85
	v_add_u32_e32 v85, s2, v122
	v_add_u32_e32 v108, s33, v122
	v_lshl_add_u64 v[106:107], v[98:99], 0, s[76:77]
	s_waitcnt lgkmcnt(1)
; #define LAS __attribute__((address_space(3)))
; __device__ __forceinline__ bf16_t f2bf(float f) { return (bf16_t)(pk2(f, 0.f) & 0xffffu); }
; __device__ __forceinline__ float fast_rcp(float x) { return __builtin_amdgcn_rcpf(x); }
; #define ML_BAR() asm volatile("s_waitcnt lgkmcnt(0)\n\ts_barrier" ::: "memory")
; __device__ __forceinline__ void mlstm_unit(const Params& p, int l, int b, int h, LAS unsigned char* lds) {
;     ...
;             const int tau0 = cidx * 64; const size_t rowc = tau0 < CTX ? (size_t)(ctxrow0 + tau0) : (size_t)(latrow0 + tau0 - CTX);
;             bf16_t* hp = HX + rowc * 256 + h * 64 + 32 * vblk + r32;
; #pragma unroll
;             for (int ig = 0; ig < 4; ++ig) { const int t0 = 32 * tblk + 8 * ig + 4 * hi;
;                 const f32x4 d0 = *(const LAS f32x4*)(L + ML_TAB + T_DP0 + t0 * 4), d1 = *(const LAS f32x4*)(L + ML_TAB + T_DP1 + t0 * 4), di = *(const LAS f32x4*)(L + ML_TAB + T_DI + t0 * 4),
;                             w4v = *(const LAS f32x4*)(L + ML_TAB + T_WP + t0 * 4), em = *(const LAS f32x4*)(L + ML_TAB + T_EMT + t0 * 4);
; #pragma unroll
;                 for (int e = 0; e < 4; ++e) { const float den = d0[e] + d1[e] + w4v[e] * di[e]; const float dn = fmaxf(fabsf(den), em[e]);
;                     const float hv = (a1[4 * ig + e] + w4v[e] * a2[4 * ig + e]) * fast_rcp(dn); hp[(size_t)(t0 + e) * 256] = f2bf(hv); } }
;         }
;         mstate = mnext; cur ^= 1;
;         ML_BAR();
	v_mfma_f32_32x32x16_bf16 v[32:47], v[142:145], v[146:149], v[32:47]
	ds_read_b128 v[142:145], v85
	v_add_u32_e32 v85, s67, v122
	ds_read_b128 v[146:149], v85
	ds_read_b128 v[84:87], v84 offset:65024
	ds_read_b128 v[150:153], v108
	s_waitcnt lgkmcnt(3)
	v_add_f32_e32 v108, v138, v142
	s_waitcnt lgkmcnt(1)
	v_fmac_f32_e32 v108, v146, v84
	s_waitcnt lgkmcnt(0)
	v_max_f32_e32 v109, v150, v150
	v_max_f32_e64 v108, |v108|, v109
	v_fma_f32 v16, v32, v84, v16
	v_rcp_f32_e32 v32, v108
	v_lshl_add_u64 v[108:109], v[106:107], 0, v[160:161]
	v_fma_f32 v17, v33, v85, v17
	v_add_u32_e32 v84, s67, v123
	v_mul_f32_e32 v16, v16, v32
	v_cvt_pk_bf16_f32 v16, v16, s0
	global_store_short v[108:109], v16, off
	v_add_f32_e32 v16, v139, v143
	v_fmac_f32_e32 v16, v147, v85
	v_max_f32_e32 v32, v151, v151
	v_max_f32_e64 v16, |v16|, v32
	v_rcp_f32_e32 v16, v16
	v_add_u32_e32 v32, s2, v123
	v_mul_f32_e32 v16, v17, v16
	v_cvt_pk_bf16_f32 v16, v16, s0
	global_store_short v[108:109], v16, off offset:512
	v_add_f32_e32 v16, v140, v144
	v_fmac_f32_e32 v16, v148, v86
	v_max_f32_e32 v17, v152, v152
	v_max_f32_e64 v16, |v16|, v17
	v_rcp_f32_e32 v16, v16
	v_fma_f32 v17, v34, v86, v18
	v_mul_f32_e32 v16, v17, v16
	v_cvt_pk_bf16_f32 v16, v16, s0
	global_store_short v[108:109], v16, off offset:1024
	v_add_f32_e32 v16, v141, v145
	v_fmac_f32_e32 v16, v149, v87
	v_max_f32_e32 v17, v153, v153
	v_max_f32_e64 v16, |v16|, v17
	v_rcp_f32_e32 v16, v16
	v_fma_f32 v17, v35, v87, v19
	ds_read_b128 v[32:35], v32
	v_mul_f32_e32 v16, v17, v16
	v_cvt_pk_bf16_f32 v16, v16, s0
	global_store_short v[108:109], v16, off offset:1536
	v_add_u32_e32 v16, s46, v123
	ds_read_b128 v[16:19], v16
	ds_read_b128 v[84:87], v84
	ds_read_b128 v[138:141], v103 offset:65024
	v_add_u32_e32 v103, s33, v123
	ds_read_b128 v[142:145], v103
	v_mov_b32_e32 v103, v161
	s_waitcnt lgkmcnt(3)
	v_add_f32_e32 v16, v16, v32
	s_waitcnt lgkmcnt(1)
	v_fmac_f32_e32 v16, v84, v138
	v_fma_f32 v20, v36, v138, v20
	s_waitcnt lgkmcnt(0)
	v_max_f32_e32 v32, v142, v142
	v_max_f32_e64 v16, |v16|, v32
	v_rcp_f32_e32 v16, v16
	v_lshl_add_u64 v[146:147], v[106:107], 0, v[102:103]
	v_add_f32_e32 v18, v18, v34
	v_fmac_f32_e32 v18, v86, v140
	v_mul_f32_e32 v16, v20, v16
	v_cvt_pk_bf16_f32 v16, v16, s0
	global_store_short v[146:147], v16, off
	v_add_f32_e32 v16, v17, v33
	v_fmac_f32_e32 v16, v85, v139
	v_max_f32_e32 v17, v143, v143
	v_max_f32_e64 v16, |v16|, v17
	v_rcp_f32_e32 v16, v16
	v_fma_f32 v17, v37, v139, v21
	v_add_u32_e32 v32, s67, v124
	v_add_u32_e32 v84, s33, v124
	v_mul_f32_e32 v16, v17, v16
	v_cvt_pk_bf16_f32 v20, v16, s0
	v_add_co_u32_e32 v16, vcc, s64, v108
	s_movk_i32 s64, 0x2000
	s_nop 0
	v_addc_co_u32_e32 v17, vcc, 0, v109, vcc
	global_store_short v[16:17], v20, off offset:512
	v_max_f32_e32 v20, v144, v144
	v_max_f32_e64 v18, |v18|, v20
	v_rcp_f32_e32 v18, v18
	v_fma_f32 v20, v38, v140, v22
	v_mul_f32_e32 v18, v20, v18
	v_cvt_pk_bf16_f32 v18, v18, s0
	global_store_short v[16:17], v18, off offset:1024
	v_add_f32_e32 v18, v19, v35
	v_fmac_f32_e32 v18, v87, v141
	v_max_f32_e32 v19, v145, v145
	v_max_f32_e64 v18, |v18|, v19
	v_rcp_f32_e32 v18, v18
	v_fma_f32 v19, v39, v141, v23
	v_add_u32_e32 v20, s2, v124
	ds_read_b128 v[20:23], v20
	v_mul_f32_e32 v18, v19, v18
	v_cvt_pk_bf16_f32 v18, v18, s0
	global_store_short v[16:17], v18, off offset:1536
	v_add_u32_e32 v16, s46, v124
	ds_read_b128 v[16:19], v16
	ds_read_b128 v[32:35], v32
	ds_read_b128 v[36:39], v105 offset:65024
	ds_read_b128 v[84:87], v84
	v_mov_b32_e32 v105, v161
	v_lshl_add_u64 v[138:139], v[106:107], 0, v[104:105]
	s_waitcnt lgkmcnt(3)
	v_add_f32_e32 v16, v16, v20
	s_waitcnt lgkmcnt(1)
	v_fmac_f32_e32 v16, v32, v36
	s_waitcnt lgkmcnt(0)
	v_max_f32_e32 v20, v84, v84
	v_max_f32_e64 v16, |v16|, v20
	v_rcp_f32_e32 v16, v16
	v_fma_f32 v20, v40, v36, v24
	v_add_f32_e32 v18, v18, v22
	v_fmac_f32_e32 v18, v34, v38
	v_mul_f32_e32 v16, v20, v16
	v_cvt_pk_bf16_f32 v16, v16, s0
	global_store_short v[138:139], v16, off
	v_add_f32_e32 v16, v17, v21
	v_fmac_f32_e32 v16, v33, v37
	v_max_f32_e32 v17, v85, v85
	v_max_f32_e64 v16, |v16|, v17
	v_rcp_f32_e32 v16, v16
	v_fma_f32 v17, v41, v37, v25
	v_add_u32_e32 v24, s67, v125
	v_add_u32_e32 v36, s33, v125
	v_mul_f32_e32 v16, v17, v16
	v_cvt_pk_bf16_f32 v20, v16, s0
	v_add_co_u32_e32 v16, vcc, s64, v108
	v_lshl_add_u64 v[40:41], v[100:101], 1, v[106:107]
	s_nop 0
	v_addc_co_u32_e32 v17, vcc, 0, v109, vcc
	global_store_short v[16:17], v20, off offset:512
	v_max_f32_e32 v20, v86, v86
	v_max_f32_e64 v18, |v18|, v20
	v_rcp_f32_e32 v18, v18
	v_fma_f32 v20, v42, v38, v26
	s_movk_i32 s64, 0x3000
	v_mul_f32_e32 v18, v20, v18
	v_cvt_pk_bf16_f32 v18, v18, s0
	global_store_short v[16:17], v18, off offset:1024
	v_add_f32_e32 v18, v19, v23
	v_fmac_f32_e32 v18, v35, v39
	v_max_f32_e32 v19, v87, v87
	v_max_f32_e64 v18, |v18|, v19
	v_rcp_f32_e32 v18, v18
	v_fma_f32 v19, v43, v39, v27
	v_add_u32_e32 v20, s2, v125
	ds_read_b128 v[20:23], v20
	v_mul_f32_e32 v18, v19, v18
	v_cvt_pk_bf16_f32 v18, v18, s0
	global_store_short v[16:17], v18, off offset:1536
	v_add_u32_e32 v16, s46, v125
	ds_read_b128 v[16:19], v16
	ds_read_b128 v[24:27], v24
	ds_read_b128 v[32:35], v154 offset:65024
	ds_read_b128 v[36:39], v36
	s_waitcnt lgkmcnt(3)
	v_add_f32_e32 v16, v16, v20
	s_waitcnt lgkmcnt(1)
	v_fmac_f32_e32 v16, v24, v32
	s_waitcnt lgkmcnt(0)
	v_max_f32_e32 v20, v36, v36
	v_max_f32_e64 v16, |v16|, v20
	v_rcp_f32_e32 v16, v16
	v_fma_f32 v20, v44, v32, v28
	v_add_f32_e32 v18, v18, v22
	v_fmac_f32_e32 v18, v26, v34
	v_mul_f32_e32 v16, v20, v16
	v_cvt_pk_bf16_f32 v16, v16, s0
	global_store_short v[40:41], v16, off
	v_add_f32_e32 v16, v17, v21
	v_fmac_f32_e32 v16, v25, v33
	v_max_f32_e32 v17, v37, v37
	v_max_f32_e64 v16, |v16|, v17
	v_rcp_f32_e32 v16, v16
	v_fma_f32 v17, v45, v33, v29
	v_fmac_f32_e32 v31, v47, v35
	v_mul_f32_e32 v16, v17, v16
	v_cvt_pk_bf16_f32 v20, v16, s0
	v_add_co_u32_e32 v16, vcc, s64, v108
	s_nop 1
	v_addc_co_u32_e32 v17, vcc, 0, v109, vcc
	global_store_short v[16:17], v20, off offset:512
	v_max_f32_e32 v20, v38, v38
	v_max_f32_e64 v18, |v18|, v20
	v_rcp_f32_e32 v18, v18
	v_fma_f32 v20, v46, v34, v30
	v_mul_f32_e32 v18, v20, v18
	v_cvt_pk_bf16_f32 v18, v18, s0
	global_store_short v[16:17], v18, off offset:1024
	v_add_f32_e32 v18, v19, v23
	v_fmac_f32_e32 v18, v27, v35
	v_max_f32_e32 v19, v39, v39
	v_max_f32_e64 v18, |v18|, v19
	v_rcp_f32_e32 v18, v18
	s_nop 0
	v_mul_f32_e32 v18, v31, v18
	v_cvt_pk_bf16_f32 v18, v18, s0
	global_store_short v[16:17], v18, off offset:1536
	s_waitcnt lgkmcnt(0)
	s_barrier
	s_cbranch_scc1 .LBB0_472
; #define LAS __attribute__((address_space(3)))
; __device__ __forceinline__ float fast_exp(float x) { return __builtin_amdgcn_exp2f(x * 1.4426950408889634f); }
; __device__ __forceinline__ void mlstm_unit(const Params& p, int l, int b, int h, LAS unsigned char* lds) {
;     ...
;         const int cidx = CHUNK_OF(j);
;         const float bc = rsc[0], av = rsc[1], cm = rsc[2];
;         const float Aq = fmaxf(cm, mstate);
;         const float wp = fast_exp(mstate - Aq), emt = fast_exp(-(bc + Aq));
;         const float A63 = __shfl(Aq, 63), bl = __shfl(bc, 63);
;         const float uu = fast_exp(av - A63), decay = fast_exp(mstate - A63), mnext = bl + A63;
;         if (w4 == 0) { LAS float* tb = (LAS float*)(L + ML_TAB); tb[T_A / 4 + tok] = av; tb[T_BIGA / 4 + tok] = Aq; tb[T_WP / 4 + tok] = wp; tb[T_U / 4 + tok] = uu; tb[T_EMT / 4 + tok] = emt; }
.LBB0_457:
	v_max_f32_e32 v16, v136, v136
	s_waitcnt vmcnt(16)
	v_max_f32_e32 v17, v82, v82
	v_max_f32_e32 v16, v17, v16
	ds_bpermute_b32 v32, v113, v16
	ds_bpermute_b32 v33, v113, v80
	s_andn2_b64 vcc, exec, s[70:71]
	s_cbranch_vccnz .LBB0_459
	s_waitcnt lgkmcnt(1)
	v_sub_f32_e32 v17, v81, v32
	v_sub_f32_e32 v19, v136, v16
	v_mul_f32_e32 v17, 0x3fb8aa3b, v17
	v_add_f32_e32 v18, v80, v16
	v_mul_f32_e32 v19, 0x3fb8aa3b, v19
	v_exp_f32_e32 v17, v17
	v_mul_f32_e32 v18, 0xbfb8aa3b, v18
	v_exp_f32_e32 v19, v19
	v_exp_f32_e32 v18, v18
	ds_write2st64_b32 v114, v81, v16 offset0:252 offset1:253
	ds_write2st64_b32 v114, v19, v17 offset0:254 offset1:255
	ds_write_b32 v115, v18 offset:1024

; #define LAS __attribute__((address_space(3)))
; __device__ __forceinline__ unsigned pk2(float lo, float hi) { f32x2_t v = {lo, hi}; bf16x2_t b = __builtin_convertvector(v, bf16x2_t); return __builtin_bit_cast(unsigned, b); }
; __device__ __forceinline__ float fast_exp(float x) { return __builtin_amdgcn_exp2f(x * 1.4426950408889634f); }
; #define MFMA32(a, b, c) __builtin_amdgcn_mfma_f32_32x32x16_bf16((a), (b), (c), 0, 0, 0)
; #define ML_BAR() asm volatile("s_waitcnt lgkmcnt(0)\n\ts_barrier" ::: "memory")
; __device__ __forceinline__ void mlstm_unit(const Params& p, int l, int b, int h, LAS unsigned char* lds) {
;     ...
;         ML_BAR();
;         const LAS unsigned char* CTc = L + (cur ? ML_CT1 : ML_CT0); LAS unsigned char* CTn = L + (cur ? ML_CT0 : ML_CT1);
;         const LAS float* tb = (const LAS float*)(L + ML_TAB);
;         {
;             const int sblk = w4 & 1, tblk = w4 >> 1;
;             f32x16 st;
; #pragma unroll
;             for (int i = 0; i < 16; ++i) st[i] = 0.f;
; #pragma unroll
;             for (int c = 0; c < 4; ++c) { const bf16x8 af = lds_rd16(L + ML_KS + (32 * sblk + r32) * 144 + hi * 16 + c * 32), bfr = lds_rd16(L + ML_QS + (32 * tblk + r32) * 144 + hi * 16 + c * 32); st = MFMA32(af, bfr, st); }
;             const int t = 32 * tblk + r32; const float At = tb[T_BIGA / 4 + t];
;             float dsum = 0.f;
; #pragma unroll
;             for (int ig = 0; ig < 4; ++ig) { const int s0 = 32 * sblk + 8 * ig + 4 * hi; const f32x4 a4 = *(const LAS f32x4*)(L + ML_TAB + T_A + s0 * 4);
;                 float w[4];
; #pragma unroll
;                 for (int e = 0; e < 4; ++e) { const int s = s0 + e; const bool valid = g ? (s >= t) : (s <= t); const float ex = fast_exp(fminf(a4[e] - At, 0.f)); w[e] = valid ? st[4 * ig + e] * ex : 0.f; dsum += w[e]; }
;                 u32x2 pw; pw.x = pk2(w[0], w[1]); pw.y = pk2(w[2], w[3]); *(LAS u32x2*)(L + ML_SW + t * 144 + s0 * 2) = pw; }
;             dsum += __shfl_xor(dsum, 32);
;             if (hi == 0) *(LAS float*)(L + ML_TAB + (sblk ? T_DP1 : T_DP0) + t * 4) = dsum;
.LBB0_464:
	s_waitcnt lgkmcnt(0)
	s_barrier
	ds_read_b128 v[16:19], v135 offset:9216
	ds_read_b128 v[34:37], v135 offset:9248
	ds_read_b128 v[20:23], v116
	ds_read_b128 v[38:41], v116 offset:32
	v_add_u32_e32 v84, s85, v122
	v_add_u32_e32 v103, s85, v123
	v_add_u32_e32 v105, s85, v124
	s_waitcnt lgkmcnt(1)
	v_mfma_f32_32x32x16_bf16 v[16:31], v[16:19], v[20:23], 0
	v_add_u32_e32 v154, s85, v125
	s_waitcnt lgkmcnt(0)
	v_mfma_f32_32x32x16_bf16 v[16:31], v[34:37], v[38:41], v[16:31]
	ds_read_b128 v[34:37], v135 offset:9280
	ds_read_b128 v[38:41], v116 offset:64
	s_waitcnt lgkmcnt(0)
	v_mfma_f32_32x32x16_bf16 v[16:31], v[34:37], v[38:41], v[16:31]
	ds_read_b128 v[34:37], v135 offset:9312
	ds_read_b128 v[38:41], v116 offset:96
	s_waitcnt lgkmcnt(0)
	v_mfma_f32_32x32x16_bf16 v[16:31], v[34:37], v[38:41], v[16:31]
	ds_read_b32 v34, v127 offset:64768
	ds_read_b128 v[36:39], v84 offset:64512
	s_waitcnt lgkmcnt(0)
	v_sub_f32_e32 v35, v36, v34
	v_sub_f32_e32 v36, v37, v34
	v_min_f32_e32 v36, 0, v36
	v_mul_f32_e32 v36, 0x3fb8aa3b, v36
	v_exp_f32_e32 v36, v36
	v_min_f32_e32 v35, 0, v35
	v_mul_f32_e32 v35, 0x3fb8aa3b, v35
	v_exp_f32_e32 v35, v35
	s_nop 0
	v_mul_f32_e32 v17, v17, v36
	v_sub_f32_e32 v36, v38, v34
	v_min_f32_e32 v36, 0, v36
	v_mul_f32_e32 v36, 0x3fb8aa3b, v36
	v_exp_f32_e32 v36, v36
	v_mul_f32_e32 v16, v16, v35
	v_cndmask_b32_e64 v16, 0, v16, s[8:9]
	v_add_f32_e32 v35, 0, v16
	v_mul_f32_e32 v18, v18, v36
	v_sub_f32_e32 v36, v39, v34
	v_min_f32_e32 v36, 0, v36
	v_mul_f32_e32 v36, 0x3fb8aa3b, v36
	v_exp_f32_e32 v36, v36
	v_cndmask_b32_e64 v17, 0, v17, s[10:11]
	v_cndmask_b32_e64 v18, 0, v18, s[12:13]
	v_add_f32_e32 v35, v17, v35
	v_mul_f32_e32 v19, v19, v36
	v_cndmask_b32_e64 v19, 0, v19, s[14:15]
	v_cvt_pk_bf16_f32 v16, v16, v17
	v_cvt_pk_bf16_f32 v17, v18, v19
	v_add_f32_e32 v35, v18, v35
	ds_write_b64 v128, v[16:17] offset:36864
	v_add_f32_e32 v35, v19, v35
	ds_read_b128 v[16:19], v103 offset:64512
	s_waitcnt lgkmcnt(0)
	v_sub_f32_e32 v16, v16, v34
	v_min_f32_e32 v16, 0, v16
	v_sub_f32_e32 v17, v17, v34
	v_sub_f32_e32 v18, v18, v34
	v_sub_f32_e32 v19, v19, v34
	v_mul_f32_e32 v16, 0x3fb8aa3b, v16
	v_min_f32_e32 v17, 0, v17
	v_min_f32_e32 v18, 0, v18
	v_min_f32_e32 v19, 0, v19
	v_exp_f32_e32 v16, v16
	v_mul_f32_e32 v17, 0x3fb8aa3b, v17
	v_mul_f32_e32 v18, 0x3fb8aa3b, v18
	v_mul_f32_e32 v19, 0x3fb8aa3b, v19
	v_exp_f32_e32 v17, v17
	v_exp_f32_e32 v18, v18
	v_exp_f32_e32 v19, v19
	v_mul_f32_e32 v16, v20, v16
	v_cndmask_b32_e64 v16, 0, v16, s[16:17]
	v_mul_f32_e32 v17, v21, v17
	v_mul_f32_e32 v18, v22, v18
	v_mul_f32_e32 v19, v23, v19
	v_add_f32_e32 v20, v16, v35
	v_cndmask_b32_e64 v17, 0, v17, s[18:19]
	v_cndmask_b32_e64 v18, 0, v18, s[20:21]
	v_cndmask_b32_e64 v19, 0, v19, s[22:23]
	v_add_f32_e32 v20, v17, v20
	v_cvt_pk_bf16_f32 v16, v16, v17
	v_cvt_pk_bf16_f32 v17, v18, v19
	v_add_f32_e32 v20, v18, v20
	ds_write_b64 v129, v[16:17] offset:36864
	v_add_f32_e32 v20, v19, v20
	ds_read_b128 v[16:19], v105 offset:64512
	s_waitcnt lgkmcnt(0)
	v_sub_f32_e32 v16, v16, v34
	v_min_f32_e32 v16, 0, v16
	v_sub_f32_e32 v17, v17, v34
	v_sub_f32_e32 v18, v18, v34
	v_sub_f32_e32 v19, v19, v34
	v_mul_f32_e32 v16, 0x3fb8aa3b, v16
	v_min_f32_e32 v17, 0, v17
	v_min_f32_e32 v18, 0, v18
	v_min_f32_e32 v19, 0, v19
	v_exp_f32_e32 v16, v16
	v_mul_f32_e32 v17, 0x3fb8aa3b, v17
	v_mul_f32_e32 v18, 0x3fb8aa3b, v18
	v_mul_f32_e32 v19, 0x3fb8aa3b, v19
	v_exp_f32_e32 v17, v17
	v_exp_f32_e32 v18, v18
	v_exp_f32_e32 v19, v19
	v_mul_f32_e32 v16, v24, v16
	v_cndmask_b32_e64 v16, 0, v16, s[24:25]
	v_mul_f32_e32 v17, v25, v17
	v_mul_f32_e32 v18, v26, v18
	v_mul_f32_e32 v19, v27, v19
	v_add_f32_e32 v20, v16, v20
	v_cndmask_b32_e64 v17, 0, v17, s[26:27]
	v_cndmask_b32_e64 v18, 0, v18, s[28:29]
	v_cndmask_b32_e64 v19, 0, v19, s[30:31]
	v_add_f32_e32 v20, v17, v20
	v_cvt_pk_bf16_f32 v16, v16, v17
	v_cvt_pk_bf16_f32 v17, v18, v19
	v_add_f32_e32 v20, v18, v20
	ds_write_b64 v131, v[16:17] offset:36864
	v_add_f32_e32 v20, v19, v20
	ds_read_b128 v[16:19], v154 offset:64512
	s_waitcnt lgkmcnt(0)
	v_sub_f32_e32 v16, v16, v34
	v_min_f32_e32 v16, 0, v16
	v_sub_f32_e32 v18, v18, v34
	v_mul_f32_e32 v16, 0x3fb8aa3b, v16
	v_min_f32_e32 v18, 0, v18
	v_exp_f32_e32 v16, v16
	v_mul_f32_e32 v18, 0x3fb8aa3b, v18
	v_exp_f32_e32 v18, v18
	v_sub_f32_e32 v17, v17, v34
	v_mul_f32_e32 v16, v28, v16
	v_cndmask_b32_e64 v21, 0, v16, s[34:35]
	v_min_f32_e32 v17, 0, v17
	v_mul_f32_e32 v18, v30, v18
	v_add_f32_e32 v16, v21, v20
	v_mul_f32_e32 v17, 0x3fb8aa3b, v17
	v_cndmask_b32_e64 v20, 0, v18, s[38:39]
	v_sub_f32_e32 v18, v19, v34
	v_exp_f32_e32 v17, v17
	v_min_f32_e32 v18, 0, v18
	v_mul_f32_e32 v18, 0x3fb8aa3b, v18
	v_exp_f32_e32 v18, v18
	v_mul_f32_e32 v17, v29, v17
	v_cndmask_b32_e64 v17, 0, v17, s[36:37]
	v_add_f32_e32 v16, v17, v16
	v_mul_f32_e32 v18, v31, v18
	v_add_f32_e32 v16, v20, v16
	v_cndmask_b32_e64 v19, 0, v18, s[40:41]
	v_add_f32_e32 v16, v19, v16
	v_cvt_pk_bf16_f32 v18, v21, v17
	ds_bpermute_b32 v17, v117, v16
	v_cvt_pk_bf16_f32 v19, v20, v19
	ds_write_b64 v132, v[18:19] offset:36864
	s_and_saveexec_b64 s[76:77], s[6:7]
	s_cbranch_execz .LBB0_466
	s_waitcnt lgkmcnt(1)
	v_add_f32_e32 v16, v16, v17
	ds_write_b32 v133, v16 offset:64512

; #define PG8_STAGE(bufoff, gbase, voff) do { _Pragma("unroll") for (int _i = 0; _i < 2; ++_i) \
;         __builtin_amdgcn_global_load_lds((const unsigned*)((const char*)(gbase) + (voff)[_i]), (PG8_LAS unsigned*)(lds + (bufoff) + ldsw + _i * 8192), 16, 0, 0); } while (0)
; #define PG8_LDA(dst, b, h) do { _Pragma("unroll") for (int m = 0; m < 4; ++m) _Pragma("unroll") for (int k = 0; k < 2; ++k) dst[m][k] = *(const PG8_LAS bf16x8*)(lds + PG8_SA(b, h) + aoff + m * 2048 + k * 1024); } while (0)
; #define PG8_LDB(dst, b, h) do { _Pragma("unroll") for (int n = 0; n < 2; ++n) _Pragma("unroll") for (int k = 0; k < 2; ++k) dst[n][k] = *(const PG8_LAS bf16x8*)(lds + PG8_SB(b, h) + boff + n * 2048 + k * 1024); } while (0)
; #define PG8_MMA(ai, bj, At, Bt) do { __builtin_amdgcn_s_setprio(1); _Pragma("unroll") for (int m = 0; m < 4; ++m) _Pragma("unroll") for (int n = 0; n < 2; ++n) _Pragma("unroll") for (int k = 0; k < 2; ++k) \
;         acc[ai][bj][m][n] = __builtin_amdgcn_mfma_f32_16x16x32_bf16(Bt[n][k], At[m][k], acc[ai][bj][m][n], 0, 0, 0); __builtin_amdgcn_s_setprio(0); } while (0)
; #define PG8_WAIT_V(n) asm volatile("s_waitcnt vmcnt(" #n ")" ::: "memory")
; #define PG8_BAR __builtin_amdgcn_s_barrier()
; template <class Epi, class Sched, bool ALIGN_EPI = false, bool SP2 = false>
; __device__ __forceinline__ void gemm_phase(PG8_LAS unsigned char* lds, const Gemm g, const Sched& S, const Epi& E) {
;     ...
;         for (int t = 0; t < nt; t += 2) {
;             const bool last = (t == nt - 2);
;             const char* a1 = cA + (size_t)(t + 1) * kstep;
;             const char* a2 = last ? nA : cA + (size_t)(t + 2) * kstep; const char* b2 = last ? nB : cB + (size_t)(t + 2) * kstep;
;             const char* a3 = a2 + kstep; const char* b3 = b2 + kstep;
;             if (last && has_next) S.a_ready(nxt);
;             if constexpr (SP2) {
;             PG8_LDB(B0, 0, 0); PG8_LDB(B1, 0, 1); PG8_SCHED; PG8_LDA(At, 0, 0); PG8_STAGE(PG8_SA(1, 1), a1 + hstep, voffA);
;             PG8_WAIT_V(8); PG8_WAIT_L(0); PG8_BAR; PG8_MMA(0, 0, At, B0); PG8_MMA(0, 1, At, B1); PG8_BAR; PG8_SCHED;
;             PG8_LDA(At, 0, 1); PG8_STAGE(PG8_SB(0, 0), b2, voffB); PG8_STAGE(PG8_SB(0, 1), b2 + hstep, voffB); PG8_STAGE(PG8_SA(0, 0), a2, voffA);
;             PG8_WAIT_V(8); PG8_WAIT_L(0); PG8_BAR; PG8_MMA(1, 0, At, B0); PG8_MMA(1, 1, At, B1); PG8_BAR; PG8_SCHED;
.LBB0_613:
	s_add_u32 s24, s22, 0xfffc0080
	s_addc_u32 s25, s23, -1
	s_add_i32 s47, 0, 0x10000
	s_cmp_eq_u32 s46, 12
	s_cselect_b32 s27, s15, s25
	s_cselect_b32 s26, s38, s24
	s_cselect_b32 s25, s13, s45
	s_cselect_b32 s24, s39, s44
	s_add_i32 s64, 0, 0x14000
	v_add_u32_e32 v154, s47, v139
	v_add_u32_e32 v158, s64, v139
	ds_read_b128 v[142:145], v154
	ds_read_b128 v[146:149], v154 offset:1024
	ds_read_b128 v[150:153], v154 offset:2048
	ds_read_b128 v[154:157], v154 offset:3072
	ds_read_b128 v[162:165], v158
	ds_read_b128 v[166:169], v158 offset:1024
	ds_read_b128 v[170:173], v158 offset:2048
	ds_read_b128 v[174:177], v158 offset:3072
	v_lshl_add_u64 v[158:159], s[22:23], 0, v[134:135]
	s_add_i32 m0, s28, 0xc000
	ds_read_b128 v[178:181], v141
	ds_read_b128 v[182:185], v141 offset:1024
	ds_read_b128 v[186:189], v141 offset:2048
	ds_read_b128 v[190:193], v141 offset:3072
	ds_read_b128 v[196:199], v141 offset:4096
	ds_read_b128 v[200:203], v141 offset:5120
	ds_read_b128 v[204:207], v141 offset:6144
	ds_read_b128 v[208:211], v141 offset:7168
	global_load_lds_dwordx4 v[158:159], off
	v_lshl_add_u64 v[158:159], s[22:23], 0, v[136:137]
	s_add_i32 m0, s28, 0xe000
	s_nop 0
	global_load_lds_dwordx4 v[158:159], off
	s_waitcnt vmcnt(8)
	s_waitcnt lgkmcnt(0)
	s_barrier
	s_setprio 1
	v_mfma_f32_16x16x32_bf16 v[124:127], v[142:145], v[178:181], v[124:127]
	v_mfma_f32_16x16x32_bf16 v[120:123], v[150:153], v[178:181], v[120:123]
	v_mfma_f32_16x16x32_bf16 v[116:119], v[142:145], v[186:189], v[116:119]
	v_mfma_f32_16x16x32_bf16 v[112:115], v[150:153], v[186:189], v[112:115]
	v_mfma_f32_16x16x32_bf16 v[100:103], v[142:145], v[196:199], v[100:103]
	v_mfma_f32_16x16x32_bf16 v[96:99], v[150:153], v[196:199], v[96:99]
	v_mfma_f32_16x16x32_bf16 v[84:87], v[142:145], v[204:207], v[84:87]
	v_mfma_f32_16x16x32_bf16 v[80:83], v[150:153], v[204:207], v[80:83]
	v_mfma_f32_16x16x32_bf16 v[124:127], v[146:149], v[182:185], v[124:127]
	v_mfma_f32_16x16x32_bf16 v[120:123], v[154:157], v[182:185], v[120:123]
	v_mfma_f32_16x16x32_bf16 v[116:119], v[146:149], v[190:193], v[116:119]
	v_mfma_f32_16x16x32_bf16 v[112:115], v[154:157], v[190:193], v[112:115]
	v_mfma_f32_16x16x32_bf16 v[100:103], v[146:149], v[200:203], v[100:103]
	v_mfma_f32_16x16x32_bf16 v[96:99], v[154:157], v[200:203], v[96:99]
	v_mfma_f32_16x16x32_bf16 v[84:87], v[146:149], v[208:211], v[84:87]
	v_mfma_f32_16x16x32_bf16 v[80:83], v[154:157], v[208:211], v[80:83]
	v_mfma_f32_16x16x32_bf16 v[108:111], v[162:165], v[178:181], v[108:111]
	v_mfma_f32_16x16x32_bf16 v[104:107], v[170:173], v[178:181], v[104:107]
	v_mfma_f32_16x16x32_bf16 v[92:95], v[162:165], v[186:189], v[92:95]
	v_mfma_f32_16x16x32_bf16 v[88:91], v[170:173], v[186:189], v[88:91]
	v_mfma_f32_16x16x32_bf16 v[76:79], v[162:165], v[196:199], v[76:79]
	v_mfma_f32_16x16x32_bf16 v[72:75], v[170:173], v[196:199], v[72:75]
	v_mfma_f32_16x16x32_bf16 v[68:71], v[162:165], v[204:207], v[68:71]
	v_mfma_f32_16x16x32_bf16 v[64:67], v[170:173], v[204:207], v[64:67]
	v_mfma_f32_16x16x32_bf16 v[108:111], v[166:169], v[182:185], v[108:111]
	v_mfma_f32_16x16x32_bf16 v[104:107], v[174:177], v[182:185], v[104:107]
	v_mfma_f32_16x16x32_bf16 v[92:95], v[166:169], v[190:193], v[92:95]
	v_mfma_f32_16x16x32_bf16 v[88:91], v[174:177], v[190:193], v[88:91]
	v_mfma_f32_16x16x32_bf16 v[76:79], v[166:169], v[200:203], v[76:79]
	v_mfma_f32_16x16x32_bf16 v[72:75], v[174:177], v[200:203], v[72:75]
	v_mfma_f32_16x16x32_bf16 v[68:71], v[166:169], v[208:211], v[68:71]
	v_mfma_f32_16x16x32_bf16 v[64:67], v[174:177], v[208:211], v[64:67]
	s_setprio 0
	s_barrier
	s_add_i32 s47, s47, s2
	v_lshl_add_u64 v[158:159], s[24:25], 0, v[160:161]
	s_mov_b32 m0, s47
	ds_read_b128 v[178:181], v141 offset:16384
	ds_read_b128 v[182:185], v141 offset:17408
	ds_read_b128 v[186:189], v141 offset:18432
	ds_read_b128 v[190:193], v141 offset:19456
	ds_read_b128 v[196:199], v141 offset:20480
	ds_read_b128 v[200:203], v141 offset:21504
	ds_read_b128 v[204:207], v141 offset:22528
	ds_read_b128 v[208:211], v141 offset:23552
	global_load_lds_dwordx4 v[158:159], off
	s_add_i32 m0, s47, 0x2000
	s_add_u32 s66, s24, 0x40000
	v_lshl_add_u64 v[212:213], s[24:25], 0, v[128:129]
	s_addc_u32 s67, s25, 0
	s_add_i32 s47, s64, s2
	global_load_lds_dwordx4 v[212:213], off
	v_lshl_add_u64 v[214:215], s[66:67], 0, v[160:161]
	s_mov_b32 m0, s47
	v_lshl_add_u64 v[216:217], s[26:27], 0, v[130:131]
	global_load_lds_dwordx4 v[214:215], off
	v_lshl_add_u64 v[214:215], s[66:67], 0, v[128:129]
	s_add_i32 m0, s47, 0x2000
	s_nop 0
	global_load_lds_dwordx4 v[214:215], off
	v_lshl_add_u64 v[214:215], s[26:27], 0, v[132:133]
	s_mov_b32 m0, s28
	s_nop 0
	global_load_lds_dwordx4 v[214:215], off
	s_mov_b32 m0, s29
	s_nop 0
	global_load_lds_dwordx4 v[216:217], off
	s_waitcnt vmcnt(8)
	s_waitcnt lgkmcnt(0)
	s_barrier
; #define PG8_STAGE(bufoff, gbase, voff) do { _Pragma("unroll") for (int _i = 0; _i < 2; ++_i) \
;         __builtin_amdgcn_global_load_lds((const unsigned*)((const char*)(gbase) + (voff)[_i]), (PG8_LAS unsigned*)(lds + (bufoff) + ldsw + _i * 8192), 16, 0, 0); } while (0)
; #define PG8_LDA(dst, b, h) do { _Pragma("unroll") for (int m = 0; m < 4; ++m) _Pragma("unroll") for (int k = 0; k < 2; ++k) dst[m][k] = *(const PG8_LAS bf16x8*)(lds + PG8_SA(b, h) + aoff + m * 2048 + k * 1024); } while (0)
; #define PG8_LDB(dst, b, h) do { _Pragma("unroll") for (int n = 0; n < 2; ++n) _Pragma("unroll") for (int k = 0; k < 2; ++k) dst[n][k] = *(const PG8_LAS bf16x8*)(lds + PG8_SB(b, h) + boff + n * 2048 + k * 1024); } while (0)
; #define PG8_MMA(ai, bj, At, Bt) do { __builtin_amdgcn_s_setprio(1); _Pragma("unroll") for (int m = 0; m < 4; ++m) _Pragma("unroll") for (int n = 0; n < 2; ++n) _Pragma("unroll") for (int k = 0; k < 2; ++k) \
;         acc[ai][bj][m][n] = __builtin_amdgcn_mfma_f32_16x16x32_bf16(Bt[n][k], At[m][k], acc[ai][bj][m][n], 0, 0, 0); __builtin_amdgcn_s_setprio(0); } while (0)
; #define PG8_WAIT_V(n) asm volatile("s_waitcnt vmcnt(" #n ")" ::: "memory")
; #define PG8_WAIT_L(n) asm volatile("s_waitcnt lgkmcnt(" #n ")" ::: "memory")
; #define PG8_BAR __builtin_amdgcn_s_barrier()
; #define PG8_SCHED __builtin_amdgcn_sched_barrier(0)
; template <class Epi, class Sched, bool ALIGN_EPI = false, bool SP2 = false>
; __device__ __forceinline__ void gemm_phase(PG8_LAS unsigned char* lds, const Gemm g, const Sched& S, const Epi& E) {
;     ...
;             PG8_WAIT_V(8); PG8_WAIT_L(0); PG8_BAR; PG8_MMA(1, 0, At, B0); PG8_MMA(1, 1, At, B1); PG8_BAR; PG8_SCHED;
;             PG8_LDB(B0, 1, 0); PG8_LDB(B1, 1, 1); PG8_SCHED; PG8_LDA(At, 1, 0); PG8_STAGE(PG8_SA(0, 1), a2 + hstep, voffA);
;             PG8_WAIT_V(8); PG8_WAIT_L(0); PG8_BAR; PG8_MMA(0, 0, At, B0); PG8_MMA(0, 1, At, B1); PG8_BAR; PG8_SCHED;
	s_setprio 1
	v_mfma_f32_16x16x32_bf16 v[60:63], v[142:145], v[178:181], v[60:63]
	v_mfma_f32_16x16x32_bf16 v[56:59], v[150:153], v[178:181], v[56:59]
	v_mfma_f32_16x16x32_bf16 v[52:55], v[142:145], v[186:189], v[52:55]
	v_mfma_f32_16x16x32_bf16 v[48:51], v[150:153], v[186:189], v[48:51]
	v_mfma_f32_16x16x32_bf16 v[36:39], v[142:145], v[196:199], v[36:39]
	v_mfma_f32_16x16x32_bf16 v[32:35], v[150:153], v[196:199], v[32:35]
	v_mfma_f32_16x16x32_bf16 v[20:23], v[142:145], v[204:207], v[20:23]
	v_mfma_f32_16x16x32_bf16 v[16:19], v[150:153], v[204:207], v[16:19]
	v_mfma_f32_16x16x32_bf16 v[60:63], v[146:149], v[182:185], v[60:63]
	v_mfma_f32_16x16x32_bf16 v[56:59], v[154:157], v[182:185], v[56:59]
	v_mfma_f32_16x16x32_bf16 v[52:55], v[146:149], v[190:193], v[52:55]
	v_mfma_f32_16x16x32_bf16 v[48:51], v[154:157], v[190:193], v[48:51]
	v_mfma_f32_16x16x32_bf16 v[36:39], v[146:149], v[200:203], v[36:39]
	v_mfma_f32_16x16x32_bf16 v[32:35], v[154:157], v[200:203], v[32:35]
	v_mfma_f32_16x16x32_bf16 v[20:23], v[146:149], v[208:211], v[20:23]
	v_mfma_f32_16x16x32_bf16 v[16:19], v[154:157], v[208:211], v[16:19]
	v_mfma_f32_16x16x32_bf16 v[44:47], v[162:165], v[178:181], v[44:47]
	v_mfma_f32_16x16x32_bf16 v[40:43], v[170:173], v[178:181], v[40:43]
	v_mfma_f32_16x16x32_bf16 v[28:31], v[162:165], v[186:189], v[28:31]
	v_mfma_f32_16x16x32_bf16 v[24:27], v[170:173], v[186:189], v[24:27]
	v_mfma_f32_16x16x32_bf16 v[12:15], v[162:165], v[196:199], v[12:15]
	v_mfma_f32_16x16x32_bf16 v[8:11], v[170:173], v[196:199], v[8:11]
	v_mfma_f32_16x16x32_bf16 v[4:7], v[162:165], v[204:207], v[4:7]
	v_mfma_f32_16x16x32_bf16 v[0:3], v[170:173], v[204:207], v[0:3]
	v_mfma_f32_16x16x32_bf16 v[44:47], v[166:169], v[182:185], v[44:47]
	v_mfma_f32_16x16x32_bf16 v[40:43], v[174:177], v[182:185], v[40:43]
	v_mfma_f32_16x16x32_bf16 v[28:31], v[166:169], v[190:193], v[28:31]
	v_mfma_f32_16x16x32_bf16 v[24:27], v[174:177], v[190:193], v[24:27]
	v_mfma_f32_16x16x32_bf16 v[12:15], v[166:169], v[200:203], v[12:15]
	v_mfma_f32_16x16x32_bf16 v[8:11], v[174:177], v[200:203], v[8:11]
	v_mfma_f32_16x16x32_bf16 v[4:7], v[166:169], v[208:211], v[4:7]
	v_mfma_f32_16x16x32_bf16 v[0:3], v[174:177], v[208:211], v[0:3]
	s_setprio 0
	s_barrier
	s_add_i32 s47, 0, 0x18000
	s_add_i32 s64, 0, 0x1c000
	v_add_u32_e32 v154, s47, v139
	v_add_u32_e32 v174, s64, v139
	ds_read_b128 v[142:145], v154
	ds_read_b128 v[146:149], v154 offset:1024
	ds_read_b128 v[150:153], v154 offset:2048
	ds_read_b128 v[154:157], v154 offset:3072
	ds_read_b128 v[162:165], v174
	ds_read_b128 v[166:169], v174 offset:1024
	ds_read_b128 v[170:173], v174 offset:2048
	ds_read_b128 v[174:177], v174 offset:3072
	s_add_u32 s26, s26, 0x40000
	s_addc_u32 s27, s27, 0
	s_mov_b32 m0, s30
	v_lshl_add_u64 v[228:229], s[26:27], 0, v[132:133]
	ds_read_b128 v[178:181], v141 offset:32768
	ds_read_b128 v[182:185], v141 offset:33792
	ds_read_b128 v[186:189], v141 offset:34816
	ds_read_b128 v[190:193], v141 offset:35840
	ds_read_b128 v[196:199], v141 offset:36864
	ds_read_b128 v[200:203], v141 offset:37888
	ds_read_b128 v[204:207], v141 offset:38912
	ds_read_b128 v[208:211], v141 offset:39936
	global_load_lds_dwordx4 v[228:229], off
	v_lshl_add_u64 v[228:229], s[26:27], 0, v[130:131]
	s_mov_b32 m0, s31
	s_nop 0
	global_load_lds_dwordx4 v[228:229], off
	s_waitcnt vmcnt(8)
	s_waitcnt lgkmcnt(0)
	s_barrier
	s_setprio 1
	v_mfma_f32_16x16x32_bf16 v[124:127], v[142:145], v[178:181], v[124:127]
	v_mfma_f32_16x16x32_bf16 v[120:123], v[150:153], v[178:181], v[120:123]
	v_mfma_f32_16x16x32_bf16 v[116:119], v[142:145], v[186:189], v[116:119]
	v_mfma_f32_16x16x32_bf16 v[112:115], v[150:153], v[186:189], v[112:115]
	v_mfma_f32_16x16x32_bf16 v[100:103], v[142:145], v[196:199], v[100:103]
	v_mfma_f32_16x16x32_bf16 v[96:99], v[150:153], v[196:199], v[96:99]
	v_mfma_f32_16x16x32_bf16 v[84:87], v[142:145], v[204:207], v[84:87]
	v_mfma_f32_16x16x32_bf16 v[80:83], v[150:153], v[204:207], v[80:83]
	v_mfma_f32_16x16x32_bf16 v[124:127], v[146:149], v[182:185], v[124:127]
	v_mfma_f32_16x16x32_bf16 v[120:123], v[154:157], v[182:185], v[120:123]
	v_mfma_f32_16x16x32_bf16 v[116:119], v[146:149], v[190:193], v[116:119]
	v_mfma_f32_16x16x32_bf16 v[112:115], v[154:157], v[190:193], v[112:115]
	v_mfma_f32_16x16x32_bf16 v[100:103], v[146:149], v[200:203], v[100:103]
	v_mfma_f32_16x16x32_bf16 v[96:99], v[154:157], v[200:203], v[96:99]
	v_mfma_f32_16x16x32_bf16 v[84:87], v[146:149], v[208:211], v[84:87]
	v_mfma_f32_16x16x32_bf16 v[80:83], v[154:157], v[208:211], v[80:83]
	v_mfma_f32_16x16x32_bf16 v[108:111], v[162:165], v[178:181], v[108:111]
	v_mfma_f32_16x16x32_bf16 v[104:107], v[170:173], v[178:181], v[104:107]
	v_mfma_f32_16x16x32_bf16 v[92:95], v[162:165], v[186:189], v[92:95]
	v_mfma_f32_16x16x32_bf16 v[88:91], v[170:173], v[186:189], v[88:91]
	v_mfma_f32_16x16x32_bf16 v[76:79], v[162:165], v[196:199], v[76:79]
	v_mfma_f32_16x16x32_bf16 v[72:75], v[170:173], v[196:199], v[72:75]
	v_mfma_f32_16x16x32_bf16 v[68:71], v[162:165], v[204:207], v[68:71]
	v_mfma_f32_16x16x32_bf16 v[64:67], v[170:173], v[204:207], v[64:67]
	v_mfma_f32_16x16x32_bf16 v[108:111], v[166:169], v[182:185], v[108:111]
	v_mfma_f32_16x16x32_bf16 v[104:107], v[174:177], v[182:185], v[104:107]
	v_mfma_f32_16x16x32_bf16 v[92:95], v[166:169], v[190:193], v[92:95]
	v_mfma_f32_16x16x32_bf16 v[88:91], v[174:177], v[190:193], v[88:91]
	v_mfma_f32_16x16x32_bf16 v[76:79], v[166:169], v[200:203], v[76:79]
	v_mfma_f32_16x16x32_bf16 v[72:75], v[174:177], v[200:203], v[72:75]
	v_mfma_f32_16x16x32_bf16 v[68:71], v[166:169], v[208:211], v[68:71]
	v_mfma_f32_16x16x32_bf16 v[64:67], v[174:177], v[208:211], v[64:67]
	s_setprio 0
	s_barrier
; #define PG8_STAGE(bufoff, gbase, voff) do { _Pragma("unroll") for (int _i = 0; _i < 2; ++_i) \
;         __builtin_amdgcn_global_load_lds((const unsigned*)((const char*)(gbase) + (voff)[_i]), (PG8_LAS unsigned*)(lds + (bufoff) + ldsw + _i * 8192), 16, 0, 0); } while (0)
; #define PG8_LDA(dst, b, h) do { _Pragma("unroll") for (int m = 0; m < 4; ++m) _Pragma("unroll") for (int k = 0; k < 2; ++k) dst[m][k] = *(const PG8_LAS bf16x8*)(lds + PG8_SA(b, h) + aoff + m * 2048 + k * 1024); } while (0)
; #define PG8_MMA(ai, bj, At, Bt) do { __builtin_amdgcn_s_setprio(1); _Pragma("unroll") for (int m = 0; m < 4; ++m) _Pragma("unroll") for (int n = 0; n < 2; ++n) _Pragma("unroll") for (int k = 0; k < 2; ++k) \
;         acc[ai][bj][m][n] = __builtin_amdgcn_mfma_f32_16x16x32_bf16(Bt[n][k], At[m][k], acc[ai][bj][m][n], 0, 0, 0); __builtin_amdgcn_s_setprio(0); } while (0)
; #define PG8_WAIT_V(n) asm volatile("s_waitcnt vmcnt(" #n ")" ::: "memory")
; #define PG8_WAIT_L(n) asm volatile("s_waitcnt lgkmcnt(" #n ")" ::: "memory")
; #define PG8_BAR __builtin_amdgcn_s_barrier()
; #define PG8_SCHED __builtin_amdgcn_sched_barrier(0)
; template <class Epi, class Sched, bool ALIGN_EPI = false, bool SP2 = false>
; __device__ __forceinline__ void gemm_phase(PG8_LAS unsigned char* lds, const Gemm g, const Sched& S, const Epi& E) {
;     ...
;             PG8_LDA(At, 1, 1); PG8_STAGE(PG8_SB(1, 0), b3, voffB); PG8_STAGE(PG8_SB(1, 1), b3 + hstep, voffB); PG8_STAGE(PG8_SA(1, 0), a3, voffA);
;             PG8_WAIT_V(8); PG8_WAIT_L(0); PG8_BAR; PG8_MMA(1, 0, At, B0); PG8_MMA(1, 1, At, B1); PG8_BAR; PG8_SCHED;
	s_add_i32 s26, s47, s2
	v_lshl_add_u64 v[158:159], v[158:159], 0, s[42:43]
	s_mov_b32 m0, s26
	ds_read_b128 v[178:181], v141 offset:49152
	ds_read_b128 v[182:185], v141 offset:50176
	ds_read_b128 v[186:189], v141 offset:51200
	ds_read_b128 v[190:193], v141 offset:52224
	ds_read_b128 v[196:199], v141 offset:53248
	ds_read_b128 v[200:203], v141 offset:54272
	ds_read_b128 v[204:207], v141 offset:55296
	ds_read_b128 v[208:211], v141 offset:56320
	global_load_lds_dwordx4 v[158:159], off
	s_add_i32 m0, s26, 0x2000
	s_add_u32 s24, s24, 0x40080
	v_lshl_add_u64 v[158:159], v[212:213], 0, s[42:43]
	s_addc_u32 s25, s25, 0
	s_add_i32 s26, s64, s2
	global_load_lds_dwordx4 v[158:159], off
	v_lshl_add_u64 v[158:159], s[24:25], 0, v[160:161]
	s_mov_b32 m0, s26
	s_nop 0
	global_load_lds_dwordx4 v[158:159], off
	v_lshl_add_u64 v[158:159], s[24:25], 0, v[128:129]
	s_add_i32 m0, s26, 0x2000
	s_nop 0
	global_load_lds_dwordx4 v[158:159], off
	v_lshl_add_u64 v[158:159], v[214:215], 0, s[42:43]
	s_mov_b32 m0, s33
	s_nop 0
	global_load_lds_dwordx4 v[158:159], off
	v_lshl_add_u64 v[158:159], v[216:217], 0, s[42:43]
	s_mov_b32 m0, s34
	s_nop 0
	global_load_lds_dwordx4 v[158:159], off
	s_waitcnt vmcnt(8)
	s_waitcnt lgkmcnt(0)
	s_barrier
	s_setprio 1
	v_mfma_f32_16x16x32_bf16 v[60:63], v[142:145], v[178:181], v[60:63]
	v_mfma_f32_16x16x32_bf16 v[56:59], v[150:153], v[178:181], v[56:59]
	v_mfma_f32_16x16x32_bf16 v[52:55], v[142:145], v[186:189], v[52:55]
	v_mfma_f32_16x16x32_bf16 v[48:51], v[150:153], v[186:189], v[48:51]
	v_mfma_f32_16x16x32_bf16 v[36:39], v[142:145], v[196:199], v[36:39]
	v_mfma_f32_16x16x32_bf16 v[32:35], v[150:153], v[196:199], v[32:35]
	v_mfma_f32_16x16x32_bf16 v[20:23], v[142:145], v[204:207], v[20:23]
	v_mfma_f32_16x16x32_bf16 v[16:19], v[150:153], v[204:207], v[16:19]
	v_mfma_f32_16x16x32_bf16 v[60:63], v[146:149], v[182:185], v[60:63]
	v_mfma_f32_16x16x32_bf16 v[56:59], v[154:157], v[182:185], v[56:59]
	v_mfma_f32_16x16x32_bf16 v[52:55], v[146:149], v[190:193], v[52:55]
	v_mfma_f32_16x16x32_bf16 v[48:51], v[154:157], v[190:193], v[48:51]
	v_mfma_f32_16x16x32_bf16 v[36:39], v[146:149], v[200:203], v[36:39]
	v_mfma_f32_16x16x32_bf16 v[32:35], v[154:157], v[200:203], v[32:35]
	v_mfma_f32_16x16x32_bf16 v[20:23], v[146:149], v[208:211], v[20:23]
	v_mfma_f32_16x16x32_bf16 v[16:19], v[154:157], v[208:211], v[16:19]
	v_mfma_f32_16x16x32_bf16 v[44:47], v[162:165], v[178:181], v[44:47]
	v_mfma_f32_16x16x32_bf16 v[40:43], v[170:173], v[178:181], v[40:43]
	v_mfma_f32_16x16x32_bf16 v[28:31], v[162:165], v[186:189], v[28:31]
	v_mfma_f32_16x16x32_bf16 v[24:27], v[170:173], v[186:189], v[24:27]
	v_mfma_f32_16x16x32_bf16 v[12:15], v[162:165], v[196:199], v[12:15]
	v_mfma_f32_16x16x32_bf16 v[8:11], v[170:173], v[196:199], v[8:11]
	v_mfma_f32_16x16x32_bf16 v[4:7], v[162:165], v[204:207], v[4:7]
	v_mfma_f32_16x16x32_bf16 v[0:3], v[170:173], v[204:207], v[0:3]
	v_mfma_f32_16x16x32_bf16 v[44:47], v[166:169], v[182:185], v[44:47]
	v_mfma_f32_16x16x32_bf16 v[40:43], v[174:177], v[182:185], v[40:43]
	v_mfma_f32_16x16x32_bf16 v[28:31], v[166:169], v[190:193], v[28:31]
	v_mfma_f32_16x16x32_bf16 v[24:27], v[174:177], v[190:193], v[24:27]
	v_mfma_f32_16x16x32_bf16 v[12:15], v[166:169], v[200:203], v[12:15]
	v_mfma_f32_16x16x32_bf16 v[8:11], v[174:177], v[200:203], v[8:11]
	v_mfma_f32_16x16x32_bf16 v[4:7], v[166:169], v[208:211], v[4:7]
	v_mfma_f32_16x16x32_bf16 v[0:3], v[174:177], v[208:211], v[0:3]
	s_setprio 0
	s_barrier
	s_add_i32 s46, s46, 2
	s_add_u32 s22, s22, 0x100
	s_addc_u32 s23, s23, 0
	s_add_u32 s44, s44, 0x100
	s_addc_u32 s45, s45, 0
	s_cmp_gt_u32 s46, 13
	s_cbranch_scc0 .LBB0_613
	s_and_b64 vcc, exec, s[10:11]
	s_cbranch_vccz .LBB0_616
	s_barrier

; __device__ __forceinline__ void ln_rows(const Params& p, const bf16_t* __restrict__ O, const float* gmod, const float* lng, const float* lnb, const float* nmod  , ...
;     float* X = (float*)(p.ws + WS_X); bf16_t* U = (bf16_t*)((unsigned char*)p.out + DO_U);
;     for (int row0 = row_first; row0 < row_end; row0 += 2 * row_step) {
;         f32x4 xv[2][4]; u32x2 ow[2][4]; int rows[2]; bool ok[2];
; #pragma unroll
;         for (int r = 0; r < 2; ++r) { const int rr = row0 + r * row_step; ok[r] = rr < row_end; rows[r] = ok[r] ? rr : row0;
; #pragma unroll
;             for (int j = 0; j < 4; ++j) { const int col = 4 * lane + 256 * j; const float* xs = xin_lat ? (rows[r] < MLAT ? xin_lat + (size_t)rows[r] * DM : xin_ctx + (size_t)(rows[r] - MLAT) * DM) : X + (size_t)rows[r] * DM; xv[r][j] = *(const f32x4*)(xs + col); ow[r][j] = *(const u32x2*)(O + (size_t)rows[r] * DM + col); } }
; __device__ __forceinline__ void ln_ctx_phase(const Params& p, int l, bool last, int which, const bf16_t* A, const bf16_t* Bt, int K, bf16_t* O, const float* gmod, const float* lng, const float* lnb, ...
;     int tid_ = threadIdx.x; asm volatile("" : "+v"(tid_));
;     const int lane = tid_ & 63, wave = tid_ >> 6;
;     if (last) { ln_rows(p, O, gmod, lng, lnb, nmod, outp, lane, blockIdx.x * 8 + wave, gridDim.x * 8, MLAT, xin_lat, xin_ctx); return; }
;     if (blockIdx.x < 32) {
.LBB0_672:
	s_or_b64 exec, exec, s[0:1]
	s_mul_i32 s64, s78, 0xd800
	s_lshl_b64 s[0:1], s[64:65], 2
	v_readlane_b32 s4, v252, 18
	v_readlane_b32 s5, v252, 19
	s_add_u32 s38, s4, s0
	s_addc_u32 s39, s5, s1
	s_add_u32 s20, s38, 0x2000
	s_addc_u32 s21, s39, 0
	s_lshl_b32 s64, s78, 10
	s_lshl_b64 s[90:91], s[64:65], 2
	s_add_u32 s22, s48, s90
	s_addc_u32 s23, s49, s91
	s_add_u32 s24, s50, s90
	s_addc_u32 s25, s51, s91
	v_readlane_b32 s4, v255, 28
	s_add_u32 s66, s38, 0x3000
	v_mov_b32_e32 v140, v218
	v_readlane_b32 s5, v255, 29
	v_readlane_b32 s48, v255, 14
	v_readlane_b32 s50, v255, 16
	s_waitcnt lgkmcnt(0)
	s_barrier
	s_addc_u32 s67, s39, 0
	s_mov_b64 s[0:1], -1
	v_and_b32_e32 v138, 63, v140
	v_ashrrev_i32_e32 v139, 6, v140
	s_and_b64 vcc, exec, s[4:5]
	v_readlane_b32 s49, v255, 15
	v_readlane_b32 s51, v255, 17
	s_cbranch_vccz .LBB0_705
	v_readlane_b32 s4, v252, 2
	s_cmp_eq_u32 s78, 0
	v_readlane_b32 s5, v252, 3
	s_cselect_b32 s27, s5, 0
	s_cselect_b32 s26, s4, 0
	v_readlane_b32 s4, v253, 57
	v_readlane_b32 s8, v252, 6
	v_readlane_b32 s9, v252, 7
	v_readlane_b32 s5, v253, 58
	s_cselect_b32 s29, s9, 0
	s_cselect_b32 s28, s8, 0
	s_and_b64 vcc, exec, s[4:5]
	v_readlane_b32 s6, v252, 4
	v_readlane_b32 s7, v252, 5
	v_readlane_b32 s10, v252, 8
	v_readlane_b32 s11, v252, 9
	v_readlane_b32 s12, v252, 10
	v_readlane_b32 s13, v252, 11
	v_readlane_b32 s14, v252, 12
	v_readlane_b32 s15, v252, 13
	v_readlane_b32 s16, v252, 14
	v_readlane_b32 s17, v252, 15
	v_readlane_b32 s18, v252, 16
	v_readlane_b32 s19, v252, 17
	s_cbranch_vccz .LBB0_682
	v_readlane_b32 s0, v253, 59
	s_nop 1
	v_add_u32_e32 v16, s0, v139
	v_cmp_gt_i32_e32 vcc, s95, v16
	s_and_saveexec_b64 s[30:31], vcc
	s_cbranch_execz .LBB0_681
	v_and_b32_e32 v0, 64, v224
	v_add_u32_e32 v0, 64, v0
	v_xor_b32_e32 v1, 1, v224
	v_cmp_lt_i32_e32 vcc, v1, v0
	s_cmp_eq_u64 s[26:27], 0
	s_cselect_b64 s[8:9], -1, 0
	v_cndmask_b32_e32 v1, v224, v1, vcc
	v_lshlrev_b32_e32 v19, 2, v1
	v_xor_b32_e32 v1, 2, v224
	v_cmp_lt_i32_e32 vcc, v1, v0
	s_and_b64 s[0:1], s[8:9], exec
	v_readlane_b32 s0, v253, 60
	v_cndmask_b32_e32 v1, v224, v1, vcc
	v_lshlrev_b32_e32 v21, 2, v1
	v_xor_b32_e32 v1, 4, v224
	v_cmp_lt_i32_e32 vcc, v1, v0
	v_ashrrev_i32_e32 v17, 31, v16
	v_lshlrev_b32_e32 v18, 2, v138
	v_cndmask_b32_e32 v1, v224, v1, vcc
	v_lshlrev_b32_e32 v23, 2, v1
	v_xor_b32_e32 v1, 8, v224
	v_cmp_lt_i32_e32 vcc, v1, v0
	v_lshlrev_b32_e32 v160, 4, v138
	v_readlane_b32 s1, v253, 61
	v_cndmask_b32_e32 v1, v224, v1, vcc
	v_lshlrev_b32_e32 v25, 2, v1
	v_xor_b32_e32 v1, 16, v224
	v_cmp_lt_i32_e32 vcc, v1, v0
	v_lshlrev_b64 v[38:39], 11, v[16:17]
	v_lshlrev_b64 v[40:41], 12, v[16:17]
	v_cndmask_b32_e32 v1, v224, v1, vcc
	v_lshlrev_b32_e32 v64, 2, v1
	v_xor_b32_e32 v1, 32, v224
	v_cmp_lt_i32_e32 vcc, v1, v0
	s_mov_b64 s[34:35], 0
	v_or_b32_e32 v20, 0x100, v18
	v_cndmask_b32_e32 v0, v224, v1, vcc
	v_lshlrev_b32_e32 v65, 2, v0
	v_lshlrev_b32_e32 v0, 3, v138
	v_mov_b32_e32 v1, v161
	v_or_b32_e32 v22, 0x200, v18
	v_or_b32_e32 v24, 0x300, v18
	v_lshl_add_u64 v[26:27], s[22:23], 0, v[160:161]
	v_lshl_add_u64 v[28:29], s[24:25], 0, v[160:161]
	s_cselect_b32 s37, s1, s27
	s_cselect_b32 s36, s0, s26
	v_lshl_add_u64 v[30:31], s[54:55], 0, v[0:1]
	v_lshl_add_u64 v[32:33], s[20:21], 0, v[160:161]
	v_lshl_add_u64 v[34:35], s[0:1], 0, v[160:161]
	v_lshl_add_u64 v[36:37], s[60:61], 0, v[0:1]
	v_lshl_or_b32 v38, v138, 3, v38
	v_lshl_or_b32 v40, v138, 4, v40
	s_branch .LBB0_677

; __device__ __forceinline__ float bflo(unsigned w) { return __uint_as_float(w << 16); }
; __device__ __forceinline__ float bfhi(unsigned w) { return __uint_as_float(w & 0xffff0000u); }
; __device__ __forceinline__ void ln_rows(const Params& p, const bf16_t* __restrict__ O, const float* gmod, const float* lng, const float* lnb, const float* nmod  , ...
;     ...
;         for (int r = 0; r < 2; ++r) { const int rr = row0 + r * row_step; ok[r] = rr < row_end; rows[r] = ok[r] ? rr : row0;
; #pragma unroll
;             for (int j = 0; j < 4; ++j) { const int col = 4 * lane + 256 * j; const float* xs = xin_lat ? (rows[r] < MLAT ? xin_lat + (size_t)rows[r] * DM : xin_ctx + (size_t)(rows[r] - MLAT) * DM) : X + (size_t)rows[r] * DM; xv[r][j] = *(const f32x4*)(xs + col); ow[r][j] = *(const u32x2*)(O + (size_t)rows[r] * DM + col); } }
; #pragma unroll
;         for (int r = 0; r < 2; ++r) {
;             const int row = rows[r]; const int bi = row < MLAT ? row / SEQ : 8;
;             const float* g = gmod + (size_t)bi * MODW;
;             f32x4 v[4]; float s = 0.f;
; #pragma unroll
;             for (int j = 0; j < 4; ++j) { const int col = 4 * lane + 256 * j; const f32x4 gv = *(const f32x4*)(g + col); f32x4 ov; ov[0] = bflo(ow[r][j].x); ov[1] = bfhi(ow[r][j].x); ov[2] = bflo(ow[r][j].y); ov[3] = bfhi(ow[r][j].y);
;                 v[j] = xv[r][j] * ALPHA + gv * ov; s += (v[j][0] + v[j][1]) + (v[j][2] + v[j][3]); }
;             const float mean = wave_sum(s) * (1.0f / DM); float s2 = 0.f;
; #pragma unroll
;             for (int j = 0; j < 4; ++j) { v[j] = v[j] - mean; s2 += (v[j][0] * v[j][0] + v[j][1] * v[j][1]) + (v[j][2] * v[j][2] + v[j][3] * v[j][3]); }
;             const float rstd = 1.0f / sqrtf(wave_sum(s2) * (1.0f / DM) + LN_EPS);
.LBB0_677:
	v_lshl_add_u64 v[0:1], s[62:63], 0, v[38:39]
	v_ashrrev_i32_e32 v2, 31, v16
	v_add_co_u32_e32 v0, vcc, 0xa800000, v0
	v_lshrrev_b32_e32 v2, 20, v2
	s_nop 0
	v_addc_co_u32_e32 v1, vcc, 0, v1, vcc
	v_add_u32_e32 v2, v16, v2
	s_waitcnt lgkmcnt(0)
	global_load_dwordx2 v[14:15], v[0:1], off
	global_load_dwordx2 v[46:47], v[0:1], off offset:512
	global_load_dwordx2 v[56:57], v[0:1], off offset:1024
	global_load_dwordx2 v[58:59], v[0:1], off offset:1536
	v_ashrrev_i32_e32 v0, 12, v2
	v_mul_hi_i32_i24_e32 v1, 0x1800, v0
	v_mul_i32_i24_e32 v0, 0x1800, v0
	v_lshlrev_b64 v[0:1], 2, v[0:1]
	v_lshl_add_u64 v[42:43], v[32:33], 0, v[0:1]
	global_load_dwordx4 v[2:5], v[42:43], off
	global_load_dwordx4 v[6:9], v[42:43], off offset:1024
	global_load_dwordx4 v[10:13], v[42:43], off offset:2048
	s_nop 0
	global_load_dwordx4 v[42:45], v[42:43], off offset:3072
	v_lshl_add_u64 v[66:67], s[36:37], 0, v[40:41]
	global_load_dwordx4 v[48:51], v[66:67], off
	global_load_dwordx4 v[52:55], v[66:67], off offset:1024
	global_load_dwordx4 v[60:63], v[66:67], off offset:2048
	s_nop 0
	global_load_dwordx4 v[66:69], v[66:67], off offset:3072
	v_readlane_b32 s4, v253, 60
	v_readlane_b32 s5, v253, 61
	s_brev_b32 s2, 64
	v_lshl_add_u64 v[84:85], s[60:61], 0, v[38:39]
	s_waitcnt vmcnt(11)
	v_lshlrev_b32_e32 v70, 16, v14
	v_and_b32_e32 v71, 0xffff0000, v14
	v_lshlrev_b32_e32 v14, 16, v15
	v_and_b32_e32 v15, 0xffff0000, v15
	s_waitcnt vmcnt(10)
	v_lshlrev_b32_e32 v72, 16, v46
	v_and_b32_e32 v73, 0xffff0000, v46
	v_lshlrev_b32_e32 v46, 16, v47
	v_and_b32_e32 v47, 0xffff0000, v47
	s_waitcnt vmcnt(9)
	v_lshlrev_b32_e32 v74, 16, v56
	v_and_b32_e32 v75, 0xffff0000, v56
	v_lshlrev_b32_e32 v56, 16, v57
	v_and_b32_e32 v57, 0xffff0000, v57
	s_waitcnt vmcnt(8)
	v_lshlrev_b32_e32 v76, 16, v58
	v_and_b32_e32 v77, 0xffff0000, v58
	v_lshlrev_b32_e32 v58, 16, v59
	v_and_b32_e32 v59, 0xffff0000, v59
	s_waitcnt vmcnt(7)
	v_pk_mul_f32 v[4:5], v[4:5], v[14:15]
	v_pk_mul_f32 v[2:3], v[2:3], v[70:71]
	s_waitcnt vmcnt(6)
	v_pk_mul_f32 v[8:9], v[8:9], v[46:47]
	v_pk_mul_f32 v[6:7], v[6:7], v[72:73]
	s_waitcnt vmcnt(5)
	v_pk_mul_f32 v[12:13], v[12:13], v[56:57]
	s_waitcnt vmcnt(4)
	v_pk_mul_f32 v[14:15], v[44:45], v[58:59]
	s_waitcnt vmcnt(3)
	v_pk_fma_f32 v[46:47], v[50:51], s[82:83], v[4:5] op_sel_hi:[1,0,1]
	v_pk_fma_f32 v[58:59], v[48:49], s[82:83], v[2:3] op_sel_hi:[1,0,1]
	s_waitcnt vmcnt(2)
	v_pk_fma_f32 v[56:57], v[54:55], s[82:83], v[8:9] op_sel_hi:[1,0,1]
	v_pk_fma_f32 v[44:45], v[52:53], s[82:83], v[6:7] op_sel_hi:[1,0,1]
	v_pk_mov_b32 v[2:3], v[58:59], v[46:47] op_sel:[1,0]
	v_mov_b32_e32 v4, v58
	v_mov_b32_e32 v5, v47
	v_pk_mov_b32 v[6:7], v[44:45], v[56:57] op_sel:[1,0]
	v_mov_b32_e32 v8, v44
	v_mov_b32_e32 v9, v57
	v_pk_mul_f32 v[10:11], v[10:11], v[74:75]
	v_pk_mul_f32 v[70:71], v[42:43], v[76:77]
	v_pk_add_f32 v[2:3], v[2:3], v[4:5]
	v_pk_add_f32 v[4:5], v[6:7], v[8:9]
	s_waitcnt vmcnt(1)
	v_pk_fma_f32 v[54:55], v[62:63], s[82:83], v[12:13] op_sel_hi:[1,0,1]
	v_pk_fma_f32 v[42:43], v[60:61], s[82:83], v[10:11] op_sel_hi:[1,0,1]
	s_waitcnt vmcnt(0)
	v_pk_fma_f32 v[52:53], v[68:69], s[82:83], v[14:15] op_sel_hi:[1,0,1]
	v_pk_fma_f32 v[50:51], v[66:67], s[82:83], v[70:71] op_sel_hi:[1,0,1]
	v_add_f32_e32 v8, v2, v3
	v_pk_add_f32 v[2:3], v[4:5], v[4:5] op_sel:[0,1] op_sel_hi:[1,0]
	v_add_f32_e32 v10, v42, v43
	v_add_f32_e32 v12, v54, v55
	v_mov_b32_e32 v15, v50
	v_mov_b32_e32 v11, v52
	v_mov_b32_e32 v13, v53
	v_add_f32_e32 v14, 0, v8
	v_mov_b32_e32 v3, v51
	v_pk_add_f32 v[6:7], v[10:11], v[12:13]
	v_pk_add_f32 v[2:3], v[14:15], v[2:3]
	global_load_dwordx4 v[66:69], v[26:27], off
	global_load_dwordx4 v[70:73], v[28:29], off
	v_pk_add_f32 v[2:3], v[2:3], v[6:7]
	v_lshl_add_u64 v[74:75], s[66:67], 0, v[0:1]
	v_add_f32_e32 v2, v2, v3
	ds_bpermute_b32 v3, v19, v2
	v_lshl_add_u64 v[62:63], s[62:63], 0, v[40:41]
	v_lshl_add_u64 v[78:79], v[74:75], 0, s[72:73]
	s_waitcnt lgkmcnt(0)
	v_add_f32_e32 v2, v2, v3
	ds_bpermute_b32 v3, v21, v2
	s_waitcnt lgkmcnt(0)
	v_add_f32_e32 v2, v2, v3
	ds_bpermute_b32 v3, v23, v2
	s_waitcnt lgkmcnt(0)
	v_add_f32_e32 v2, v2, v3
	ds_bpermute_b32 v3, v25, v2
	s_waitcnt lgkmcnt(0)
	v_add_f32_e32 v2, v2, v3
	ds_bpermute_b32 v3, v64, v2
	s_waitcnt lgkmcnt(0)
	v_add_f32_e32 v2, v2, v3
	ds_bpermute_b32 v3, v65, v2
	s_waitcnt lgkmcnt(0)
	v_add_f32_e32 v2, v2, v3
	v_fmamk_f32 v59, v2, 0xba800000, v59
	v_fmac_f32_e32 v58, 0xba800000, v2
	v_fmamk_f32 v47, v2, 0xba800000, v47
	v_fmac_f32_e32 v46, 0xba800000, v2
	v_fmamk_f32 v45, v2, 0xba800000, v45
	v_fmac_f32_e32 v44, 0xba800000, v2
	v_fmamk_f32 v57, v2, 0xba800000, v57
	v_fmac_f32_e32 v56, 0xba800000, v2
	v_fmamk_f32 v43, v2, 0xba800000, v43
	v_fmac_f32_e32 v42, 0xba800000, v2
	v_fmamk_f32 v55, v2, 0xba800000, v55
	v_fmac_f32_e32 v54, 0xba800000, v2
	v_fmamk_f32 v53, v2, 0xba800000, v53
	v_fmac_f32_e32 v52, 0xba800000, v2
	v_fmamk_f32 v51, v2, 0xba800000, v51
	v_fmac_f32_e32 v50, 0xba800000, v2
	v_pk_mul_f32 v[2:3], v[46:47], v[46:47]
	v_pk_mul_f32 v[4:5], v[58:59], v[58:59]
	v_pk_mul_f32 v[6:7], v[56:57], v[56:57]
	v_pk_mul_f32 v[8:9], v[44:45], v[44:45]
	v_pk_mov_b32 v[14:15], v[4:5], v[2:3] op_sel:[1,0]
	v_mov_b32_e32 v5, v3
	v_pk_mov_b32 v[2:3], v[8:9], v[6:7] op_sel:[1,0]
	v_mov_b32_e32 v9, v7
	v_mul_f32_e32 v10, v42, v42
	v_mul_f32_e32 v12, v54, v54
	v_pk_add_f32 v[4:5], v[14:15], v[4:5]
	v_pk_add_f32 v[2:3], v[2:3], v[8:9]
	v_pk_fma_f32 v[6:7], v[42:43], v[42:43], v[10:11] op_sel_hi:[1,1,0]
	v_pk_fma_f32 v[10:11], v[54:55], v[54:55], v[12:13] op_sel_hi:[1,1,0]
	v_pk_add_f32 v[4:5], v[4:5], v[4:5] op_sel_hi:[0,1]
	v_pk_add_f32 v[2:3], v[2:3], v[2:3] op_sel_hi:[0,1]
	v_mul_f32_e32 v6, v50, v50
	v_mul_f32_e32 v10, v51, v51
	v_mul_f32_e32 v4, v52, v52
	v_mul_f32_e32 v2, v53, v53
	v_pk_add_f32 v[6:7], v[6:7], v[10:11]
	v_pk_add_f32 v[2:3], v[4:5], v[2:3]
	v_add_u32_e32 v4, s97, v16
	v_pk_add_f32 v[2:3], v[6:7], v[2:3]
	v_add_u32_e32 v4, 0xffffff00, v4
	v_add_f32_e32 v2, v2, v3
	ds_bpermute_b32 v3, v19, v2
	v_cmp_gt_i32_e64 s[0:1], s95, v4
	s_waitcnt lgkmcnt(0)
; __device__ __forceinline__ unsigned pk2(float lo, float hi) { f32x2_t v = {lo, hi}; bf16x2_t b = __builtin_convertvector(v, bf16x2_t); return __builtin_bit_cast(unsigned, b); }
; __device__ __forceinline__ void ln_rows(const Params& p, const bf16_t* __restrict__ O, const float* gmod, const float* lng, const float* lnb, const float* nmod  , ...
;     ...
;             const float mean = wave_sum(s) * (1.0f / DM); float s2 = 0.f;
; #pragma unroll
;             for (int j = 0; j < 4; ++j) { v[j] = v[j] - mean; s2 += (v[j][0] * v[j][0] + v[j][1] * v[j][1]) + (v[j][2] * v[j][2] + v[j][3] * v[j][3]); }
;             const float rstd = 1.0f / sqrtf(wave_sum(s2) * (1.0f / DM) + LN_EPS);
;             if (ok[r]) {
; #pragma unroll
;                 for (int j = 0; j < 4; ++j) { const int col = 4 * lane + 256 * j; const f32x4 y = v[j] * rstd * *(const f32x4*)(lng + col) + *(const f32x4*)(lnb + col);
;                     if (outp) { *(f32x4*)(outp + (size_t)row * DM + col) = y; }
;                     else { *(f32x4*)(X + (size_t)row * DM + col) = y;
;                         const float* nm = nmod + (size_t)bi * MODW; const f32x4 u = y * (*(const f32x4*)(nm + 1024 + col) + 1.0f) + *(const f32x4*)(nm + col);
;                         u32x2 w; w.x = pk2(u[0], u[1]); w.y = pk2(u[2], u[3]); *(u32x2*)(U + (size_t)row * DM + col) = w; } }
	v_add_f32_e32 v2, v2, v3
	ds_bpermute_b32 v3, v21, v2
	v_cndmask_b32_e64 v60, v16, v4, s[0:1]
	v_ashrrev_i32_e32 v61, 31, v60
	v_add_u32_e32 v160, 0xffff8000, v60
	v_lshlrev_b64 v[48:49], 12, v[60:61]
	s_waitcnt lgkmcnt(0)
	v_add_f32_e32 v5, v2, v3
	ds_bpermute_b32 v6, v23, v5
	v_lshlrev_b64 v[2:3], 12, v[160:161]
	v_lshl_add_u64 v[2:3], s[28:29], 0, v[2:3]
	v_cmp_gt_i32_e64 s[10:11], s95, v60
	v_lshlrev_b32_e32 v160, 2, v18
	s_waitcnt lgkmcnt(0)
	v_add_f32_e32 v6, v5, v6
	ds_bpermute_b32 v7, v25, v6
	v_lshl_add_u64 v[4:5], s[26:27], 0, v[48:49]
	v_cndmask_b32_e64 v2, v2, v4, s[10:11]
	v_cndmask_b32_e64 v3, v3, v5, s[10:11]
	s_waitcnt lgkmcnt(0)
	v_add_f32_e32 v8, v6, v7
	ds_bpermute_b32 v9, v64, v8
	v_lshl_add_u64 v[6:7], s[4:5], 0, v[48:49]
	v_cndmask_b32_e64 v0, v2, v6, s[8:9]
	v_cndmask_b32_e64 v1, v3, v7, s[8:9]
	v_lshl_add_u64 v[0:1], v[0:1], 0, v[160:161]
	s_waitcnt lgkmcnt(0)
	v_add_f32_e32 v4, v8, v9
	ds_bpermute_b32 v5, v65, v4
	global_load_dwordx4 v[12:15], v[0:1], off
	global_load_dwordx4 v[8:11], v[0:1], off offset:1024
	s_waitcnt lgkmcnt(0)
	v_add_f32_e32 v2, v4, v5
	v_fmamk_f32 v2, v2, 0x3a800000, v219
	v_mul_f32_e32 v3, 0x4f800000, v2
	v_cmp_gt_f32_e32 vcc, s86, v2
	s_nop 1
	v_cndmask_b32_e32 v2, v2, v3, vcc
	v_sqrt_f32_e32 v3, v2
	s_nop 0
	v_add_u32_e32 v4, -1, v3
	v_add_u32_e32 v5, 1, v3
	v_fma_f32 v6, -v4, v3, v2
	v_fma_f32 v7, -v5, v3, v2
	v_cmp_ge_f32_e64 s[12:13], 0, v6
	s_nop 1
	v_cndmask_b32_e64 v3, v3, v4, s[12:13]
	v_cmp_lt_f32_e64 s[12:13], 0, v7
	s_nop 1
	v_cndmask_b32_e64 v3, v3, v5, s[12:13]
	v_mul_f32_e32 v4, 0x37800000, v3
	v_cndmask_b32_e32 v3, v3, v4, vcc
	v_cmp_class_f32_e32 vcc, v2, v222
	s_nop 1
	v_cndmask_b32_e32 v17, v3, v2, vcc
	v_div_scale_f32 v76, s[12:13], v17, v17, 1.0
	v_rcp_f32_e32 v77, v76
	v_div_scale_f32 v80, vcc, 1.0, v17, 1.0
	global_load_dwordx4 v[4:7], v[0:1], off offset:2048
	s_nop 0
	global_load_dwordx4 v[0:3], v[0:1], off offset:3072
	v_fma_f32 v81, -v76, v77, 1.0
	v_fmac_f32_e32 v77, v81, v77
	v_mul_f32_e32 v81, v80, v77
	v_fma_f32 v82, -v76, v81, v80
	v_fmac_f32_e32 v81, v82, v77
	v_fma_f32 v76, -v76, v81, v80
	v_div_fmas_f32 v76, v76, v77, v81
	v_div_fixup_f32 v80, v76, v17, 1.0
	v_pk_mul_f32 v[58:59], v[58:59], v[80:81] op_sel_hi:[1,0]
	v_pk_mul_f32 v[46:47], v[46:47], v[80:81] op_sel_hi:[1,0]
	v_add_co_u32_e32 v62, vcc, s2, v62
	s_waitcnt vmcnt(4)
	v_pk_fma_f32 v[68:69], v[68:69], v[46:47], v[72:73]
	v_pk_fma_f32 v[66:67], v[66:67], v[58:59], v[70:71]
	v_addc_co_u32_e32 v63, vcc, 0, v63, vcc
	global_store_dwordx4 v[62:63], v[66:69], off
	v_lshl_add_u64 v[46:47], v[78:79], 0, v[160:161]
	global_load_dwordx4 v[70:73], v[46:47], off
	v_lshl_add_u64 v[82:83], v[74:75], 0, v[160:161]
	global_load_dwordx4 v[74:77], v[82:83], off
	v_pk_mul_f32 v[44:45], v[44:45], v[80:81] op_sel_hi:[1,0]
	v_pk_mul_f32 v[42:43], v[42:43], v[80:81] op_sel_hi:[1,0]
	v_pk_mul_f32 v[52:53], v[52:53], v[80:81] op_sel_hi:[1,0]
	v_pk_mul_f32 v[50:51], v[50:51], v[80:81] op_sel_hi:[1,0]
	s_waitcnt vmcnt(1)
	v_pk_add_f32 v[46:47], v[72:73], 1.0 op_sel_hi:[1,0]
	v_pk_add_f32 v[58:59], v[70:71], 1.0 op_sel_hi:[1,0]
	s_waitcnt vmcnt(0)
	v_pk_fma_f32 v[46:47], v[46:47], v[68:69], v[76:77]
	v_pk_fma_f32 v[58:59], v[58:59], v[66:67], v[74:75]
	s_nop 0
	v_cvt_pk_bf16_f32 v58, v58, v59
	v_cvt_pk_bf16_f32 v59, v46, v47
	global_store_dwordx2 v[84:85], v[58:59], off
	global_load_dwordx4 v[66:69], v[26:27], off offset:1024
	global_load_dwordx4 v[70:73], v[28:29], off offset:1024
	v_pk_mul_f32 v[58:59], v[56:57], v[80:81] op_sel_hi:[1,0]
	v_lshlrev_b32_e32 v46, 2, v20
	v_mov_b32_e32 v47, v161
	v_lshl_add_u64 v[74:75], v[78:79], 0, v[46:47]
	s_waitcnt vmcnt(0)
	v_pk_fma_f32 v[56:57], v[66:67], v[44:45], v[70:71]
	v_pk_fma_f32 v[58:59], v[68:69], v[58:59], v[72:73]
	global_store_dwordx4 v[62:63], v[56:59], off offset:1024
	global_load_dwordx4 v[66:69], v[74:75], off
	global_load_dwordx4 v[70:73], v[82:83], off offset:1024
	s_waitcnt vmcnt(1)
	v_pk_add_f32 v[44:45], v[68:69], 1.0 op_sel_hi:[1,0]
	v_pk_add_f32 v[66:67], v[66:67], 1.0 op_sel_hi:[1,0]
	s_waitcnt vmcnt(0)
	v_pk_fma_f32 v[44:45], v[44:45], v[58:59], v[72:73]
	v_pk_fma_f32 v[56:57], v[66:67], v[56:57], v[70:71]
	v_pk_mul_f32 v[72:73], v[54:55], v[80:81] op_sel_hi:[1,0]
	v_cvt_pk_bf16_f32 v56, v56, v57
	v_cvt_pk_bf16_f32 v57, v44, v45
	global_store_dwordx2 v[84:85], v[56:57], off offset:512
	global_load_dwordx4 v[56:59], v[26:27], off offset:2048
	s_nop 0
	global_load_dwordx4 v[66:69], v[28:29], off offset:2048
	v_lshlrev_b32_e32 v44, 2, v22
	v_mov_b32_e32 v45, v161
	v_lshl_add_u64 v[70:71], v[78:79], 0, v[44:45]
	s_waitcnt vmcnt(0)
	v_pk_fma_f32 v[54:55], v[56:57], v[42:43], v[66:67]
	v_pk_fma_f32 v[56:57], v[58:59], v[72:73], v[68:69]
	global_store_dwordx4 v[62:63], v[54:57], off offset:2048
	global_load_dwordx4 v[66:69], v[70:71], off
	s_nop 0
	global_load_dwordx4 v[70:73], v[82:83], off offset:2048
	s_waitcnt vmcnt(1)
	v_pk_add_f32 v[42:43], v[68:69], 1.0 op_sel_hi:[1,0]
	v_pk_add_f32 v[58:59], v[66:67], 1.0 op_sel_hi:[1,0]
	s_waitcnt vmcnt(0)
	v_pk_fma_f32 v[42:43], v[42:43], v[56:57], v[72:73]
	v_pk_fma_f32 v[54:55], v[58:59], v[54:55], v[70:71]
	s_nop 0
	v_cvt_pk_bf16_f32 v54, v54, v55
	v_cvt_pk_bf16_f32 v55, v42, v43
	global_store_dwordx2 v[84:85], v[54:55], off offset:1024
	global_load_dwordx4 v[54:57], v[26:27], off offset:3072
	s_nop 0
	global_load_dwordx4 v[66:69], v[28:29], off offset:3072
	v_lshlrev_b32_e32 v42, 2, v24
	v_mov_b32_e32 v43, v161
	v_lshl_add_u64 v[58:59], v[78:79], 0, v[42:43]
	s_waitcnt vmcnt(0)
; __device__ __forceinline__ float bflo(unsigned w) { return __uint_as_float(w << 16); }
; __device__ __forceinline__ float bfhi(unsigned w) { return __uint_as_float(w & 0xffff0000u); }
; __device__ __forceinline__ void ln_rows(const Params& p, const bf16_t* __restrict__ O, const float* gmod, const float* lng, const float* lnb, const float* nmod  , ...
;     ...
;         for (int r = 0; r < 2; ++r) {
;             const int row = rows[r]; const int bi = row < MLAT ? row / SEQ : 8;
;             const float* g = gmod + (size_t)bi * MODW;
;             f32x4 v[4]; float s = 0.f;
; #pragma unroll
;             for (int j = 0; j < 4; ++j) { const int col = 4 * lane + 256 * j; const f32x4 gv = *(const f32x4*)(g + col); f32x4 ov; ov[0] = bflo(ow[r][j].x); ov[1] = bfhi(ow[r][j].x); ov[2] = bflo(ow[r][j].y); ov[3] = bfhi(ow[r][j].y);
;                 v[j] = xv[r][j] * ALPHA + gv * ov; s += (v[j][0] + v[j][1]) + (v[j][2] + v[j][3]); }
;             const float mean = wave_sum(s) * (1.0f / DM); float s2 = 0.f;
; #pragma unroll
;             for (int j = 0; j < 4; ++j) { v[j] = v[j] - mean; s2 += (v[j][0] * v[j][0] + v[j][1] * v[j][1]) + (v[j][2] * v[j][2] + v[j][3] * v[j][3]); }
;             const float rstd = 1.0f / sqrtf(wave_sum(s2) * (1.0f / DM) + LN_EPS);
	v_pk_fma_f32 v[66:67], v[54:55], v[50:51], v[66:67]
	v_pk_fma_f32 v[68:69], v[56:57], v[52:53], v[68:69]
	v_lshlrev_b64 v[50:51], 11, v[60:61]
	global_store_dwordx4 v[62:63], v[66:69], off offset:3072
	v_lshl_add_u64 v[52:53], v[30:31], 0, v[50:51]
	global_load_dwordx4 v[70:73], v[58:59], off
	global_load_dwordx4 v[74:77], v[82:83], off offset:3072
	global_load_dwordx2 v[54:55], v[52:53], off
	s_nop 0
	global_load_dwordx2 v[58:59], v[52:53], off offset:512
	global_load_dwordx2 v[62:63], v[52:53], off offset:1024
	global_load_dwordx2 v[56:57], v[52:53], off offset:1536
	s_waitcnt vmcnt(5)
	v_pk_add_f32 v[52:53], v[72:73], 1.0 op_sel_hi:[1,0]
	v_pk_add_f32 v[70:71], v[70:71], 1.0 op_sel_hi:[1,0]
	s_waitcnt vmcnt(4)
	v_pk_fma_f32 v[52:53], v[52:53], v[68:69], v[76:77]
	v_pk_fma_f32 v[66:67], v[70:71], v[66:67], v[74:75]
	s_nop 0
	v_cvt_pk_bf16_f32 v66, v66, v67
	v_cvt_pk_bf16_f32 v67, v52, v53
	v_mov_b64_e32 v[52:53], 0xc000
	global_store_dwordx2 v[84:85], v[66:67], off offset:1536
	s_and_saveexec_b64 s[12:13], s[10:11]
	v_ashrrev_i32_e32 v17, 31, v60
	v_lshrrev_b32_e32 v17, 20, v17
	v_add_u32_e32 v17, v60, v17
	v_ashrrev_i32_e32 v17, 12, v17
	v_mul_hi_i32_i24_e32 v53, 0x1800, v17
	v_mul_i32_i24_e32 v52, 0x1800, v17
	s_or_b64 exec, exec, s[12:13]
	v_lshl_add_u64 v[60:61], v[52:53], 2, v[32:33]
	global_load_dwordx4 v[66:69], v[60:61], off
	s_waitcnt vmcnt(5)
	v_lshlrev_b32_e32 v70, 16, v54
	v_and_b32_e32 v71, 0xffff0000, v54
	v_lshlrev_b32_e32 v54, 16, v55
	v_and_b32_e32 v55, 0xffff0000, v55
	s_waitcnt vmcnt(0)
	v_pk_mul_f32 v[68:69], v[68:69], v[54:55]
	v_pk_mul_f32 v[54:55], v[66:67], v[70:71]
	v_lshlrev_b32_e32 v70, 16, v58
	v_pk_fma_f32 v[54:55], v[12:13], s[82:83], v[54:55] op_sel_hi:[1,0,1]
	v_pk_fma_f32 v[12:13], v[14:15], s[82:83], v[68:69] op_sel_hi:[1,0,1]
	v_mov_b32_e32 v66, v54
	v_pk_mov_b32 v[14:15], v[54:55], v[12:13] op_sel:[1,0]
	v_mov_b32_e32 v67, v13
	v_pk_add_f32 v[14:15], v[14:15], v[66:67]
	global_load_dwordx4 v[66:69], v[60:61], off offset:1024
	v_and_b32_e32 v71, 0xffff0000, v58
	v_lshlrev_b32_e32 v58, 16, v59
	v_and_b32_e32 v59, 0xffff0000, v59
	v_add_f32_e32 v14, v14, v15
	v_add_f32_e32 v14, 0, v14
	s_waitcnt vmcnt(0)
	v_pk_mul_f32 v[58:59], v[68:69], v[58:59]
	v_pk_mul_f32 v[66:67], v[66:67], v[70:71]
	v_pk_fma_f32 v[10:11], v[10:11], s[82:83], v[58:59] op_sel_hi:[1,0,1]
	v_pk_fma_f32 v[8:9], v[8:9], s[82:83], v[66:67] op_sel_hi:[1,0,1]
	v_mov_b32_e32 v67, v11
	v_pk_mov_b32 v[58:59], v[8:9], v[10:11] op_sel:[1,0]
	v_mov_b32_e32 v66, v8
	v_pk_add_f32 v[58:59], v[58:59], v[66:67]
	global_load_dwordx4 v[66:69], v[60:61], off offset:2048
	v_lshlrev_b32_e32 v70, 16, v62
	v_and_b32_e32 v71, 0xffff0000, v62
	v_lshlrev_b32_e32 v62, 16, v63
	v_and_b32_e32 v63, 0xffff0000, v63
	v_pk_add_f32 v[58:59], v[58:59], v[58:59] op_sel:[0,1] op_sel_hi:[1,0]
	s_waitcnt vmcnt(0)
	v_pk_mul_f32 v[62:63], v[68:69], v[62:63]
	s_nop 0
	v_pk_fma_f32 v[6:7], v[6:7], s[82:83], v[62:63] op_sel_hi:[1,0,1]
	global_load_dwordx4 v[60:63], v[60:61], off offset:3072
	v_pk_mul_f32 v[66:67], v[66:67], v[70:71]
	v_lshlrev_b32_e32 v70, 16, v56
	v_and_b32_e32 v71, 0xffff0000, v56
	v_lshlrev_b32_e32 v56, 16, v57
	v_and_b32_e32 v57, 0xffff0000, v57
	v_pk_fma_f32 v[4:5], v[4:5], s[82:83], v[66:67] op_sel_hi:[1,0,1]
	v_add_f32_e32 v68, v6, v7
	v_add_f32_e32 v66, v4, v5
	s_waitcnt vmcnt(0)
	v_pk_mul_f32 v[60:61], v[60:61], v[70:71]
	v_pk_mul_f32 v[56:57], v[62:63], v[56:57]
	v_pk_fma_f32 v[0:1], v[0:1], s[82:83], v[60:61] op_sel_hi:[1,0,1]
	v_pk_fma_f32 v[2:3], v[2:3], s[82:83], v[56:57] op_sel_hi:[1,0,1]
	v_mov_b32_e32 v15, v0
	v_mov_b32_e32 v59, v1
	v_mov_b32_e32 v67, v2
	v_mov_b32_e32 v69, v3
	v_pk_add_f32 v[14:15], v[14:15], v[58:59]
	v_pk_add_f32 v[56:57], v[66:67], v[68:69]
	s_nop 0
	v_pk_add_f32 v[14:15], v[14:15], v[56:57]
	s_nop 0
	v_add_f32_e32 v14, v14, v15
	ds_bpermute_b32 v15, v19, v14
	s_waitcnt lgkmcnt(0)
	v_add_f32_e32 v14, v14, v15
	ds_bpermute_b32 v15, v21, v14
	s_waitcnt lgkmcnt(0)
	v_add_f32_e32 v14, v14, v15
	ds_bpermute_b32 v15, v23, v14
	s_waitcnt lgkmcnt(0)
	v_add_f32_e32 v14, v14, v15
	ds_bpermute_b32 v15, v25, v14
	s_waitcnt lgkmcnt(0)
	v_add_f32_e32 v14, v14, v15
	ds_bpermute_b32 v15, v64, v14
	s_waitcnt lgkmcnt(0)
	v_add_f32_e32 v14, v14, v15
	ds_bpermute_b32 v15, v65, v14
	s_waitcnt lgkmcnt(0)
	v_add_f32_e32 v14, v14, v15
	v_fmamk_f32 v13, v14, 0xba800000, v13
	v_fmamk_f32 v55, v14, 0xba800000, v55
	v_fmac_f32_e32 v12, 0xba800000, v14
	v_fmac_f32_e32 v54, 0xba800000, v14
	v_mul_f32_e32 v15, v55, v55
	v_mul_f32_e32 v17, v13, v13
	v_fmac_f32_e32 v15, v54, v54
	v_fmac_f32_e32 v17, v12, v12
	v_fmamk_f32 v11, v14, 0xba800000, v11
	v_fmamk_f32 v9, v14, 0xba800000, v9
	v_add_f32_e32 v15, v15, v17
	v_fmac_f32_e32 v10, 0xba800000, v14
	v_fmac_f32_e32 v8, 0xba800000, v14
	v_mul_f32_e32 v17, v9, v9
	v_mul_f32_e32 v43, v11, v11
	v_fmac_f32_e32 v17, v8, v8
	v_fmac_f32_e32 v43, v10, v10
	v_add_f32_e32 v17, v17, v43
	v_fmamk_f32 v7, v14, 0xba800000, v7
	v_fmamk_f32 v5, v14, 0xba800000, v5
	v_add_f32_e32 v15, v15, v17
	v_fmac_f32_e32 v6, 0xba800000, v14
	v_fmac_f32_e32 v4, 0xba800000, v14
	v_mul_f32_e32 v17, v5, v5
	v_mul_f32_e32 v43, v7, v7
	v_fmac_f32_e32 v17, v4, v4
	v_fmac_f32_e32 v43, v6, v6
	v_add_f32_e32 v17, v17, v43
	v_fmamk_f32 v3, v14, 0xba800000, v3
	v_fmamk_f32 v1, v14, 0xba800000, v1
	v_add_f32_e32 v15, v17, v15
	v_fmac_f32_e32 v2, 0xba800000, v14
	v_fmac_f32_e32 v0, 0xba800000, v14
	v_mul_f32_e32 v14, v1, v1
	v_mul_f32_e32 v17, v3, v3
	v_fmac_f32_e32 v14, v0, v0
	v_fmac_f32_e32 v17, v2, v2
	v_add_f32_e32 v14, v14, v17
	v_add_f32_e32 v14, v14, v15
	ds_bpermute_b32 v15, v19, v14
	s_waitcnt lgkmcnt(0)
	v_add_f32_e32 v14, v14, v15
	ds_bpermute_b32 v15, v21, v14
	s_waitcnt lgkmcnt(0)
	v_add_f32_e32 v14, v14, v15
	ds_bpermute_b32 v15, v23, v14
	s_waitcnt lgkmcnt(0)
	v_add_f32_e32 v14, v14, v15
	ds_bpermute_b32 v15, v25, v14
	s_waitcnt lgkmcnt(0)
	v_add_f32_e32 v14, v14, v15
	ds_bpermute_b32 v15, v64, v14
	s_waitcnt lgkmcnt(0)
	v_add_f32_e32 v14, v14, v15
	ds_bpermute_b32 v15, v65, v14
	s_and_saveexec_b64 s[10:11], s[0:1]
	s_cbranch_execz .LBB0_676
; __device__ __forceinline__ unsigned pk2(float lo, float hi) { f32x2_t v = {lo, hi}; bf16x2_t b = __builtin_convertvector(v, bf16x2_t); return __builtin_bit_cast(unsigned, b); }
; __device__ __forceinline__ void ln_rows(const Params& p, const bf16_t* __restrict__ O, const float* gmod, const float* lng, const float* lnb, const float* nmod  , ...
;     ...
;             const float rstd = 1.0f / sqrtf(wave_sum(s2) * (1.0f / DM) + LN_EPS);
;             if (ok[r]) {
; #pragma unroll
;                 for (int j = 0; j < 4; ++j) { const int col = 4 * lane + 256 * j; const f32x4 y = v[j] * rstd * *(const f32x4*)(lng + col) + *(const f32x4*)(lnb + col);
;                     if (outp) { *(f32x4*)(outp + (size_t)row * DM + col) = y; }
;                     else { *(f32x4*)(X + (size_t)row * DM + col) = y;
;                         const float* nm = nmod + (size_t)bi * MODW; const f32x4 u = y * (*(const f32x4*)(nm + 1024 + col) + 1.0f) + *(const f32x4*)(nm + col);
;                         u32x2 w; w.x = pk2(u[0], u[1]); w.y = pk2(u[2], u[3]); *(u32x2*)(U + (size_t)row * DM + col) = w; } }
	global_load_dwordx4 v[58:61], v[26:27], off
	global_load_dwordx4 v[66:69], v[28:29], off
	s_waitcnt lgkmcnt(0)
	v_add_f32_e32 v14, v14, v15
	v_fmamk_f32 v14, v14, 0x3a800000, v219
	v_cmp_gt_f32_e32 vcc, s86, v14
	v_mul_f32_e32 v15, 0x4f800000, v14
	v_lshl_add_u64 v[52:53], v[52:53], 2, s[66:67]
	v_cndmask_b32_e32 v14, v14, v15, vcc
	v_sqrt_f32_e32 v15, v14
	v_lshl_add_u64 v[50:51], v[36:37], 0, v[50:51]
	v_add_u32_e32 v17, -1, v15
	v_fma_f32 v43, -v17, v15, v14
	v_cmp_ge_f32_e64 s[0:1], 0, v43
	v_add_u32_e32 v43, 1, v15
	s_nop 0
	v_cndmask_b32_e64 v17, v15, v17, s[0:1]
	v_fma_f32 v15, -v43, v15, v14
	v_cmp_lt_f32_e64 s[0:1], 0, v15
	s_nop 1
	v_cndmask_b32_e64 v15, v17, v43, s[0:1]
	v_mul_f32_e32 v17, 0x37800000, v15
	v_cndmask_b32_e32 v15, v15, v17, vcc
	v_cmp_class_f32_e32 vcc, v14, v222
	s_nop 1
	v_cndmask_b32_e32 v14, v15, v14, vcc
	v_div_scale_f32 v15, s[0:1], v14, v14, 1.0
	v_rcp_f32_e32 v17, v15
	s_nop 0
	v_fma_f32 v43, -v15, v17, 1.0
	v_fmac_f32_e32 v17, v43, v17
	v_div_scale_f32 v43, vcc, 1.0, v14, 1.0
	v_mul_f32_e32 v45, v43, v17
	v_fma_f32 v47, -v15, v45, v43
	v_fmac_f32_e32 v45, v47, v17
	v_fma_f32 v15, -v15, v45, v43
	v_div_fmas_f32 v15, v15, v17, v45
	v_div_fixup_f32 v56, v15, v14, 1.0
	v_pk_mul_f32 v[54:55], v[54:55], v[56:57] op_sel_hi:[1,0]
	v_pk_mul_f32 v[12:13], v[12:13], v[56:57] op_sel_hi:[1,0]
	v_lshl_add_u64 v[14:15], v[52:53], 0, s[72:73]
	v_mov_b32_e32 v47, v161
	v_lshl_add_u64 v[46:47], v[14:15], 0, v[46:47]
	v_mov_b32_e32 v45, v161
	v_mov_b32_e32 v43, v161
	s_waitcnt vmcnt(0)
	v_pk_fma_f32 v[60:61], v[12:13], v[60:61], v[68:69]
	v_pk_fma_f32 v[58:59], v[54:55], v[58:59], v[66:67]
	v_lshl_add_u64 v[12:13], v[34:35], 0, v[48:49]
	global_store_dwordx4 v[12:13], v[58:61], off
	v_lshl_add_u64 v[48:49], v[14:15], 0, v[160:161]
	global_load_dwordx4 v[66:69], v[48:49], off
	v_lshl_add_u64 v[48:49], v[52:53], 0, v[160:161]
	global_load_dwordx4 v[52:55], v[48:49], off
	s_waitcnt vmcnt(1)
	v_pk_add_f32 v[62:63], v[68:69], 1.0 op_sel_hi:[1,0]
	v_pk_add_f32 v[66:67], v[66:67], 1.0 op_sel_hi:[1,0]
	s_waitcnt vmcnt(0)
	v_pk_fma_f32 v[54:55], v[60:61], v[62:63], v[54:55]
	v_pk_fma_f32 v[52:53], v[58:59], v[66:67], v[52:53]
	v_pk_mul_f32 v[58:59], v[10:11], v[56:57] op_sel_hi:[1,0]
	v_cvt_pk_bf16_f32 v52, v52, v53
	v_cvt_pk_bf16_f32 v53, v54, v55
	global_store_dwordx2 v[50:51], v[52:53], off
	v_pk_mul_f32 v[60:61], v[8:9], v[56:57] op_sel_hi:[1,0]
	global_load_dwordx4 v[8:11], v[26:27], off offset:1024
	global_load_dwordx4 v[52:55], v[28:29], off offset:1024
	s_waitcnt vmcnt(0)
	v_pk_fma_f32 v[8:9], v[60:61], v[8:9], v[52:53]
	v_pk_fma_f32 v[10:11], v[58:59], v[10:11], v[54:55]
	global_store_dwordx4 v[12:13], v[8:11], off offset:1024
	global_load_dwordx4 v[52:55], v[46:47], off
	s_waitcnt vmcnt(0)
	v_pk_add_f32 v[46:47], v[54:55], 1.0 op_sel_hi:[1,0]
	v_pk_add_f32 v[58:59], v[52:53], 1.0 op_sel_hi:[1,0]
	global_load_dwordx4 v[52:55], v[48:49], off offset:1024
	s_waitcnt vmcnt(0)
	v_pk_fma_f32 v[10:11], v[10:11], v[46:47], v[54:55]
	v_pk_fma_f32 v[8:9], v[8:9], v[58:59], v[52:53]
	v_pk_mul_f32 v[46:47], v[6:7], v[56:57] op_sel_hi:[1,0]
	v_cvt_pk_bf16_f32 v8, v8, v9
	v_cvt_pk_bf16_f32 v9, v10, v11
	global_store_dwordx2 v[50:51], v[8:9], off offset:512
	v_pk_mul_f32 v[52:53], v[4:5], v[56:57] op_sel_hi:[1,0]
	global_load_dwordx4 v[4:7], v[26:27], off offset:2048
	global_load_dwordx4 v[8:11], v[28:29], off offset:2048
	s_waitcnt vmcnt(0)
	v_pk_fma_f32 v[4:5], v[52:53], v[4:5], v[8:9]
	v_pk_fma_f32 v[6:7], v[46:47], v[6:7], v[10:11]
	global_store_dwordx4 v[12:13], v[4:7], off offset:2048
	v_lshl_add_u64 v[8:9], v[14:15], 0, v[44:45]
	global_load_dwordx4 v[8:11], v[8:9], off
	s_waitcnt vmcnt(0)
	v_pk_add_f32 v[44:45], v[10:11], 1.0 op_sel_hi:[1,0]
	v_pk_add_f32 v[46:47], v[8:9], 1.0 op_sel_hi:[1,0]
	global_load_dwordx4 v[8:11], v[48:49], off offset:2048
	s_waitcnt vmcnt(0)
	v_pk_fma_f32 v[6:7], v[6:7], v[44:45], v[10:11]
	v_pk_fma_f32 v[4:5], v[4:5], v[46:47], v[8:9]
	v_pk_mul_f32 v[8:9], v[2:3], v[56:57] op_sel_hi:[1,0]
	v_cvt_pk_bf16_f32 v4, v4, v5
	v_cvt_pk_bf16_f32 v5, v6, v7
	global_store_dwordx2 v[50:51], v[4:5], off offset:1024
	v_pk_mul_f32 v[10:11], v[0:1], v[56:57] op_sel_hi:[1,0]
	global_load_dwordx4 v[0:3], v[26:27], off offset:3072
	global_load_dwordx4 v[4:7], v[28:29], off offset:3072
	s_waitcnt vmcnt(0)
	v_pk_fma_f32 v[0:1], v[10:11], v[0:1], v[4:5]
	v_pk_fma_f32 v[2:3], v[8:9], v[2:3], v[6:7]
	global_store_dwordx4 v[12:13], v[0:3], off offset:3072
	v_lshl_add_u64 v[4:5], v[14:15], 0, v[42:43]
	global_load_dwordx4 v[4:7], v[4:5], off
	s_waitcnt vmcnt(0)
	v_pk_add_f32 v[8:9], v[6:7], 1.0 op_sel_hi:[1,0]
	v_pk_add_f32 v[10:11], v[4:5], 1.0 op_sel_hi:[1,0]
	global_load_dwordx4 v[4:7], v[48:49], off offset:3072
	s_waitcnt vmcnt(0)
	v_pk_fma_f32 v[2:3], v[2:3], v[8:9], v[6:7]
	v_pk_fma_f32 v[0:1], v[0:1], v[10:11], v[4:5]
	s_nop 0
	v_cvt_pk_bf16_f32 v0, v0, v1
	v_cvt_pk_bf16_f32 v1, v2, v3
	global_store_dwordx2 v[50:51], v[0:1], off offset:1536
	s_branch .LBB0_676

; #define PG8_STAGE(bufoff, gbase, voff) do { _Pragma("unroll") for (int _i = 0; _i < 2; ++_i) \
;         __builtin_amdgcn_global_load_lds((const unsigned*)((const char*)(gbase) + (voff)[_i]), (PG8_LAS unsigned*)(lds + (bufoff) + ldsw + _i * 8192), 16, 0, 0); } while (0)
; #define PG8_LDA(dst, b, h) do { _Pragma("unroll") for (int m = 0; m < 4; ++m) _Pragma("unroll") for (int k = 0; k < 2; ++k) dst[m][k] = *(const PG8_LAS bf16x8*)(lds + PG8_SA(b, h) + aoff + m * 2048 + k * 1024); } while (0)
; #define PG8_LDB(dst, b, h) do { _Pragma("unroll") for (int n = 0; n < 2; ++n) _Pragma("unroll") for (int k = 0; k < 2; ++k) dst[n][k] = *(const PG8_LAS bf16x8*)(lds + PG8_SB(b, h) + boff + n * 2048 + k * 1024); } while (0)
; #define PG8_MMA(ai, bj, At, Bt) do { __builtin_amdgcn_s_setprio(1); _Pragma("unroll") for (int m = 0; m < 4; ++m) _Pragma("unroll") for (int n = 0; n < 2; ++n) _Pragma("unroll") for (int k = 0; k < 2; ++k) \
;         acc[ai][bj][m][n] = __builtin_amdgcn_mfma_f32_16x16x32_bf16(Bt[n][k], At[m][k], acc[ai][bj][m][n], 0, 0, 0); __builtin_amdgcn_s_setprio(0); } while (0)
; #define PG8_WAIT_V(n) asm volatile("s_waitcnt vmcnt(" #n ")" ::: "memory")
; #define PG8_BAR __builtin_amdgcn_s_barrier()
; template <class Epi, class Sched, bool ALIGN_EPI = false, bool SP2 = false>
; __device__ __forceinline__ void gemm_phase(PG8_LAS unsigned char* lds, const Gemm g, const Sched& S, const Epi& E) {
;     ...
;         for (int t = 0; t < nt; t += 2) {
;             const bool last = (t == nt - 2);
;             const char* a1 = cA + (size_t)(t + 1) * kstep;
;             const char* a2 = last ? nA : cA + (size_t)(t + 2) * kstep; const char* b2 = last ? nB : cB + (size_t)(t + 2) * kstep;
;             const char* a3 = a2 + kstep; const char* b3 = b2 + kstep;
;             if (last && has_next) S.a_ready(nxt);
;             if constexpr (SP2) {
;             PG8_LDB(B0, 0, 0); PG8_LDB(B1, 0, 1); PG8_SCHED; PG8_LDA(At, 0, 0); PG8_STAGE(PG8_SA(1, 1), a1 + hstep, voffA);
;             PG8_WAIT_V(8); PG8_WAIT_L(0); PG8_BAR; PG8_MMA(0, 0, At, B0); PG8_MMA(0, 1, At, B1); PG8_BAR; PG8_SCHED;
;             PG8_LDA(At, 0, 1); PG8_STAGE(PG8_SB(0, 0), b2, voffB); PG8_STAGE(PG8_SB(0, 1), b2 + hstep, voffB); PG8_STAGE(PG8_SA(0, 0), a2, voffA);
;             PG8_WAIT_V(8); PG8_WAIT_L(0); PG8_BAR; PG8_MMA(1, 0, At, B0); PG8_MMA(1, 1, At, B1); PG8_BAR; PG8_SCHED;
.LBB0_686:
	s_add_u32 s10, s8, 0xe89c0080
	s_addc_u32 s11, s9, -1
	s_cmp_lg_u32 s41, 12
	s_cselect_b32 s10, s10, 0
	s_cselect_b32 s11, s11, 0
	s_add_u32 s12, s4, s10
	s_addc_u32 s13, s5, s11
	s_add_i32 s44, 0, 0x10000
	s_add_u32 s10, s0, s10
	v_add_u32_e32 v145, s44, v143
	s_addc_u32 s11, s1, s11
	s_add_i32 s46, 0, 0x14000
	ds_read_b128 v[146:149], v145
	ds_read_b128 v[150:153], v145 offset:1024
	ds_read_b128 v[154:157], v145 offset:2048
	ds_read_b128 v[162:165], v145 offset:3072
	v_add_u32_e32 v145, s46, v143
	ds_read_b128 v[166:169], v145
	ds_read_b128 v[170:173], v145 offset:1024
	ds_read_b128 v[174:177], v145 offset:2048
	ds_read_b128 v[178:181], v145 offset:3072
	v_lshl_add_u64 v[158:159], v[134:135], 0, s[8:9]
	s_add_i32 m0, s31, 0xc000
	ds_read_b128 v[182:185], v144
	ds_read_b128 v[186:189], v144 offset:1024
	ds_read_b128 v[190:193], v144 offset:2048
	ds_read_b128 v[196:199], v144 offset:3072
	ds_read_b128 v[200:203], v144 offset:4096
	ds_read_b128 v[204:207], v144 offset:5120
	ds_read_b128 v[208:211], v144 offset:6144
	ds_read_b128 v[212:215], v144 offset:7168
	global_load_lds_dwordx4 v[158:159], off
	v_lshl_add_u64 v[158:159], v[136:137], 0, s[8:9]
	s_add_i32 m0, s31, 0xe000
	s_nop 0
	global_load_lds_dwordx4 v[158:159], off
	s_waitcnt vmcnt(8)
	s_waitcnt lgkmcnt(0)
	s_barrier
	s_setprio 1
	v_mfma_f32_16x16x32_bf16 v[124:127], v[146:149], v[182:185], v[124:127]
	v_mfma_f32_16x16x32_bf16 v[120:123], v[154:157], v[182:185], v[120:123]
	v_mfma_f32_16x16x32_bf16 v[116:119], v[146:149], v[190:193], v[116:119]
	v_mfma_f32_16x16x32_bf16 v[112:115], v[154:157], v[190:193], v[112:115]
	v_mfma_f32_16x16x32_bf16 v[100:103], v[146:149], v[200:203], v[100:103]
	v_mfma_f32_16x16x32_bf16 v[96:99], v[154:157], v[200:203], v[96:99]
	v_mfma_f32_16x16x32_bf16 v[84:87], v[146:149], v[208:211], v[84:87]
	v_mfma_f32_16x16x32_bf16 v[80:83], v[154:157], v[208:211], v[80:83]
	v_mfma_f32_16x16x32_bf16 v[124:127], v[150:153], v[186:189], v[124:127]
	v_mfma_f32_16x16x32_bf16 v[120:123], v[162:165], v[186:189], v[120:123]
	v_mfma_f32_16x16x32_bf16 v[116:119], v[150:153], v[196:199], v[116:119]
	v_mfma_f32_16x16x32_bf16 v[112:115], v[162:165], v[196:199], v[112:115]
	v_mfma_f32_16x16x32_bf16 v[100:103], v[150:153], v[204:207], v[100:103]
	v_mfma_f32_16x16x32_bf16 v[96:99], v[162:165], v[204:207], v[96:99]
	v_mfma_f32_16x16x32_bf16 v[84:87], v[150:153], v[212:215], v[84:87]
	v_mfma_f32_16x16x32_bf16 v[80:83], v[162:165], v[212:215], v[80:83]
	v_mfma_f32_16x16x32_bf16 v[108:111], v[166:169], v[182:185], v[108:111]
	v_mfma_f32_16x16x32_bf16 v[104:107], v[174:177], v[182:185], v[104:107]
	v_mfma_f32_16x16x32_bf16 v[92:95], v[166:169], v[190:193], v[92:95]
	v_mfma_f32_16x16x32_bf16 v[88:91], v[174:177], v[190:193], v[88:91]
	v_mfma_f32_16x16x32_bf16 v[76:79], v[166:169], v[200:203], v[76:79]
	v_mfma_f32_16x16x32_bf16 v[72:75], v[174:177], v[200:203], v[72:75]
	v_mfma_f32_16x16x32_bf16 v[68:71], v[166:169], v[208:211], v[68:71]
	v_mfma_f32_16x16x32_bf16 v[64:67], v[174:177], v[208:211], v[64:67]
	v_mfma_f32_16x16x32_bf16 v[108:111], v[170:173], v[186:189], v[108:111]
	v_mfma_f32_16x16x32_bf16 v[104:107], v[178:181], v[186:189], v[104:107]
	v_mfma_f32_16x16x32_bf16 v[92:95], v[170:173], v[196:199], v[92:95]
	v_mfma_f32_16x16x32_bf16 v[88:91], v[178:181], v[196:199], v[88:91]
	v_mfma_f32_16x16x32_bf16 v[76:79], v[170:173], v[204:207], v[76:79]
	v_mfma_f32_16x16x32_bf16 v[72:75], v[178:181], v[204:207], v[72:75]
	v_mfma_f32_16x16x32_bf16 v[68:71], v[170:173], v[212:215], v[68:71]
	v_mfma_f32_16x16x32_bf16 v[64:67], v[178:181], v[212:215], v[64:67]
	s_setprio 0
	s_barrier
	s_add_i32 s44, s44, s30
	v_lshl_add_u64 v[158:159], s[10:11], 0, v[160:161]
	s_mov_b32 m0, s44
	ds_read_b128 v[182:185], v144 offset:16384
	ds_read_b128 v[186:189], v144 offset:17408
	ds_read_b128 v[190:193], v144 offset:18432
	ds_read_b128 v[196:199], v144 offset:19456
	ds_read_b128 v[200:203], v144 offset:20480
	ds_read_b128 v[204:207], v144 offset:21504
	ds_read_b128 v[208:211], v144 offset:22528
	ds_read_b128 v[212:215], v144 offset:23552
	global_load_lds_dwordx4 v[158:159], off
	s_add_i32 m0, s44, 0x2000
	s_add_u32 s44, s10, 0x40000
	v_lshl_add_u64 v[216:217], s[10:11], 0, v[132:133]
	s_addc_u32 s45, s11, 0
	s_add_i32 s46, s46, s30
	global_load_lds_dwordx4 v[216:217], off
	v_lshl_add_u64 v[228:229], s[44:45], 0, v[160:161]
	s_mov_b32 m0, s46
	v_lshl_add_u64 v[230:231], s[12:13], 0, v[130:131]
	global_load_lds_dwordx4 v[228:229], off
	v_lshl_add_u64 v[228:229], s[44:45], 0, v[132:133]
	s_add_i32 m0, s46, 0x2000
	s_nop 0
	global_load_lds_dwordx4 v[228:229], off
	v_lshl_add_u64 v[228:229], s[12:13], 0, v[128:129]
	s_mov_b32 m0, s31
	s_nop 0
	global_load_lds_dwordx4 v[228:229], off
	s_mov_b32 m0, s33
	s_nop 0
	global_load_lds_dwordx4 v[230:231], off
	s_waitcnt vmcnt(8)
	s_waitcnt lgkmcnt(0)
	s_barrier
; #define PG8_STAGE(bufoff, gbase, voff) do { _Pragma("unroll") for (int _i = 0; _i < 2; ++_i) \
;         __builtin_amdgcn_global_load_lds((const unsigned*)((const char*)(gbase) + (voff)[_i]), (PG8_LAS unsigned*)(lds + (bufoff) + ldsw + _i * 8192), 16, 0, 0); } while (0)
; #define PG8_LDA(dst, b, h) do { _Pragma("unroll") for (int m = 0; m < 4; ++m) _Pragma("unroll") for (int k = 0; k < 2; ++k) dst[m][k] = *(const PG8_LAS bf16x8*)(lds + PG8_SA(b, h) + aoff + m * 2048 + k * 1024); } while (0)
; #define PG8_LDB(dst, b, h) do { _Pragma("unroll") for (int n = 0; n < 2; ++n) _Pragma("unroll") for (int k = 0; k < 2; ++k) dst[n][k] = *(const PG8_LAS bf16x8*)(lds + PG8_SB(b, h) + boff + n * 2048 + k * 1024); } while (0)
; #define PG8_MMA(ai, bj, At, Bt) do { __builtin_amdgcn_s_setprio(1); _Pragma("unroll") for (int m = 0; m < 4; ++m) _Pragma("unroll") for (int n = 0; n < 2; ++n) _Pragma("unroll") for (int k = 0; k < 2; ++k) \
;         acc[ai][bj][m][n] = __builtin_amdgcn_mfma_f32_16x16x32_bf16(Bt[n][k], At[m][k], acc[ai][bj][m][n], 0, 0, 0); __builtin_amdgcn_s_setprio(0); } while (0)
; #define PG8_WAIT_V(n) asm volatile("s_waitcnt vmcnt(" #n ")" ::: "memory")
; #define PG8_WAIT_L(n) asm volatile("s_waitcnt lgkmcnt(" #n ")" ::: "memory")
; #define PG8_BAR __builtin_amdgcn_s_barrier()
; #define PG8_SCHED __builtin_amdgcn_sched_barrier(0)
; template <class Epi, class Sched, bool ALIGN_EPI = false, bool SP2 = false>
; __device__ __forceinline__ void gemm_phase(PG8_LAS unsigned char* lds, const Gemm g, const Sched& S, const Epi& E) {
;     ...
;             PG8_WAIT_V(8); PG8_WAIT_L(0); PG8_BAR; PG8_MMA(1, 0, At, B0); PG8_MMA(1, 1, At, B1); PG8_BAR; PG8_SCHED;
;             PG8_LDB(B0, 1, 0); PG8_LDB(B1, 1, 1); PG8_SCHED; PG8_LDA(At, 1, 0); PG8_STAGE(PG8_SA(0, 1), a2 + hstep, voffA);
;             PG8_WAIT_V(8); PG8_WAIT_L(0); PG8_BAR; PG8_MMA(0, 0, At, B0); PG8_MMA(0, 1, At, B1); PG8_BAR; PG8_SCHED;
	s_setprio 1
	v_mfma_f32_16x16x32_bf16 v[60:63], v[146:149], v[182:185], v[60:63]
	v_mfma_f32_16x16x32_bf16 v[56:59], v[154:157], v[182:185], v[56:59]
	v_mfma_f32_16x16x32_bf16 v[52:55], v[146:149], v[190:193], v[52:55]
	v_mfma_f32_16x16x32_bf16 v[48:51], v[154:157], v[190:193], v[48:51]
	v_mfma_f32_16x16x32_bf16 v[36:39], v[146:149], v[200:203], v[36:39]
	v_mfma_f32_16x16x32_bf16 v[32:35], v[154:157], v[200:203], v[32:35]
	v_mfma_f32_16x16x32_bf16 v[20:23], v[146:149], v[208:211], v[20:23]
	v_mfma_f32_16x16x32_bf16 v[16:19], v[154:157], v[208:211], v[16:19]
	v_mfma_f32_16x16x32_bf16 v[60:63], v[150:153], v[186:189], v[60:63]
	v_mfma_f32_16x16x32_bf16 v[56:59], v[162:165], v[186:189], v[56:59]
	v_mfma_f32_16x16x32_bf16 v[52:55], v[150:153], v[196:199], v[52:55]
	v_mfma_f32_16x16x32_bf16 v[48:51], v[162:165], v[196:199], v[48:51]
	v_mfma_f32_16x16x32_bf16 v[36:39], v[150:153], v[204:207], v[36:39]
	v_mfma_f32_16x16x32_bf16 v[32:35], v[162:165], v[204:207], v[32:35]
	v_mfma_f32_16x16x32_bf16 v[20:23], v[150:153], v[212:215], v[20:23]
	v_mfma_f32_16x16x32_bf16 v[16:19], v[162:165], v[212:215], v[16:19]
	v_mfma_f32_16x16x32_bf16 v[44:47], v[166:169], v[182:185], v[44:47]
	v_mfma_f32_16x16x32_bf16 v[40:43], v[174:177], v[182:185], v[40:43]
	v_mfma_f32_16x16x32_bf16 v[28:31], v[166:169], v[190:193], v[28:31]
	v_mfma_f32_16x16x32_bf16 v[24:27], v[174:177], v[190:193], v[24:27]
	v_mfma_f32_16x16x32_bf16 v[12:15], v[166:169], v[200:203], v[12:15]
	v_mfma_f32_16x16x32_bf16 v[8:11], v[174:177], v[200:203], v[8:11]
	v_mfma_f32_16x16x32_bf16 v[4:7], v[166:169], v[208:211], v[4:7]
	v_mfma_f32_16x16x32_bf16 v[0:3], v[174:177], v[208:211], v[0:3]
	v_mfma_f32_16x16x32_bf16 v[44:47], v[170:173], v[186:189], v[44:47]
	v_mfma_f32_16x16x32_bf16 v[40:43], v[178:181], v[186:189], v[40:43]
	v_mfma_f32_16x16x32_bf16 v[28:31], v[170:173], v[196:199], v[28:31]
	v_mfma_f32_16x16x32_bf16 v[24:27], v[178:181], v[196:199], v[24:27]
	v_mfma_f32_16x16x32_bf16 v[12:15], v[170:173], v[204:207], v[12:15]
	v_mfma_f32_16x16x32_bf16 v[8:11], v[178:181], v[204:207], v[8:11]
	v_mfma_f32_16x16x32_bf16 v[4:7], v[170:173], v[212:215], v[4:7]
	v_mfma_f32_16x16x32_bf16 v[0:3], v[178:181], v[212:215], v[0:3]
	s_setprio 0
	s_barrier
	s_add_i32 s44, 0, 0x18000
	v_add_u32_e32 v145, s44, v143
	s_add_i32 s45, 0, 0x1c000
	ds_read_b128 v[146:149], v145
	ds_read_b128 v[150:153], v145 offset:1024
	ds_read_b128 v[154:157], v145 offset:2048
	ds_read_b128 v[162:165], v145 offset:3072
	v_add_u32_e32 v145, s45, v143
	ds_read_b128 v[166:169], v145
	ds_read_b128 v[170:173], v145 offset:1024
	ds_read_b128 v[174:177], v145 offset:2048
	ds_read_b128 v[178:181], v145 offset:3072
	s_add_u32 s12, s12, 0x40000
	s_addc_u32 s13, s13, 0
	s_mov_b32 m0, s34
	v_lshl_add_u64 v[232:233], s[12:13], 0, v[128:129]
	ds_read_b128 v[182:185], v144 offset:32768
	ds_read_b128 v[186:189], v144 offset:33792
	ds_read_b128 v[190:193], v144 offset:34816
	ds_read_b128 v[196:199], v144 offset:35840
	ds_read_b128 v[200:203], v144 offset:36864
	ds_read_b128 v[204:207], v144 offset:37888
	ds_read_b128 v[208:211], v144 offset:38912
	ds_read_b128 v[212:215], v144 offset:39936
	global_load_lds_dwordx4 v[232:233], off
	v_lshl_add_u64 v[232:233], s[12:13], 0, v[130:131]
	s_mov_b32 m0, s35
	s_nop 0
	global_load_lds_dwordx4 v[232:233], off
	s_waitcnt vmcnt(8)
	s_waitcnt lgkmcnt(0)
	s_barrier
	s_setprio 1
	v_mfma_f32_16x16x32_bf16 v[124:127], v[146:149], v[182:185], v[124:127]
	v_mfma_f32_16x16x32_bf16 v[120:123], v[154:157], v[182:185], v[120:123]
	v_mfma_f32_16x16x32_bf16 v[116:119], v[146:149], v[190:193], v[116:119]
	v_mfma_f32_16x16x32_bf16 v[112:115], v[154:157], v[190:193], v[112:115]
	v_mfma_f32_16x16x32_bf16 v[100:103], v[146:149], v[200:203], v[100:103]
	v_mfma_f32_16x16x32_bf16 v[96:99], v[154:157], v[200:203], v[96:99]
	v_mfma_f32_16x16x32_bf16 v[84:87], v[146:149], v[208:211], v[84:87]
	v_mfma_f32_16x16x32_bf16 v[80:83], v[154:157], v[208:211], v[80:83]
	v_mfma_f32_16x16x32_bf16 v[124:127], v[150:153], v[186:189], v[124:127]
	v_mfma_f32_16x16x32_bf16 v[120:123], v[162:165], v[186:189], v[120:123]
	v_mfma_f32_16x16x32_bf16 v[116:119], v[150:153], v[196:199], v[116:119]
	v_mfma_f32_16x16x32_bf16 v[112:115], v[162:165], v[196:199], v[112:115]
	v_mfma_f32_16x16x32_bf16 v[100:103], v[150:153], v[204:207], v[100:103]
	v_mfma_f32_16x16x32_bf16 v[96:99], v[162:165], v[204:207], v[96:99]
	v_mfma_f32_16x16x32_bf16 v[84:87], v[150:153], v[212:215], v[84:87]
	v_mfma_f32_16x16x32_bf16 v[80:83], v[162:165], v[212:215], v[80:83]
	v_mfma_f32_16x16x32_bf16 v[108:111], v[166:169], v[182:185], v[108:111]
	v_mfma_f32_16x16x32_bf16 v[104:107], v[174:177], v[182:185], v[104:107]
	v_mfma_f32_16x16x32_bf16 v[92:95], v[166:169], v[190:193], v[92:95]
	v_mfma_f32_16x16x32_bf16 v[88:91], v[174:177], v[190:193], v[88:91]
	v_mfma_f32_16x16x32_bf16 v[76:79], v[166:169], v[200:203], v[76:79]
	v_mfma_f32_16x16x32_bf16 v[72:75], v[174:177], v[200:203], v[72:75]
	v_mfma_f32_16x16x32_bf16 v[68:71], v[166:169], v[208:211], v[68:71]
	v_mfma_f32_16x16x32_bf16 v[64:67], v[174:177], v[208:211], v[64:67]
	v_mfma_f32_16x16x32_bf16 v[108:111], v[170:173], v[186:189], v[108:111]
	v_mfma_f32_16x16x32_bf16 v[104:107], v[178:181], v[186:189], v[104:107]
	v_mfma_f32_16x16x32_bf16 v[92:95], v[170:173], v[196:199], v[92:95]
	v_mfma_f32_16x16x32_bf16 v[88:91], v[178:181], v[196:199], v[88:91]
	v_mfma_f32_16x16x32_bf16 v[76:79], v[170:173], v[204:207], v[76:79]
	v_mfma_f32_16x16x32_bf16 v[72:75], v[178:181], v[204:207], v[72:75]
	v_mfma_f32_16x16x32_bf16 v[68:71], v[170:173], v[212:215], v[68:71]
	v_mfma_f32_16x16x32_bf16 v[64:67], v[178:181], v[212:215], v[64:67]
	s_setprio 0
	s_barrier
; #define PG8_STAGE(bufoff, gbase, voff) do { _Pragma("unroll") for (int _i = 0; _i < 2; ++_i) \
;         __builtin_amdgcn_global_load_lds((const unsigned*)((const char*)(gbase) + (voff)[_i]), (PG8_LAS unsigned*)(lds + (bufoff) + ldsw + _i * 8192), 16, 0, 0); } while (0)
; #define PG8_LDA(dst, b, h) do { _Pragma("unroll") for (int m = 0; m < 4; ++m) _Pragma("unroll") for (int k = 0; k < 2; ++k) dst[m][k] = *(const PG8_LAS bf16x8*)(lds + PG8_SA(b, h) + aoff + m * 2048 + k * 1024); } while (0)
; #define PG8_MMA(ai, bj, At, Bt) do { __builtin_amdgcn_s_setprio(1); _Pragma("unroll") for (int m = 0; m < 4; ++m) _Pragma("unroll") for (int n = 0; n < 2; ++n) _Pragma("unroll") for (int k = 0; k < 2; ++k) \
;         acc[ai][bj][m][n] = __builtin_amdgcn_mfma_f32_16x16x32_bf16(Bt[n][k], At[m][k], acc[ai][bj][m][n], 0, 0, 0); __builtin_amdgcn_s_setprio(0); } while (0)
; #define PG8_WAIT_V(n) asm volatile("s_waitcnt vmcnt(" #n ")" ::: "memory")
; #define PG8_WAIT_L(n) asm volatile("s_waitcnt lgkmcnt(" #n ")" ::: "memory")
; #define PG8_BAR __builtin_amdgcn_s_barrier()
; #define PG8_SCHED __builtin_amdgcn_sched_barrier(0)
; template <class Epi, class Sched, bool ALIGN_EPI = false, bool SP2 = false>
; __device__ __forceinline__ void gemm_phase(PG8_LAS unsigned char* lds, const Gemm g, const Sched& S, const Epi& E) {
;     ...
;             PG8_LDA(At, 1, 1); PG8_STAGE(PG8_SB(1, 0), b3, voffB); PG8_STAGE(PG8_SB(1, 1), b3 + hstep, voffB); PG8_STAGE(PG8_SA(1, 0), a3, voffA);
;             PG8_WAIT_V(8); PG8_WAIT_L(0); PG8_BAR; PG8_MMA(1, 0, At, B0); PG8_MMA(1, 1, At, B1); PG8_BAR; PG8_SCHED;
	s_add_i32 s12, s44, s30
	v_lshl_add_u64 v[158:159], v[158:159], 0, s[42:43]
	s_mov_b32 m0, s12
	ds_read_b128 v[182:185], v144 offset:49152
	ds_read_b128 v[186:189], v144 offset:50176
	ds_read_b128 v[190:193], v144 offset:51200
	ds_read_b128 v[196:199], v144 offset:52224
	ds_read_b128 v[200:203], v144 offset:53248
	ds_read_b128 v[204:207], v144 offset:54272
	ds_read_b128 v[208:211], v144 offset:55296
	ds_read_b128 v[212:215], v144 offset:56320
	global_load_lds_dwordx4 v[158:159], off
	s_add_i32 m0, s12, 0x2000
	s_add_u32 s10, s10, 0x40080
	v_lshl_add_u64 v[158:159], v[216:217], 0, s[42:43]
	s_addc_u32 s11, s11, 0
	s_add_i32 s12, s45, s30
	global_load_lds_dwordx4 v[158:159], off
	v_lshl_add_u64 v[158:159], s[10:11], 0, v[160:161]
	s_mov_b32 m0, s12
	s_nop 0
	global_load_lds_dwordx4 v[158:159], off
	v_lshl_add_u64 v[158:159], s[10:11], 0, v[132:133]
	s_add_i32 m0, s12, 0x2000
	s_nop 0
	global_load_lds_dwordx4 v[158:159], off
	v_lshl_add_u64 v[158:159], v[228:229], 0, s[42:43]
	s_mov_b32 m0, s37
	s_nop 0
	global_load_lds_dwordx4 v[158:159], off
	v_lshl_add_u64 v[158:159], v[230:231], 0, s[42:43]
	s_mov_b32 m0, s40
	s_nop 0
	global_load_lds_dwordx4 v[158:159], off
	s_waitcnt vmcnt(8)
	s_waitcnt lgkmcnt(0)
	s_barrier
	s_setprio 1
	v_mfma_f32_16x16x32_bf16 v[60:63], v[146:149], v[182:185], v[60:63]
	v_mfma_f32_16x16x32_bf16 v[56:59], v[154:157], v[182:185], v[56:59]
	v_mfma_f32_16x16x32_bf16 v[52:55], v[146:149], v[190:193], v[52:55]
	v_mfma_f32_16x16x32_bf16 v[48:51], v[154:157], v[190:193], v[48:51]
	v_mfma_f32_16x16x32_bf16 v[36:39], v[146:149], v[200:203], v[36:39]
	v_mfma_f32_16x16x32_bf16 v[32:35], v[154:157], v[200:203], v[32:35]
	v_mfma_f32_16x16x32_bf16 v[20:23], v[146:149], v[208:211], v[20:23]
	v_mfma_f32_16x16x32_bf16 v[16:19], v[154:157], v[208:211], v[16:19]
	v_mfma_f32_16x16x32_bf16 v[60:63], v[150:153], v[186:189], v[60:63]
	v_mfma_f32_16x16x32_bf16 v[56:59], v[162:165], v[186:189], v[56:59]
	v_mfma_f32_16x16x32_bf16 v[52:55], v[150:153], v[196:199], v[52:55]
	v_mfma_f32_16x16x32_bf16 v[48:51], v[162:165], v[196:199], v[48:51]
	v_mfma_f32_16x16x32_bf16 v[36:39], v[150:153], v[204:207], v[36:39]
	v_mfma_f32_16x16x32_bf16 v[32:35], v[162:165], v[204:207], v[32:35]
	v_mfma_f32_16x16x32_bf16 v[20:23], v[150:153], v[212:215], v[20:23]
	v_mfma_f32_16x16x32_bf16 v[16:19], v[162:165], v[212:215], v[16:19]
	v_mfma_f32_16x16x32_bf16 v[44:47], v[166:169], v[182:185], v[44:47]
	v_mfma_f32_16x16x32_bf16 v[40:43], v[174:177], v[182:185], v[40:43]
	v_mfma_f32_16x16x32_bf16 v[28:31], v[166:169], v[190:193], v[28:31]
	v_mfma_f32_16x16x32_bf16 v[24:27], v[174:177], v[190:193], v[24:27]
	v_mfma_f32_16x16x32_bf16 v[12:15], v[166:169], v[200:203], v[12:15]
	v_mfma_f32_16x16x32_bf16 v[8:11], v[174:177], v[200:203], v[8:11]
	v_mfma_f32_16x16x32_bf16 v[4:7], v[166:169], v[208:211], v[4:7]
	v_mfma_f32_16x16x32_bf16 v[0:3], v[174:177], v[208:211], v[0:3]
	v_mfma_f32_16x16x32_bf16 v[44:47], v[170:173], v[186:189], v[44:47]
	v_mfma_f32_16x16x32_bf16 v[40:43], v[178:181], v[186:189], v[40:43]
	v_mfma_f32_16x16x32_bf16 v[28:31], v[170:173], v[196:199], v[28:31]
	v_mfma_f32_16x16x32_bf16 v[24:27], v[178:181], v[196:199], v[24:27]
	v_mfma_f32_16x16x32_bf16 v[12:15], v[170:173], v[204:207], v[12:15]
	v_mfma_f32_16x16x32_bf16 v[8:11], v[178:181], v[204:207], v[8:11]
	v_mfma_f32_16x16x32_bf16 v[4:7], v[170:173], v[212:215], v[4:7]
	v_mfma_f32_16x16x32_bf16 v[0:3], v[178:181], v[212:215], v[0:3]
	s_setprio 0
	s_barrier
	s_add_i32 s41, s41, 2
	s_add_u32 s8, s8, 0x100
	s_addc_u32 s9, s9, 0
	s_cmp_gt_u32 s41, 13
	s_cbranch_scc0 .LBB0_686
	s_cmpk_lt_u32 s2, 0x100
	s_cbranch_scc0 .LBB0_689
	s_barrier

; #define PG8_STAGE(bufoff, gbase, voff) do { _Pragma("unroll") for (int _i = 0; _i < 2; ++_i) \
;         __builtin_amdgcn_global_load_lds((const unsigned*)((const char*)(gbase) + (voff)[_i]), (PG8_LAS unsigned*)(lds + (bufoff) + ldsw + _i * 8192), 16, 0, 0); } while (0)
; #define PG8_LDA(dst, b, h) do { _Pragma("unroll") for (int m = 0; m < 4; ++m) _Pragma("unroll") for (int k = 0; k < 2; ++k) dst[m][k] = *(const PG8_LAS bf16x8*)(lds + PG8_SA(b, h) + aoff + m * 2048 + k * 1024); } while (0)
; #define PG8_LDB(dst, b, h) do { _Pragma("unroll") for (int n = 0; n < 2; ++n) _Pragma("unroll") for (int k = 0; k < 2; ++k) dst[n][k] = *(const PG8_LAS bf16x8*)(lds + PG8_SB(b, h) + boff + n * 2048 + k * 1024); } while (0)
; #define PG8_MMA(ai, bj, At, Bt) do { __builtin_amdgcn_s_setprio(1); _Pragma("unroll") for (int m = 0; m < 4; ++m) _Pragma("unroll") for (int n = 0; n < 2; ++n) _Pragma("unroll") for (int k = 0; k < 2; ++k) \
;         acc[ai][bj][m][n] = __builtin_amdgcn_mfma_f32_16x16x32_bf16(Bt[n][k], At[m][k], acc[ai][bj][m][n], 0, 0, 0); __builtin_amdgcn_s_setprio(0); } while (0)
; #define PG8_WAIT_V(n) asm volatile("s_waitcnt vmcnt(" #n ")" ::: "memory")
; #define PG8_BAR __builtin_amdgcn_s_barrier()
; template <class Epi, class Sched, bool ALIGN_EPI = false, bool SP2 = false>
; __device__ __forceinline__ void gemm_phase(PG8_LAS unsigned char* lds, const Gemm g, const Sched& S, const Epi& E) {
;     ...
;         for (int t = 0; t < nt; t += 2) {
;             const bool last = (t == nt - 2);
;             const char* a1 = cA + (size_t)(t + 1) * kstep;
;             const char* a2 = last ? nA : cA + (size_t)(t + 2) * kstep; const char* b2 = last ? nB : cB + (size_t)(t + 2) * kstep;
;             const char* a3 = a2 + kstep; const char* b3 = b2 + kstep;
;             if (last && has_next) S.a_ready(nxt);
;             if constexpr (SP2) {
;             PG8_LDB(B0, 0, 0); PG8_LDB(B1, 0, 1); PG8_SCHED; PG8_LDA(At, 0, 0); PG8_STAGE(PG8_SA(1, 1), a1 + hstep, voffA);
;             PG8_WAIT_V(8); PG8_WAIT_L(0); PG8_BAR; PG8_MMA(0, 0, At, B0); PG8_MMA(0, 1, At, B1); PG8_BAR; PG8_SCHED;
;             PG8_LDA(At, 0, 1); PG8_STAGE(PG8_SB(0, 0), b2, voffB); PG8_STAGE(PG8_SB(0, 1), b2 + hstep, voffB); PG8_STAGE(PG8_SA(0, 0), a2, voffA);
;             PG8_WAIT_V(8); PG8_WAIT_L(0); PG8_BAR; PG8_MMA(1, 0, At, B0); PG8_MMA(1, 1, At, B1); PG8_BAR; PG8_SCHED;
.LBB0_775:
	s_add_u32 s30, s28, 0xfffc0080
	s_addc_u32 s31, s29, -1
	s_add_i32 s72, 0, 0x10000
	s_cmp_eq_u32 s71, 12
	s_cselect_b32 s35, s19, s31
	s_cselect_b32 s34, s25, s30
	v_add_u32_e32 v138, s72, v141
	s_cselect_b32 s31, s13, s70
	s_cselect_b32 s30, s68, s69
	s_add_i32 s74, 0, 0x14000
	ds_read_b128 v[144:147], v138
	ds_read_b128 v[148:151], v138 offset:1024
	ds_read_b128 v[152:155], v138 offset:2048
	ds_read_b128 v[156:159], v138 offset:3072
	v_add_u32_e32 v138, s74, v141
	ds_read_b128 v[162:165], v138
	ds_read_b128 v[166:169], v138 offset:1024
	ds_read_b128 v[170:173], v138 offset:2048
	ds_read_b128 v[174:177], v138 offset:3072
	v_lshl_add_u64 v[138:139], s[28:29], 0, v[134:135]
	s_add_i32 m0, s27, 0xc000
	ds_read_b128 v[178:181], v143
	ds_read_b128 v[182:185], v143 offset:1024
	ds_read_b128 v[186:189], v143 offset:2048
	ds_read_b128 v[190:193], v143 offset:3072
	ds_read_b128 v[196:199], v143 offset:4096
	ds_read_b128 v[200:203], v143 offset:5120
	ds_read_b128 v[204:207], v143 offset:6144
	ds_read_b128 v[208:211], v143 offset:7168
	global_load_lds_dwordx4 v[138:139], off
	v_lshl_add_u64 v[138:139], s[28:29], 0, v[136:137]
	s_add_i32 m0, s27, 0xe000
	s_nop 0
	global_load_lds_dwordx4 v[138:139], off
	s_waitcnt vmcnt(8)
	s_waitcnt lgkmcnt(0)
	s_barrier
	s_setprio 1
	v_mfma_f32_16x16x32_bf16 v[124:127], v[144:147], v[178:181], v[124:127]
	v_mfma_f32_16x16x32_bf16 v[116:119], v[152:155], v[178:181], v[116:119]
	v_mfma_f32_16x16x32_bf16 v[108:111], v[144:147], v[186:189], v[108:111]
	v_mfma_f32_16x16x32_bf16 v[100:103], v[152:155], v[186:189], v[100:103]
	v_mfma_f32_16x16x32_bf16 v[92:95], v[144:147], v[196:199], v[92:95]
	v_mfma_f32_16x16x32_bf16 v[84:87], v[152:155], v[196:199], v[84:87]
	v_mfma_f32_16x16x32_bf16 v[76:79], v[144:147], v[204:207], v[76:79]
	v_mfma_f32_16x16x32_bf16 v[68:71], v[152:155], v[204:207], v[68:71]
	v_mfma_f32_16x16x32_bf16 v[124:127], v[148:151], v[182:185], v[124:127]
	v_mfma_f32_16x16x32_bf16 v[116:119], v[156:159], v[182:185], v[116:119]
	v_mfma_f32_16x16x32_bf16 v[108:111], v[148:151], v[190:193], v[108:111]
	v_mfma_f32_16x16x32_bf16 v[100:103], v[156:159], v[190:193], v[100:103]
	v_mfma_f32_16x16x32_bf16 v[92:95], v[148:151], v[200:203], v[92:95]
	v_mfma_f32_16x16x32_bf16 v[84:87], v[156:159], v[200:203], v[84:87]
	v_mfma_f32_16x16x32_bf16 v[76:79], v[148:151], v[208:211], v[76:79]
	v_mfma_f32_16x16x32_bf16 v[68:71], v[156:159], v[208:211], v[68:71]
	v_mfma_f32_16x16x32_bf16 v[120:123], v[162:165], v[178:181], v[120:123]
	v_mfma_f32_16x16x32_bf16 v[112:115], v[170:173], v[178:181], v[112:115]
	v_mfma_f32_16x16x32_bf16 v[104:107], v[162:165], v[186:189], v[104:107]
	v_mfma_f32_16x16x32_bf16 v[96:99], v[170:173], v[186:189], v[96:99]
	v_mfma_f32_16x16x32_bf16 v[88:91], v[162:165], v[196:199], v[88:91]
	v_mfma_f32_16x16x32_bf16 v[80:83], v[170:173], v[196:199], v[80:83]
	v_mfma_f32_16x16x32_bf16 v[72:75], v[162:165], v[204:207], v[72:75]
	v_mfma_f32_16x16x32_bf16 v[64:67], v[170:173], v[204:207], v[64:67]
	v_mfma_f32_16x16x32_bf16 v[120:123], v[166:169], v[182:185], v[120:123]
	v_mfma_f32_16x16x32_bf16 v[112:115], v[174:177], v[182:185], v[112:115]
	v_mfma_f32_16x16x32_bf16 v[104:107], v[166:169], v[190:193], v[104:107]
	v_mfma_f32_16x16x32_bf16 v[96:99], v[174:177], v[190:193], v[96:99]
	v_mfma_f32_16x16x32_bf16 v[88:91], v[166:169], v[200:203], v[88:91]
	v_mfma_f32_16x16x32_bf16 v[80:83], v[174:177], v[200:203], v[80:83]
	v_mfma_f32_16x16x32_bf16 v[72:75], v[166:169], v[208:211], v[72:75]
	v_mfma_f32_16x16x32_bf16 v[64:67], v[174:177], v[208:211], v[64:67]
	s_setprio 0
	s_barrier
	s_add_i32 s72, s72, s37
	v_lshl_add_u64 v[138:139], s[30:31], 0, v[160:161]
	s_mov_b32 m0, s72
	ds_read_b128 v[178:181], v143 offset:16384
	ds_read_b128 v[182:185], v143 offset:17408
	ds_read_b128 v[186:189], v143 offset:18432
	ds_read_b128 v[190:193], v143 offset:19456
	ds_read_b128 v[196:199], v143 offset:20480
	ds_read_b128 v[200:203], v143 offset:21504
	ds_read_b128 v[204:207], v143 offset:22528
	ds_read_b128 v[208:211], v143 offset:23552
	global_load_lds_dwordx4 v[138:139], off
	s_add_i32 m0, s72, 0x2000
	s_add_u32 s72, s30, 0x40000
	v_lshl_add_u64 v[212:213], s[30:31], 0, v[128:129]
	s_addc_u32 s73, s31, 0
	s_add_i32 s74, s74, s37
	global_load_lds_dwordx4 v[212:213], off
	v_lshl_add_u64 v[214:215], s[72:73], 0, v[160:161]
	s_mov_b32 m0, s74
	v_lshl_add_u64 v[216:217], s[34:35], 0, v[130:131]
	global_load_lds_dwordx4 v[214:215], off
	v_lshl_add_u64 v[214:215], s[72:73], 0, v[128:129]
	s_add_i32 m0, s74, 0x2000
	s_nop 0
	global_load_lds_dwordx4 v[214:215], off
	v_lshl_add_u64 v[214:215], s[34:35], 0, v[132:133]
	s_mov_b32 m0, s27
	s_nop 0
	global_load_lds_dwordx4 v[214:215], off
	s_mov_b32 m0, s44
	s_nop 0
	global_load_lds_dwordx4 v[216:217], off
	s_waitcnt vmcnt(8)
	s_waitcnt lgkmcnt(0)
	s_barrier
; #define PG8_STAGE(bufoff, gbase, voff) do { _Pragma("unroll") for (int _i = 0; _i < 2; ++_i) \
;         __builtin_amdgcn_global_load_lds((const unsigned*)((const char*)(gbase) + (voff)[_i]), (PG8_LAS unsigned*)(lds + (bufoff) + ldsw + _i * 8192), 16, 0, 0); } while (0)
; #define PG8_LDA(dst, b, h) do { _Pragma("unroll") for (int m = 0; m < 4; ++m) _Pragma("unroll") for (int k = 0; k < 2; ++k) dst[m][k] = *(const PG8_LAS bf16x8*)(lds + PG8_SA(b, h) + aoff + m * 2048 + k * 1024); } while (0)
; #define PG8_LDB(dst, b, h) do { _Pragma("unroll") for (int n = 0; n < 2; ++n) _Pragma("unroll") for (int k = 0; k < 2; ++k) dst[n][k] = *(const PG8_LAS bf16x8*)(lds + PG8_SB(b, h) + boff + n * 2048 + k * 1024); } while (0)
; #define PG8_MMA(ai, bj, At, Bt) do { __builtin_amdgcn_s_setprio(1); _Pragma("unroll") for (int m = 0; m < 4; ++m) _Pragma("unroll") for (int n = 0; n < 2; ++n) _Pragma("unroll") for (int k = 0; k < 2; ++k) \
;         acc[ai][bj][m][n] = __builtin_amdgcn_mfma_f32_16x16x32_bf16(Bt[n][k], At[m][k], acc[ai][bj][m][n], 0, 0, 0); __builtin_amdgcn_s_setprio(0); } while (0)
; #define PG8_WAIT_V(n) asm volatile("s_waitcnt vmcnt(" #n ")" ::: "memory")
; #define PG8_WAIT_L(n) asm volatile("s_waitcnt lgkmcnt(" #n ")" ::: "memory")
; #define PG8_BAR __builtin_amdgcn_s_barrier()
; #define PG8_SCHED __builtin_amdgcn_sched_barrier(0)
; template <class Epi, class Sched, bool ALIGN_EPI = false, bool SP2 = false>
; __device__ __forceinline__ void gemm_phase(PG8_LAS unsigned char* lds, const Gemm g, const Sched& S, const Epi& E) {
;     ...
;             PG8_WAIT_V(8); PG8_WAIT_L(0); PG8_BAR; PG8_MMA(1, 0, At, B0); PG8_MMA(1, 1, At, B1); PG8_BAR; PG8_SCHED;
;             PG8_LDB(B0, 1, 0); PG8_LDB(B1, 1, 1); PG8_SCHED; PG8_LDA(At, 1, 0); PG8_STAGE(PG8_SA(0, 1), a2 + hstep, voffA);
;             PG8_WAIT_V(8); PG8_WAIT_L(0); PG8_BAR; PG8_MMA(0, 0, At, B0); PG8_MMA(0, 1, At, B1); PG8_BAR; PG8_SCHED;
	s_setprio 1
	v_mfma_f32_16x16x32_bf16 v[60:63], v[144:147], v[178:181], v[60:63]
	v_mfma_f32_16x16x32_bf16 v[52:55], v[152:155], v[178:181], v[52:55]
	v_mfma_f32_16x16x32_bf16 v[44:47], v[144:147], v[186:189], v[44:47]
	v_mfma_f32_16x16x32_bf16 v[36:39], v[152:155], v[186:189], v[36:39]
	v_mfma_f32_16x16x32_bf16 v[28:31], v[144:147], v[196:199], v[28:31]
	v_mfma_f32_16x16x32_bf16 v[20:23], v[152:155], v[196:199], v[20:23]
	v_mfma_f32_16x16x32_bf16 v[12:15], v[144:147], v[204:207], v[12:15]
	v_mfma_f32_16x16x32_bf16 v[4:7], v[152:155], v[204:207], v[4:7]
	v_mfma_f32_16x16x32_bf16 v[60:63], v[148:151], v[182:185], v[60:63]
	v_mfma_f32_16x16x32_bf16 v[52:55], v[156:159], v[182:185], v[52:55]
	v_mfma_f32_16x16x32_bf16 v[44:47], v[148:151], v[190:193], v[44:47]
	v_mfma_f32_16x16x32_bf16 v[36:39], v[156:159], v[190:193], v[36:39]
	v_mfma_f32_16x16x32_bf16 v[28:31], v[148:151], v[200:203], v[28:31]
	v_mfma_f32_16x16x32_bf16 v[20:23], v[156:159], v[200:203], v[20:23]
	v_mfma_f32_16x16x32_bf16 v[12:15], v[148:151], v[208:211], v[12:15]
	v_mfma_f32_16x16x32_bf16 v[4:7], v[156:159], v[208:211], v[4:7]
	v_mfma_f32_16x16x32_bf16 v[56:59], v[162:165], v[178:181], v[56:59]
	v_mfma_f32_16x16x32_bf16 v[48:51], v[170:173], v[178:181], v[48:51]
	v_mfma_f32_16x16x32_bf16 v[40:43], v[162:165], v[186:189], v[40:43]
	v_mfma_f32_16x16x32_bf16 v[32:35], v[170:173], v[186:189], v[32:35]
	v_mfma_f32_16x16x32_bf16 v[24:27], v[162:165], v[196:199], v[24:27]
	v_mfma_f32_16x16x32_bf16 v[16:19], v[170:173], v[196:199], v[16:19]
	v_mfma_f32_16x16x32_bf16 v[8:11], v[162:165], v[204:207], v[8:11]
	v_mfma_f32_16x16x32_bf16 v[0:3], v[170:173], v[204:207], v[0:3]
	v_mfma_f32_16x16x32_bf16 v[56:59], v[166:169], v[182:185], v[56:59]
	v_mfma_f32_16x16x32_bf16 v[48:51], v[174:177], v[182:185], v[48:51]
	v_mfma_f32_16x16x32_bf16 v[40:43], v[166:169], v[190:193], v[40:43]
	v_mfma_f32_16x16x32_bf16 v[32:35], v[174:177], v[190:193], v[32:35]
	v_mfma_f32_16x16x32_bf16 v[24:27], v[166:169], v[200:203], v[24:27]
	v_mfma_f32_16x16x32_bf16 v[16:19], v[174:177], v[200:203], v[16:19]
	v_mfma_f32_16x16x32_bf16 v[8:11], v[166:169], v[208:211], v[8:11]
	v_mfma_f32_16x16x32_bf16 v[0:3], v[174:177], v[208:211], v[0:3]
	s_setprio 0
	s_barrier
	s_add_i32 s72, 0, 0x18000
	s_add_i32 s73, 0, 0x1c000
	v_add_u32_e32 v156, s72, v141
	v_add_u32_e32 v174, s73, v141
	ds_read_b128 v[144:147], v156
	ds_read_b128 v[148:151], v156 offset:1024
	ds_read_b128 v[152:155], v156 offset:2048
	ds_read_b128 v[156:159], v156 offset:3072
	ds_read_b128 v[162:165], v174
	ds_read_b128 v[166:169], v174 offset:1024
	ds_read_b128 v[170:173], v174 offset:2048
	ds_read_b128 v[174:177], v174 offset:3072
	s_add_u32 s34, s34, 0x40000
	s_addc_u32 s35, s35, 0
	s_mov_b32 m0, s45
	v_lshl_add_u64 v[228:229], s[34:35], 0, v[132:133]
	ds_read_b128 v[178:181], v143 offset:32768
	ds_read_b128 v[182:185], v143 offset:33792
	ds_read_b128 v[186:189], v143 offset:34816
	ds_read_b128 v[190:193], v143 offset:35840
	ds_read_b128 v[196:199], v143 offset:36864
	ds_read_b128 v[200:203], v143 offset:37888
	ds_read_b128 v[204:207], v143 offset:38912
	ds_read_b128 v[208:211], v143 offset:39936
	global_load_lds_dwordx4 v[228:229], off
	v_lshl_add_u64 v[228:229], s[34:35], 0, v[130:131]
	s_mov_b32 m0, s46
	s_nop 0
	global_load_lds_dwordx4 v[228:229], off
	s_waitcnt vmcnt(8)
	s_waitcnt lgkmcnt(0)
	s_barrier
	s_setprio 1
	v_mfma_f32_16x16x32_bf16 v[124:127], v[144:147], v[178:181], v[124:127]
	v_mfma_f32_16x16x32_bf16 v[116:119], v[152:155], v[178:181], v[116:119]
	v_mfma_f32_16x16x32_bf16 v[108:111], v[144:147], v[186:189], v[108:111]
	v_mfma_f32_16x16x32_bf16 v[100:103], v[152:155], v[186:189], v[100:103]
	v_mfma_f32_16x16x32_bf16 v[92:95], v[144:147], v[196:199], v[92:95]
	v_mfma_f32_16x16x32_bf16 v[84:87], v[152:155], v[196:199], v[84:87]
	v_mfma_f32_16x16x32_bf16 v[76:79], v[144:147], v[204:207], v[76:79]
	v_mfma_f32_16x16x32_bf16 v[68:71], v[152:155], v[204:207], v[68:71]
	v_mfma_f32_16x16x32_bf16 v[124:127], v[148:151], v[182:185], v[124:127]
	v_mfma_f32_16x16x32_bf16 v[116:119], v[156:159], v[182:185], v[116:119]
	v_mfma_f32_16x16x32_bf16 v[108:111], v[148:151], v[190:193], v[108:111]
	v_mfma_f32_16x16x32_bf16 v[100:103], v[156:159], v[190:193], v[100:103]
	v_mfma_f32_16x16x32_bf16 v[92:95], v[148:151], v[200:203], v[92:95]
	v_mfma_f32_16x16x32_bf16 v[84:87], v[156:159], v[200:203], v[84:87]
	v_mfma_f32_16x16x32_bf16 v[76:79], v[148:151], v[208:211], v[76:79]
	v_mfma_f32_16x16x32_bf16 v[68:71], v[156:159], v[208:211], v[68:71]
	v_mfma_f32_16x16x32_bf16 v[120:123], v[162:165], v[178:181], v[120:123]
	v_mfma_f32_16x16x32_bf16 v[112:115], v[170:173], v[178:181], v[112:115]
	v_mfma_f32_16x16x32_bf16 v[104:107], v[162:165], v[186:189], v[104:107]
	v_mfma_f32_16x16x32_bf16 v[96:99], v[170:173], v[186:189], v[96:99]
	v_mfma_f32_16x16x32_bf16 v[88:91], v[162:165], v[196:199], v[88:91]
	v_mfma_f32_16x16x32_bf16 v[80:83], v[170:173], v[196:199], v[80:83]
	v_mfma_f32_16x16x32_bf16 v[72:75], v[162:165], v[204:207], v[72:75]
	v_mfma_f32_16x16x32_bf16 v[64:67], v[170:173], v[204:207], v[64:67]
	v_mfma_f32_16x16x32_bf16 v[120:123], v[166:169], v[182:185], v[120:123]
	v_mfma_f32_16x16x32_bf16 v[112:115], v[174:177], v[182:185], v[112:115]
	v_mfma_f32_16x16x32_bf16 v[104:107], v[166:169], v[190:193], v[104:107]
	v_mfma_f32_16x16x32_bf16 v[96:99], v[174:177], v[190:193], v[96:99]
	v_mfma_f32_16x16x32_bf16 v[88:91], v[166:169], v[200:203], v[88:91]
	v_mfma_f32_16x16x32_bf16 v[80:83], v[174:177], v[200:203], v[80:83]
	v_mfma_f32_16x16x32_bf16 v[72:75], v[166:169], v[208:211], v[72:75]
	v_mfma_f32_16x16x32_bf16 v[64:67], v[174:177], v[208:211], v[64:67]
	s_setprio 0
	s_barrier
; #define PG8_STAGE(bufoff, gbase, voff) do { _Pragma("unroll") for (int _i = 0; _i < 2; ++_i) \
;         __builtin_amdgcn_global_load_lds((const unsigned*)((const char*)(gbase) + (voff)[_i]), (PG8_LAS unsigned*)(lds + (bufoff) + ldsw + _i * 8192), 16, 0, 0); } while (0)
; #define PG8_LDA(dst, b, h) do { _Pragma("unroll") for (int m = 0; m < 4; ++m) _Pragma("unroll") for (int k = 0; k < 2; ++k) dst[m][k] = *(const PG8_LAS bf16x8*)(lds + PG8_SA(b, h) + aoff + m * 2048 + k * 1024); } while (0)
; #define PG8_MMA(ai, bj, At, Bt) do { __builtin_amdgcn_s_setprio(1); _Pragma("unroll") for (int m = 0; m < 4; ++m) _Pragma("unroll") for (int n = 0; n < 2; ++n) _Pragma("unroll") for (int k = 0; k < 2; ++k) \
;         acc[ai][bj][m][n] = __builtin_amdgcn_mfma_f32_16x16x32_bf16(Bt[n][k], At[m][k], acc[ai][bj][m][n], 0, 0, 0); __builtin_amdgcn_s_setprio(0); } while (0)
; #define PG8_WAIT_V(n) asm volatile("s_waitcnt vmcnt(" #n ")" ::: "memory")
; #define PG8_WAIT_L(n) asm volatile("s_waitcnt lgkmcnt(" #n ")" ::: "memory")
; #define PG8_BAR __builtin_amdgcn_s_barrier()
; #define PG8_SCHED __builtin_amdgcn_sched_barrier(0)
; template <class Epi, class Sched, bool ALIGN_EPI = false, bool SP2 = false>
; __device__ __forceinline__ void gemm_phase(PG8_LAS unsigned char* lds, const Gemm g, const Sched& S, const Epi& E) {
;     ...
;             PG8_LDA(At, 1, 1); PG8_STAGE(PG8_SB(1, 0), b3, voffB); PG8_STAGE(PG8_SB(1, 1), b3 + hstep, voffB); PG8_STAGE(PG8_SA(1, 0), a3, voffA);
;             PG8_WAIT_V(8); PG8_WAIT_L(0); PG8_BAR; PG8_MMA(1, 0, At, B0); PG8_MMA(1, 1, At, B1); PG8_BAR; PG8_SCHED;
	s_add_i32 s34, s72, s37
	v_lshl_add_u64 v[138:139], v[138:139], 0, s[42:43]
	s_mov_b32 m0, s34
	ds_read_b128 v[178:181], v143 offset:49152
	ds_read_b128 v[182:185], v143 offset:50176
	ds_read_b128 v[186:189], v143 offset:51200
	ds_read_b128 v[190:193], v143 offset:52224
	ds_read_b128 v[196:199], v143 offset:53248
	ds_read_b128 v[200:203], v143 offset:54272
	ds_read_b128 v[204:207], v143 offset:55296
	ds_read_b128 v[208:211], v143 offset:56320
	global_load_lds_dwordx4 v[138:139], off
	s_add_i32 m0, s34, 0x2000
	s_add_u32 s30, s30, 0x40080
	v_lshl_add_u64 v[138:139], v[212:213], 0, s[42:43]
	s_addc_u32 s31, s31, 0
	s_add_i32 s34, s73, s37
	global_load_lds_dwordx4 v[138:139], off
	v_lshl_add_u64 v[138:139], s[30:31], 0, v[160:161]
	s_mov_b32 m0, s34
	s_nop 0
	global_load_lds_dwordx4 v[138:139], off
	v_lshl_add_u64 v[138:139], s[30:31], 0, v[128:129]
	s_add_i32 m0, s34, 0x2000
	s_nop 0
	global_load_lds_dwordx4 v[138:139], off
	v_lshl_add_u64 v[138:139], v[214:215], 0, s[42:43]
	s_mov_b32 m0, s47
	s_nop 0
	global_load_lds_dwordx4 v[138:139], off
	v_lshl_add_u64 v[138:139], v[216:217], 0, s[42:43]
	s_mov_b32 m0, s66
	s_nop 0
	global_load_lds_dwordx4 v[138:139], off
	s_waitcnt vmcnt(8)
	s_waitcnt lgkmcnt(0)
	s_barrier
	s_setprio 1
	v_mfma_f32_16x16x32_bf16 v[60:63], v[144:147], v[178:181], v[60:63]
	v_mfma_f32_16x16x32_bf16 v[52:55], v[152:155], v[178:181], v[52:55]
	v_mfma_f32_16x16x32_bf16 v[44:47], v[144:147], v[186:189], v[44:47]
	v_mfma_f32_16x16x32_bf16 v[36:39], v[152:155], v[186:189], v[36:39]
	v_mfma_f32_16x16x32_bf16 v[28:31], v[144:147], v[196:199], v[28:31]
	v_mfma_f32_16x16x32_bf16 v[20:23], v[152:155], v[196:199], v[20:23]
	v_mfma_f32_16x16x32_bf16 v[12:15], v[144:147], v[204:207], v[12:15]
	v_mfma_f32_16x16x32_bf16 v[4:7], v[152:155], v[204:207], v[4:7]
	v_mfma_f32_16x16x32_bf16 v[60:63], v[148:151], v[182:185], v[60:63]
	v_mfma_f32_16x16x32_bf16 v[52:55], v[156:159], v[182:185], v[52:55]
	v_mfma_f32_16x16x32_bf16 v[44:47], v[148:151], v[190:193], v[44:47]
	v_mfma_f32_16x16x32_bf16 v[36:39], v[156:159], v[190:193], v[36:39]
	v_mfma_f32_16x16x32_bf16 v[28:31], v[148:151], v[200:203], v[28:31]
	v_mfma_f32_16x16x32_bf16 v[20:23], v[156:159], v[200:203], v[20:23]
	v_mfma_f32_16x16x32_bf16 v[12:15], v[148:151], v[208:211], v[12:15]
	v_mfma_f32_16x16x32_bf16 v[4:7], v[156:159], v[208:211], v[4:7]
	v_mfma_f32_16x16x32_bf16 v[56:59], v[162:165], v[178:181], v[56:59]
	v_mfma_f32_16x16x32_bf16 v[48:51], v[170:173], v[178:181], v[48:51]
	v_mfma_f32_16x16x32_bf16 v[40:43], v[162:165], v[186:189], v[40:43]
	v_mfma_f32_16x16x32_bf16 v[32:35], v[170:173], v[186:189], v[32:35]
	v_mfma_f32_16x16x32_bf16 v[24:27], v[162:165], v[196:199], v[24:27]
	v_mfma_f32_16x16x32_bf16 v[16:19], v[170:173], v[196:199], v[16:19]
	v_mfma_f32_16x16x32_bf16 v[8:11], v[162:165], v[204:207], v[8:11]
	v_mfma_f32_16x16x32_bf16 v[0:3], v[170:173], v[204:207], v[0:3]
	v_mfma_f32_16x16x32_bf16 v[56:59], v[166:169], v[182:185], v[56:59]
	v_mfma_f32_16x16x32_bf16 v[48:51], v[174:177], v[182:185], v[48:51]
	v_mfma_f32_16x16x32_bf16 v[40:43], v[166:169], v[190:193], v[40:43]
	v_mfma_f32_16x16x32_bf16 v[32:35], v[174:177], v[190:193], v[32:35]
	v_mfma_f32_16x16x32_bf16 v[24:27], v[166:169], v[200:203], v[24:27]
	v_mfma_f32_16x16x32_bf16 v[16:19], v[174:177], v[200:203], v[16:19]
	v_mfma_f32_16x16x32_bf16 v[8:11], v[166:169], v[208:211], v[8:11]
	v_mfma_f32_16x16x32_bf16 v[0:3], v[174:177], v[208:211], v[0:3]
	s_setprio 0
	s_barrier
	s_add_i32 s71, s71, 2
	s_add_u32 s28, s28, 0x100
	s_addc_u32 s29, s29, 0
	s_add_u32 s69, s69, 0x100
	s_addc_u32 s70, s70, 0
	s_cmp_gt_u32 s71, 13
	s_cbranch_scc0 .LBB0_775
	s_and_b64 vcc, exec, s[10:11]
	s_cbranch_vccz .LBB0_778
	s_barrier

; #define PG8_STAGE(bufoff, gbase, voff) do { _Pragma("unroll") for (int _i = 0; _i < 2; ++_i) \
;         __builtin_amdgcn_global_load_lds((const unsigned*)((const char*)(gbase) + (voff)[_i]), (PG8_LAS unsigned*)(lds + (bufoff) + ldsw + _i * 8192), 16, 0, 0); } while (0)
; #define PG8_LDA(dst, b, h) do { _Pragma("unroll") for (int m = 0; m < 4; ++m) _Pragma("unroll") for (int k = 0; k < 2; ++k) dst[m][k] = *(const PG8_LAS bf16x8*)(lds + PG8_SA(b, h) + aoff + m * 2048 + k * 1024); } while (0)
; #define PG8_LDB(dst, b, h) do { _Pragma("unroll") for (int n = 0; n < 2; ++n) _Pragma("unroll") for (int k = 0; k < 2; ++k) dst[n][k] = *(const PG8_LAS bf16x8*)(lds + PG8_SB(b, h) + boff + n * 2048 + k * 1024); } while (0)
; #define PG8_MMA(ai, bj, At, Bt) do { __builtin_amdgcn_s_setprio(1); _Pragma("unroll") for (int m = 0; m < 4; ++m) _Pragma("unroll") for (int n = 0; n < 2; ++n) _Pragma("unroll") for (int k = 0; k < 2; ++k) \
;         acc[ai][bj][m][n] = __builtin_amdgcn_mfma_f32_16x16x32_bf16(Bt[n][k], At[m][k], acc[ai][bj][m][n], 0, 0, 0); __builtin_amdgcn_s_setprio(0); } while (0)
; #define PG8_WAIT_V(n) asm volatile("s_waitcnt vmcnt(" #n ")" ::: "memory")
; #define PG8_BAR __builtin_amdgcn_s_barrier()
; template <class Epi, class Sched, bool ALIGN_EPI = false, bool SP2 = false>
; __device__ __forceinline__ void gemm_phase(PG8_LAS unsigned char* lds, const Gemm g, const Sched& S, const Epi& E) {
;     ...
;         for (int t = 0; t < nt; t += 2) {
;             const bool last = (t == nt - 2);
;             const char* a1 = cA + (size_t)(t + 1) * kstep;
;             const char* a2 = last ? nA : cA + (size_t)(t + 2) * kstep; const char* b2 = last ? nB : cB + (size_t)(t + 2) * kstep;
;             const char* a3 = a2 + kstep; const char* b3 = b2 + kstep;
;             if (last && has_next) S.a_ready(nxt);
;             if constexpr (SP2) {
;             PG8_LDB(B0, 0, 0); PG8_LDB(B1, 0, 1); PG8_SCHED; PG8_LDA(At, 0, 0); PG8_STAGE(PG8_SA(1, 1), a1 + hstep, voffA);
;             PG8_WAIT_V(8); PG8_WAIT_L(0); PG8_BAR; PG8_MMA(0, 0, At, B0); PG8_MMA(0, 1, At, B1); PG8_BAR; PG8_SCHED;
;             PG8_LDA(At, 0, 1); PG8_STAGE(PG8_SB(0, 0), b2, voffB); PG8_STAGE(PG8_SB(0, 1), b2 + hstep, voffB); PG8_STAGE(PG8_SA(0, 0), a2, voffA);
;             PG8_WAIT_V(8); PG8_WAIT_L(0); PG8_BAR; PG8_MMA(1, 0, At, B0); PG8_MMA(1, 1, At, B1); PG8_BAR; PG8_SCHED;
.LBB0_851:
	s_add_u32 s18, s16, 0x100
	s_addc_u32 s19, s17, 0
	s_add_i32 s45, 0, 0x10000
	s_cmp_eq_u32 s44, 40
	s_cselect_b32 s23, s7, s19
	s_cselect_b32 s22, s6, s18
	s_cselect_b32 s21, s13, s41
	s_cselect_b32 s20, s12, s40
	s_add_i32 s46, 0, 0x14000
	v_add_u32_e32 v154, s45, v139
	v_add_u32_e32 v158, s46, v139
	ds_read_b128 v[142:145], v154
	ds_read_b128 v[146:149], v154 offset:1024
	ds_read_b128 v[150:153], v154 offset:2048
	ds_read_b128 v[154:157], v154 offset:3072
	ds_read_b128 v[162:165], v158
	ds_read_b128 v[166:169], v158 offset:1024
	ds_read_b128 v[170:173], v158 offset:2048
	ds_read_b128 v[174:177], v158 offset:3072
	v_lshl_add_u64 v[158:159], s[16:17], 0, v[134:135]
	s_add_i32 m0, s26, 0xc000
	ds_read_b128 v[178:181], v141
	ds_read_b128 v[182:185], v141 offset:1024
	ds_read_b128 v[186:189], v141 offset:2048
	ds_read_b128 v[190:193], v141 offset:3072
	ds_read_b128 v[196:199], v141 offset:4096
	ds_read_b128 v[200:203], v141 offset:5120
	ds_read_b128 v[204:207], v141 offset:6144
	ds_read_b128 v[208:211], v141 offset:7168
	global_load_lds_dwordx4 v[158:159], off
	v_lshl_add_u64 v[158:159], s[16:17], 0, v[136:137]
	s_add_i32 m0, s26, 0xe000
	s_nop 0
	global_load_lds_dwordx4 v[158:159], off
	s_waitcnt vmcnt(8)
	s_waitcnt lgkmcnt(0)
	s_barrier
	s_setprio 1
	v_mfma_f32_16x16x32_bf16 v[124:127], v[142:145], v[178:181], v[124:127]
	v_mfma_f32_16x16x32_bf16 v[120:123], v[150:153], v[178:181], v[120:123]
	v_mfma_f32_16x16x32_bf16 v[116:119], v[142:145], v[186:189], v[116:119]
	v_mfma_f32_16x16x32_bf16 v[112:115], v[150:153], v[186:189], v[112:115]
	v_mfma_f32_16x16x32_bf16 v[100:103], v[142:145], v[196:199], v[100:103]
	v_mfma_f32_16x16x32_bf16 v[96:99], v[150:153], v[196:199], v[96:99]
	v_mfma_f32_16x16x32_bf16 v[84:87], v[142:145], v[204:207], v[84:87]
	v_mfma_f32_16x16x32_bf16 v[80:83], v[150:153], v[204:207], v[80:83]
	v_mfma_f32_16x16x32_bf16 v[124:127], v[146:149], v[182:185], v[124:127]
	v_mfma_f32_16x16x32_bf16 v[120:123], v[154:157], v[182:185], v[120:123]
	v_mfma_f32_16x16x32_bf16 v[116:119], v[146:149], v[190:193], v[116:119]
	v_mfma_f32_16x16x32_bf16 v[112:115], v[154:157], v[190:193], v[112:115]
	v_mfma_f32_16x16x32_bf16 v[100:103], v[146:149], v[200:203], v[100:103]
	v_mfma_f32_16x16x32_bf16 v[96:99], v[154:157], v[200:203], v[96:99]
	v_mfma_f32_16x16x32_bf16 v[84:87], v[146:149], v[208:211], v[84:87]
	v_mfma_f32_16x16x32_bf16 v[80:83], v[154:157], v[208:211], v[80:83]
	v_mfma_f32_16x16x32_bf16 v[108:111], v[162:165], v[178:181], v[108:111]
	v_mfma_f32_16x16x32_bf16 v[104:107], v[170:173], v[178:181], v[104:107]
	v_mfma_f32_16x16x32_bf16 v[92:95], v[162:165], v[186:189], v[92:95]
	v_mfma_f32_16x16x32_bf16 v[88:91], v[170:173], v[186:189], v[88:91]
	v_mfma_f32_16x16x32_bf16 v[76:79], v[162:165], v[196:199], v[76:79]
	v_mfma_f32_16x16x32_bf16 v[72:75], v[170:173], v[196:199], v[72:75]
	v_mfma_f32_16x16x32_bf16 v[68:71], v[162:165], v[204:207], v[68:71]
	v_mfma_f32_16x16x32_bf16 v[64:67], v[170:173], v[204:207], v[64:67]
	v_mfma_f32_16x16x32_bf16 v[108:111], v[166:169], v[182:185], v[108:111]
	v_mfma_f32_16x16x32_bf16 v[104:107], v[174:177], v[182:185], v[104:107]
	v_mfma_f32_16x16x32_bf16 v[92:95], v[166:169], v[190:193], v[92:95]
	v_mfma_f32_16x16x32_bf16 v[88:91], v[174:177], v[190:193], v[88:91]
	v_mfma_f32_16x16x32_bf16 v[76:79], v[166:169], v[200:203], v[76:79]
	v_mfma_f32_16x16x32_bf16 v[72:75], v[174:177], v[200:203], v[72:75]
	v_mfma_f32_16x16x32_bf16 v[68:71], v[166:169], v[208:211], v[68:71]
	v_mfma_f32_16x16x32_bf16 v[64:67], v[174:177], v[208:211], v[64:67]
	s_setprio 0
	s_barrier
	s_add_i32 s16, s45, s2
	v_lshl_add_u64 v[158:159], s[20:21], 0, v[160:161]
	s_mov_b32 m0, s16
	ds_read_b128 v[178:181], v141 offset:16384
	ds_read_b128 v[182:185], v141 offset:17408
	ds_read_b128 v[186:189], v141 offset:18432
	ds_read_b128 v[190:193], v141 offset:19456
	ds_read_b128 v[196:199], v141 offset:20480
	ds_read_b128 v[200:203], v141 offset:21504
	ds_read_b128 v[204:207], v141 offset:22528
	ds_read_b128 v[208:211], v141 offset:23552
	global_load_lds_dwordx4 v[158:159], off
	s_add_i32 m0, s16, 0x2000
	s_add_u32 s16, s20, 0xb0000
	v_lshl_add_u64 v[212:213], s[20:21], 0, v[128:129]
	s_addc_u32 s17, s21, 0
	s_add_i32 s45, s46, s2
	global_load_lds_dwordx4 v[212:213], off
	v_lshl_add_u64 v[214:215], s[16:17], 0, v[160:161]
	s_mov_b32 m0, s45
	v_lshl_add_u64 v[216:217], s[22:23], 0, v[130:131]
	global_load_lds_dwordx4 v[214:215], off
	v_lshl_add_u64 v[214:215], s[16:17], 0, v[128:129]
	s_add_i32 m0, s45, 0x2000
	s_nop 0
	global_load_lds_dwordx4 v[214:215], off
	v_lshl_add_u64 v[214:215], s[22:23], 0, v[132:133]
	s_mov_b32 m0, s26
	s_nop 0
	global_load_lds_dwordx4 v[214:215], off
	s_mov_b32 m0, s27
	s_nop 0
	global_load_lds_dwordx4 v[216:217], off
	s_waitcnt vmcnt(8)
	s_waitcnt lgkmcnt(0)
	s_barrier
; #define PG8_STAGE(bufoff, gbase, voff) do { _Pragma("unroll") for (int _i = 0; _i < 2; ++_i) \
;         __builtin_amdgcn_global_load_lds((const unsigned*)((const char*)(gbase) + (voff)[_i]), (PG8_LAS unsigned*)(lds + (bufoff) + ldsw + _i * 8192), 16, 0, 0); } while (0)
; #define PG8_LDA(dst, b, h) do { _Pragma("unroll") for (int m = 0; m < 4; ++m) _Pragma("unroll") for (int k = 0; k < 2; ++k) dst[m][k] = *(const PG8_LAS bf16x8*)(lds + PG8_SA(b, h) + aoff + m * 2048 + k * 1024); } while (0)
; #define PG8_LDB(dst, b, h) do { _Pragma("unroll") for (int n = 0; n < 2; ++n) _Pragma("unroll") for (int k = 0; k < 2; ++k) dst[n][k] = *(const PG8_LAS bf16x8*)(lds + PG8_SB(b, h) + boff + n * 2048 + k * 1024); } while (0)
; #define PG8_MMA(ai, bj, At, Bt) do { __builtin_amdgcn_s_setprio(1); _Pragma("unroll") for (int m = 0; m < 4; ++m) _Pragma("unroll") for (int n = 0; n < 2; ++n) _Pragma("unroll") for (int k = 0; k < 2; ++k) \
;         acc[ai][bj][m][n] = __builtin_amdgcn_mfma_f32_16x16x32_bf16(Bt[n][k], At[m][k], acc[ai][bj][m][n], 0, 0, 0); __builtin_amdgcn_s_setprio(0); } while (0)
; #define PG8_WAIT_V(n) asm volatile("s_waitcnt vmcnt(" #n ")" ::: "memory")
; #define PG8_WAIT_L(n) asm volatile("s_waitcnt lgkmcnt(" #n ")" ::: "memory")
; #define PG8_BAR __builtin_amdgcn_s_barrier()
; #define PG8_SCHED __builtin_amdgcn_sched_barrier(0)
; template <class Epi, class Sched, bool ALIGN_EPI = false, bool SP2 = false>
; __device__ __forceinline__ void gemm_phase(PG8_LAS unsigned char* lds, const Gemm g, const Sched& S, const Epi& E) {
;     ...
;             PG8_WAIT_V(8); PG8_WAIT_L(0); PG8_BAR; PG8_MMA(1, 0, At, B0); PG8_MMA(1, 1, At, B1); PG8_BAR; PG8_SCHED;
;             PG8_LDB(B0, 1, 0); PG8_LDB(B1, 1, 1); PG8_SCHED; PG8_LDA(At, 1, 0); PG8_STAGE(PG8_SA(0, 1), a2 + hstep, voffA);
;             PG8_WAIT_V(8); PG8_WAIT_L(0); PG8_BAR; PG8_MMA(0, 0, At, B0); PG8_MMA(0, 1, At, B1); PG8_BAR; PG8_SCHED;
	s_setprio 1
	v_mfma_f32_16x16x32_bf16 v[60:63], v[142:145], v[178:181], v[60:63]
	v_mfma_f32_16x16x32_bf16 v[56:59], v[150:153], v[178:181], v[56:59]
	v_mfma_f32_16x16x32_bf16 v[52:55], v[142:145], v[186:189], v[52:55]
	v_mfma_f32_16x16x32_bf16 v[48:51], v[150:153], v[186:189], v[48:51]
	v_mfma_f32_16x16x32_bf16 v[36:39], v[142:145], v[196:199], v[36:39]
	v_mfma_f32_16x16x32_bf16 v[32:35], v[150:153], v[196:199], v[32:35]
	v_mfma_f32_16x16x32_bf16 v[20:23], v[142:145], v[204:207], v[20:23]
	v_mfma_f32_16x16x32_bf16 v[16:19], v[150:153], v[204:207], v[16:19]
	v_mfma_f32_16x16x32_bf16 v[60:63], v[146:149], v[182:185], v[60:63]
	v_mfma_f32_16x16x32_bf16 v[56:59], v[154:157], v[182:185], v[56:59]
	v_mfma_f32_16x16x32_bf16 v[52:55], v[146:149], v[190:193], v[52:55]
	v_mfma_f32_16x16x32_bf16 v[48:51], v[154:157], v[190:193], v[48:51]
	v_mfma_f32_16x16x32_bf16 v[36:39], v[146:149], v[200:203], v[36:39]
	v_mfma_f32_16x16x32_bf16 v[32:35], v[154:157], v[200:203], v[32:35]
	v_mfma_f32_16x16x32_bf16 v[20:23], v[146:149], v[208:211], v[20:23]
	v_mfma_f32_16x16x32_bf16 v[16:19], v[154:157], v[208:211], v[16:19]
	v_mfma_f32_16x16x32_bf16 v[44:47], v[162:165], v[178:181], v[44:47]
	v_mfma_f32_16x16x32_bf16 v[40:43], v[170:173], v[178:181], v[40:43]
	v_mfma_f32_16x16x32_bf16 v[28:31], v[162:165], v[186:189], v[28:31]
	v_mfma_f32_16x16x32_bf16 v[24:27], v[170:173], v[186:189], v[24:27]
	v_mfma_f32_16x16x32_bf16 v[12:15], v[162:165], v[196:199], v[12:15]
	v_mfma_f32_16x16x32_bf16 v[8:11], v[170:173], v[196:199], v[8:11]
	v_mfma_f32_16x16x32_bf16 v[4:7], v[162:165], v[204:207], v[4:7]
	v_mfma_f32_16x16x32_bf16 v[0:3], v[170:173], v[204:207], v[0:3]
	v_mfma_f32_16x16x32_bf16 v[44:47], v[166:169], v[182:185], v[44:47]
	v_mfma_f32_16x16x32_bf16 v[40:43], v[174:177], v[182:185], v[40:43]
	v_mfma_f32_16x16x32_bf16 v[28:31], v[166:169], v[190:193], v[28:31]
	v_mfma_f32_16x16x32_bf16 v[24:27], v[174:177], v[190:193], v[24:27]
	v_mfma_f32_16x16x32_bf16 v[12:15], v[166:169], v[200:203], v[12:15]
	v_mfma_f32_16x16x32_bf16 v[8:11], v[174:177], v[200:203], v[8:11]
	v_mfma_f32_16x16x32_bf16 v[4:7], v[166:169], v[208:211], v[4:7]
	v_mfma_f32_16x16x32_bf16 v[0:3], v[174:177], v[208:211], v[0:3]
	s_setprio 0
	s_barrier
	s_add_i32 s45, 0, 0x18000
	s_add_i32 s46, 0, 0x1c000
	v_add_u32_e32 v154, s45, v139
	v_add_u32_e32 v174, s46, v139
	ds_read_b128 v[142:145], v154
	ds_read_b128 v[146:149], v154 offset:1024
	ds_read_b128 v[150:153], v154 offset:2048
	ds_read_b128 v[154:157], v154 offset:3072
	ds_read_b128 v[162:165], v174
	ds_read_b128 v[166:169], v174 offset:1024
	ds_read_b128 v[170:173], v174 offset:2048
	ds_read_b128 v[174:177], v174 offset:3072
	s_add_u32 s16, s22, 0xb0000
	s_addc_u32 s17, s23, 0
	s_mov_b32 m0, s28
	v_lshl_add_u64 v[228:229], s[16:17], 0, v[132:133]
	ds_read_b128 v[178:181], v141 offset:32768
	ds_read_b128 v[182:185], v141 offset:33792
	ds_read_b128 v[186:189], v141 offset:34816
	ds_read_b128 v[190:193], v141 offset:35840
	ds_read_b128 v[196:199], v141 offset:36864
	ds_read_b128 v[200:203], v141 offset:37888
	ds_read_b128 v[204:207], v141 offset:38912
	ds_read_b128 v[208:211], v141 offset:39936
	global_load_lds_dwordx4 v[228:229], off
	v_lshl_add_u64 v[228:229], s[16:17], 0, v[130:131]
	s_mov_b32 m0, s29
	s_nop 0
	global_load_lds_dwordx4 v[228:229], off
	s_waitcnt vmcnt(8)
	s_waitcnt lgkmcnt(0)
	s_barrier
	s_setprio 1
	v_mfma_f32_16x16x32_bf16 v[124:127], v[142:145], v[178:181], v[124:127]
	v_mfma_f32_16x16x32_bf16 v[120:123], v[150:153], v[178:181], v[120:123]
	v_mfma_f32_16x16x32_bf16 v[116:119], v[142:145], v[186:189], v[116:119]
	v_mfma_f32_16x16x32_bf16 v[112:115], v[150:153], v[186:189], v[112:115]
	v_mfma_f32_16x16x32_bf16 v[100:103], v[142:145], v[196:199], v[100:103]
	v_mfma_f32_16x16x32_bf16 v[96:99], v[150:153], v[196:199], v[96:99]
	v_mfma_f32_16x16x32_bf16 v[84:87], v[142:145], v[204:207], v[84:87]
	v_mfma_f32_16x16x32_bf16 v[80:83], v[150:153], v[204:207], v[80:83]
	v_mfma_f32_16x16x32_bf16 v[124:127], v[146:149], v[182:185], v[124:127]
	v_mfma_f32_16x16x32_bf16 v[120:123], v[154:157], v[182:185], v[120:123]
	v_mfma_f32_16x16x32_bf16 v[116:119], v[146:149], v[190:193], v[116:119]
	v_mfma_f32_16x16x32_bf16 v[112:115], v[154:157], v[190:193], v[112:115]
	v_mfma_f32_16x16x32_bf16 v[100:103], v[146:149], v[200:203], v[100:103]
	v_mfma_f32_16x16x32_bf16 v[96:99], v[154:157], v[200:203], v[96:99]
	v_mfma_f32_16x16x32_bf16 v[84:87], v[146:149], v[208:211], v[84:87]
	v_mfma_f32_16x16x32_bf16 v[80:83], v[154:157], v[208:211], v[80:83]
	v_mfma_f32_16x16x32_bf16 v[108:111], v[162:165], v[178:181], v[108:111]
	v_mfma_f32_16x16x32_bf16 v[104:107], v[170:173], v[178:181], v[104:107]
	v_mfma_f32_16x16x32_bf16 v[92:95], v[162:165], v[186:189], v[92:95]
	v_mfma_f32_16x16x32_bf16 v[88:91], v[170:173], v[186:189], v[88:91]
	v_mfma_f32_16x16x32_bf16 v[76:79], v[162:165], v[196:199], v[76:79]
	v_mfma_f32_16x16x32_bf16 v[72:75], v[170:173], v[196:199], v[72:75]
	v_mfma_f32_16x16x32_bf16 v[68:71], v[162:165], v[204:207], v[68:71]
	v_mfma_f32_16x16x32_bf16 v[64:67], v[170:173], v[204:207], v[64:67]
	v_mfma_f32_16x16x32_bf16 v[108:111], v[166:169], v[182:185], v[108:111]
	v_mfma_f32_16x16x32_bf16 v[104:107], v[174:177], v[182:185], v[104:107]
	v_mfma_f32_16x16x32_bf16 v[92:95], v[166:169], v[190:193], v[92:95]
	v_mfma_f32_16x16x32_bf16 v[88:91], v[174:177], v[190:193], v[88:91]
	v_mfma_f32_16x16x32_bf16 v[76:79], v[166:169], v[200:203], v[76:79]
	v_mfma_f32_16x16x32_bf16 v[72:75], v[174:177], v[200:203], v[72:75]
	v_mfma_f32_16x16x32_bf16 v[68:71], v[166:169], v[208:211], v[68:71]
	v_mfma_f32_16x16x32_bf16 v[64:67], v[174:177], v[208:211], v[64:67]
	s_setprio 0
	s_barrier
; #define PG8_STAGE(bufoff, gbase, voff) do { _Pragma("unroll") for (int _i = 0; _i < 2; ++_i) \
;         __builtin_amdgcn_global_load_lds((const unsigned*)((const char*)(gbase) + (voff)[_i]), (PG8_LAS unsigned*)(lds + (bufoff) + ldsw + _i * 8192), 16, 0, 0); } while (0)
; #define PG8_LDA(dst, b, h) do { _Pragma("unroll") for (int m = 0; m < 4; ++m) _Pragma("unroll") for (int k = 0; k < 2; ++k) dst[m][k] = *(const PG8_LAS bf16x8*)(lds + PG8_SA(b, h) + aoff + m * 2048 + k * 1024); } while (0)
; #define PG8_MMA(ai, bj, At, Bt) do { __builtin_amdgcn_s_setprio(1); _Pragma("unroll") for (int m = 0; m < 4; ++m) _Pragma("unroll") for (int n = 0; n < 2; ++n) _Pragma("unroll") for (int k = 0; k < 2; ++k) \
;         acc[ai][bj][m][n] = __builtin_amdgcn_mfma_f32_16x16x32_bf16(Bt[n][k], At[m][k], acc[ai][bj][m][n], 0, 0, 0); __builtin_amdgcn_s_setprio(0); } while (0)
; #define PG8_WAIT_V(n) asm volatile("s_waitcnt vmcnt(" #n ")" ::: "memory")
; #define PG8_WAIT_L(n) asm volatile("s_waitcnt lgkmcnt(" #n ")" ::: "memory")
; #define PG8_BAR __builtin_amdgcn_s_barrier()
; #define PG8_SCHED __builtin_amdgcn_sched_barrier(0)
; template <class Epi, class Sched, bool ALIGN_EPI = false, bool SP2 = false>
; __device__ __forceinline__ void gemm_phase(PG8_LAS unsigned char* lds, const Gemm g, const Sched& S, const Epi& E) {
;     ...
;             PG8_LDA(At, 1, 1); PG8_STAGE(PG8_SB(1, 0), b3, voffB); PG8_STAGE(PG8_SB(1, 1), b3 + hstep, voffB); PG8_STAGE(PG8_SA(1, 0), a3, voffA);
;             PG8_WAIT_V(8); PG8_WAIT_L(0); PG8_BAR; PG8_MMA(1, 0, At, B0); PG8_MMA(1, 1, At, B1); PG8_BAR; PG8_SCHED;
;     ...
;         if constexpr (ALIGN_EPI) { if (wr == 0) PG8_BAR; }
	s_add_i32 s16, s45, s2
	v_lshl_add_u64 v[158:159], v[158:159], 0, s[42:43]
	s_mov_b32 m0, s16
	ds_read_b128 v[178:181], v141 offset:49152
	ds_read_b128 v[182:185], v141 offset:50176
	ds_read_b128 v[186:189], v141 offset:51200
	ds_read_b128 v[190:193], v141 offset:52224
	ds_read_b128 v[196:199], v141 offset:53248
	ds_read_b128 v[200:203], v141 offset:54272
	ds_read_b128 v[204:207], v141 offset:55296
	ds_read_b128 v[208:211], v141 offset:56320
	global_load_lds_dwordx4 v[158:159], off
	s_add_i32 m0, s16, 0x2000
	s_add_u32 s16, s20, 0xb0080
	v_lshl_add_u64 v[158:159], v[212:213], 0, s[42:43]
	s_addc_u32 s17, s21, 0
	s_add_i32 s20, s46, s2
	global_load_lds_dwordx4 v[158:159], off
	v_lshl_add_u64 v[158:159], s[16:17], 0, v[160:161]
	s_mov_b32 m0, s20
	s_nop 0
	global_load_lds_dwordx4 v[158:159], off
	v_lshl_add_u64 v[158:159], s[16:17], 0, v[128:129]
	s_add_i32 m0, s20, 0x2000
	s_nop 0
	global_load_lds_dwordx4 v[158:159], off
	v_lshl_add_u64 v[158:159], v[214:215], 0, s[42:43]
	s_mov_b32 m0, s30
	s_nop 0
	global_load_lds_dwordx4 v[158:159], off
	v_lshl_add_u64 v[158:159], v[216:217], 0, s[42:43]
	s_mov_b32 m0, s31
	s_nop 0
	global_load_lds_dwordx4 v[158:159], off
	s_waitcnt vmcnt(8)
	s_waitcnt lgkmcnt(0)
	s_barrier
	s_setprio 1
	v_mfma_f32_16x16x32_bf16 v[60:63], v[142:145], v[178:181], v[60:63]
	v_mfma_f32_16x16x32_bf16 v[56:59], v[150:153], v[178:181], v[56:59]
	v_mfma_f32_16x16x32_bf16 v[52:55], v[142:145], v[186:189], v[52:55]
	v_mfma_f32_16x16x32_bf16 v[48:51], v[150:153], v[186:189], v[48:51]
	v_mfma_f32_16x16x32_bf16 v[36:39], v[142:145], v[196:199], v[36:39]
	v_mfma_f32_16x16x32_bf16 v[32:35], v[150:153], v[196:199], v[32:35]
	v_mfma_f32_16x16x32_bf16 v[20:23], v[142:145], v[204:207], v[20:23]
	v_mfma_f32_16x16x32_bf16 v[16:19], v[150:153], v[204:207], v[16:19]
	v_mfma_f32_16x16x32_bf16 v[60:63], v[146:149], v[182:185], v[60:63]
	v_mfma_f32_16x16x32_bf16 v[56:59], v[154:157], v[182:185], v[56:59]
	v_mfma_f32_16x16x32_bf16 v[52:55], v[146:149], v[190:193], v[52:55]
	v_mfma_f32_16x16x32_bf16 v[48:51], v[154:157], v[190:193], v[48:51]
	v_mfma_f32_16x16x32_bf16 v[36:39], v[146:149], v[200:203], v[36:39]
	v_mfma_f32_16x16x32_bf16 v[32:35], v[154:157], v[200:203], v[32:35]
	v_mfma_f32_16x16x32_bf16 v[20:23], v[146:149], v[208:211], v[20:23]
	v_mfma_f32_16x16x32_bf16 v[16:19], v[154:157], v[208:211], v[16:19]
	v_mfma_f32_16x16x32_bf16 v[44:47], v[162:165], v[178:181], v[44:47]
	v_mfma_f32_16x16x32_bf16 v[40:43], v[170:173], v[178:181], v[40:43]
	v_mfma_f32_16x16x32_bf16 v[28:31], v[162:165], v[186:189], v[28:31]
	v_mfma_f32_16x16x32_bf16 v[24:27], v[170:173], v[186:189], v[24:27]
	v_mfma_f32_16x16x32_bf16 v[12:15], v[162:165], v[196:199], v[12:15]
	v_mfma_f32_16x16x32_bf16 v[8:11], v[170:173], v[196:199], v[8:11]
	v_mfma_f32_16x16x32_bf16 v[4:7], v[162:165], v[204:207], v[4:7]
	v_mfma_f32_16x16x32_bf16 v[0:3], v[170:173], v[204:207], v[0:3]
	v_mfma_f32_16x16x32_bf16 v[44:47], v[166:169], v[182:185], v[44:47]
	v_mfma_f32_16x16x32_bf16 v[40:43], v[174:177], v[182:185], v[40:43]
	v_mfma_f32_16x16x32_bf16 v[28:31], v[166:169], v[190:193], v[28:31]
	v_mfma_f32_16x16x32_bf16 v[24:27], v[174:177], v[190:193], v[24:27]
	v_mfma_f32_16x16x32_bf16 v[12:15], v[166:169], v[200:203], v[12:15]
	v_mfma_f32_16x16x32_bf16 v[8:11], v[174:177], v[200:203], v[8:11]
	v_mfma_f32_16x16x32_bf16 v[4:7], v[166:169], v[208:211], v[4:7]
	v_mfma_f32_16x16x32_bf16 v[0:3], v[174:177], v[208:211], v[0:3]
	s_setprio 0
	s_barrier
	s_add_i32 s44, s44, 2
	s_add_u32 s40, s40, 0x100
	s_addc_u32 s41, s41, 0
	s_cmp_gt_u32 s44, 41
	s_mov_b64 s[16:17], s[18:19]
	s_cbranch_scc0 .LBB0_851
	s_and_b64 vcc, exec, s[10:11]
	s_cbranch_vccz .LBB0_854
	s_barrier

; #define PG8_STAGE(bufoff, gbase, voff) do { _Pragma("unroll") for (int _i = 0; _i < 2; ++_i) \
;         __builtin_amdgcn_global_load_lds((const unsigned*)((const char*)(gbase) + (voff)[_i]), (PG8_LAS unsigned*)(lds + (bufoff) + ldsw + _i * 8192), 16, 0, 0); } while (0)
; #define PG8_LDA(dst, b, h) do { _Pragma("unroll") for (int m = 0; m < 4; ++m) _Pragma("unroll") for (int k = 0; k < 2; ++k) dst[m][k] = *(const PG8_LAS bf16x8*)(lds + PG8_SA(b, h) + aoff + m * 2048 + k * 1024); } while (0)
; #define PG8_LDB(dst, b, h) do { _Pragma("unroll") for (int n = 0; n < 2; ++n) _Pragma("unroll") for (int k = 0; k < 2; ++k) dst[n][k] = *(const PG8_LAS bf16x8*)(lds + PG8_SB(b, h) + boff + n * 2048 + k * 1024); } while (0)
; #define PG8_MMA(ai, bj, At, Bt) do { __builtin_amdgcn_s_setprio(1); _Pragma("unroll") for (int m = 0; m < 4; ++m) _Pragma("unroll") for (int n = 0; n < 2; ++n) _Pragma("unroll") for (int k = 0; k < 2; ++k) \
;         acc[ai][bj][m][n] = __builtin_amdgcn_mfma_f32_16x16x32_bf16(Bt[n][k], At[m][k], acc[ai][bj][m][n], 0, 0, 0); __builtin_amdgcn_s_setprio(0); } while (0)
; #define PG8_WAIT_V(n) asm volatile("s_waitcnt vmcnt(" #n ")" ::: "memory")
; #define PG8_WAIT_L(n) asm volatile("s_waitcnt lgkmcnt(" #n ")" ::: "memory")
; #define PG8_BAR __builtin_amdgcn_s_barrier()
; template <class Epi, class Sched, bool ALIGN_EPI = false, bool SP2 = false>
; __device__ __forceinline__ void gemm_phase(PG8_LAS unsigned char* lds, const Gemm g, const Sched& S, const Epi& E) {
;     ...
;             const char* a1 = cA + (size_t)(t + 1) * kstep;
;             const char* a2 = last ? nA : cA + (size_t)(t + 2) * kstep; const char* b2 = last ? nB : cB + (size_t)(t + 2) * kstep;
;             const char* a3 = a2 + kstep; const char* b3 = b2 + kstep;
;             if (last && has_next) S.a_ready(nxt);
;             if constexpr (SP2) {
;             PG8_LDB(B0, 0, 0); PG8_LDB(B1, 0, 1); PG8_SCHED; PG8_LDA(At, 0, 0); PG8_STAGE(PG8_SA(1, 1), a1 + hstep, voffA);
;             PG8_WAIT_V(8); PG8_WAIT_L(0); PG8_BAR; PG8_MMA(0, 0, At, B0); PG8_MMA(0, 1, At, B1); PG8_BAR; PG8_SCHED;
;             PG8_LDA(At, 0, 1); PG8_STAGE(PG8_SB(0, 0), b2, voffB); PG8_STAGE(PG8_SB(0, 1), b2 + hstep, voffB); PG8_STAGE(PG8_SA(0, 0), a2, voffA);
;             PG8_WAIT_V(8); PG8_WAIT_L(0); PG8_BAR; PG8_MMA(1, 0, At, B0); PG8_MMA(1, 1, At, B1); PG8_BAR; PG8_SCHED;
.LBB0_924:
	s_add_u32 s16, s6, 0xf5750080
	s_addc_u32 s17, s7, -1
	s_cmp_lg_u32 s28, 40
	s_cselect_b32 s16, s16, 0
	s_cselect_b32 s17, s17, 0
	s_add_u32 s18, s34, s16
	s_addc_u32 s19, s35, s17
	s_add_i32 s29, 0, 0x10000
	s_add_u32 s16, s0, s16
	v_add_u32_e32 v145, s29, v143
	s_addc_u32 s17, s1, s17
	s_add_i32 s33, 0, 0x14000
	ds_read_b128 v[146:149], v145
	ds_read_b128 v[150:153], v145 offset:1024
	ds_read_b128 v[154:157], v145 offset:2048
	ds_read_b128 v[162:165], v145 offset:3072
	v_add_u32_e32 v145, s33, v143
	ds_read_b128 v[166:169], v145
	ds_read_b128 v[170:173], v145 offset:1024
	ds_read_b128 v[174:177], v145 offset:2048
	ds_read_b128 v[178:181], v145 offset:3072
	v_lshl_add_u64 v[158:159], v[134:135], 0, s[6:7]
	s_add_i32 m0, s21, 0xc000
	ds_read_b128 v[182:185], v144
	ds_read_b128 v[186:189], v144 offset:1024
	ds_read_b128 v[190:193], v144 offset:2048
	ds_read_b128 v[196:199], v144 offset:3072
	ds_read_b128 v[200:203], v144 offset:4096
	ds_read_b128 v[204:207], v144 offset:5120
	ds_read_b128 v[208:211], v144 offset:6144
	ds_read_b128 v[212:215], v144 offset:7168
	global_load_lds_dwordx4 v[158:159], off
	v_lshl_add_u64 v[158:159], v[136:137], 0, s[6:7]
	s_add_i32 m0, s21, 0xe000
	s_nop 0
	global_load_lds_dwordx4 v[158:159], off
	s_waitcnt vmcnt(8)
	s_waitcnt lgkmcnt(0)
	s_barrier
	s_setprio 1
	v_mfma_f32_16x16x32_bf16 v[124:127], v[146:149], v[182:185], v[124:127]
	v_mfma_f32_16x16x32_bf16 v[120:123], v[154:157], v[182:185], v[120:123]
	v_mfma_f32_16x16x32_bf16 v[116:119], v[146:149], v[190:193], v[116:119]
	v_mfma_f32_16x16x32_bf16 v[112:115], v[154:157], v[190:193], v[112:115]
	v_mfma_f32_16x16x32_bf16 v[100:103], v[146:149], v[200:203], v[100:103]
	v_mfma_f32_16x16x32_bf16 v[96:99], v[154:157], v[200:203], v[96:99]
	v_mfma_f32_16x16x32_bf16 v[84:87], v[146:149], v[208:211], v[84:87]
	v_mfma_f32_16x16x32_bf16 v[80:83], v[154:157], v[208:211], v[80:83]
	v_mfma_f32_16x16x32_bf16 v[124:127], v[150:153], v[186:189], v[124:127]
	v_mfma_f32_16x16x32_bf16 v[120:123], v[162:165], v[186:189], v[120:123]
	v_mfma_f32_16x16x32_bf16 v[116:119], v[150:153], v[196:199], v[116:119]
	v_mfma_f32_16x16x32_bf16 v[112:115], v[162:165], v[196:199], v[112:115]
	v_mfma_f32_16x16x32_bf16 v[100:103], v[150:153], v[204:207], v[100:103]
	v_mfma_f32_16x16x32_bf16 v[96:99], v[162:165], v[204:207], v[96:99]
	v_mfma_f32_16x16x32_bf16 v[84:87], v[150:153], v[212:215], v[84:87]
	v_mfma_f32_16x16x32_bf16 v[80:83], v[162:165], v[212:215], v[80:83]
	v_mfma_f32_16x16x32_bf16 v[108:111], v[166:169], v[182:185], v[108:111]
	v_mfma_f32_16x16x32_bf16 v[104:107], v[174:177], v[182:185], v[104:107]
	v_mfma_f32_16x16x32_bf16 v[92:95], v[166:169], v[190:193], v[92:95]
	v_mfma_f32_16x16x32_bf16 v[88:91], v[174:177], v[190:193], v[88:91]
	v_mfma_f32_16x16x32_bf16 v[76:79], v[166:169], v[200:203], v[76:79]
	v_mfma_f32_16x16x32_bf16 v[72:75], v[174:177], v[200:203], v[72:75]
	v_mfma_f32_16x16x32_bf16 v[68:71], v[166:169], v[208:211], v[68:71]
	v_mfma_f32_16x16x32_bf16 v[64:67], v[174:177], v[208:211], v[64:67]
	v_mfma_f32_16x16x32_bf16 v[108:111], v[170:173], v[186:189], v[108:111]
	v_mfma_f32_16x16x32_bf16 v[104:107], v[178:181], v[186:189], v[104:107]
	v_mfma_f32_16x16x32_bf16 v[92:95], v[170:173], v[196:199], v[92:95]
	v_mfma_f32_16x16x32_bf16 v[88:91], v[178:181], v[196:199], v[88:91]
	v_mfma_f32_16x16x32_bf16 v[76:79], v[170:173], v[204:207], v[76:79]
	v_mfma_f32_16x16x32_bf16 v[72:75], v[178:181], v[204:207], v[72:75]
	v_mfma_f32_16x16x32_bf16 v[68:71], v[170:173], v[212:215], v[68:71]
	v_mfma_f32_16x16x32_bf16 v[64:67], v[178:181], v[212:215], v[64:67]
	s_setprio 0
	s_barrier
	s_add_i32 s29, s29, s20
	v_lshl_add_u64 v[158:159], s[16:17], 0, v[160:161]
	s_mov_b32 m0, s29
	ds_read_b128 v[182:185], v144 offset:16384
	ds_read_b128 v[186:189], v144 offset:17408
	ds_read_b128 v[190:193], v144 offset:18432
	ds_read_b128 v[196:199], v144 offset:19456
	ds_read_b128 v[200:203], v144 offset:20480
	ds_read_b128 v[204:207], v144 offset:21504
	ds_read_b128 v[208:211], v144 offset:22528
	ds_read_b128 v[212:215], v144 offset:23552
	global_load_lds_dwordx4 v[158:159], off
	s_add_i32 m0, s29, 0x2000
	s_add_u32 s30, s16, 0xb0000
	v_lshl_add_u64 v[216:217], s[16:17], 0, v[132:133]
	s_addc_u32 s31, s17, 0
	s_add_i32 s29, s33, s20
	global_load_lds_dwordx4 v[216:217], off
	v_lshl_add_u64 v[228:229], s[30:31], 0, v[160:161]
	s_mov_b32 m0, s29
	v_lshl_add_u64 v[230:231], s[18:19], 0, v[130:131]
	global_load_lds_dwordx4 v[228:229], off
	v_lshl_add_u64 v[228:229], s[30:31], 0, v[132:133]
	s_add_i32 m0, s29, 0x2000
	s_nop 0
	global_load_lds_dwordx4 v[228:229], off
	v_lshl_add_u64 v[228:229], s[18:19], 0, v[128:129]
	s_mov_b32 m0, s21
	s_nop 0
	global_load_lds_dwordx4 v[228:229], off
	s_mov_b32 m0, s22
	s_nop 0
	global_load_lds_dwordx4 v[230:231], off
	s_waitcnt vmcnt(8)
	s_waitcnt lgkmcnt(0)
	s_barrier
; #define PG8_STAGE(bufoff, gbase, voff) do { _Pragma("unroll") for (int _i = 0; _i < 2; ++_i) \
;         __builtin_amdgcn_global_load_lds((const unsigned*)((const char*)(gbase) + (voff)[_i]), (PG8_LAS unsigned*)(lds + (bufoff) + ldsw + _i * 8192), 16, 0, 0); } while (0)
; #define PG8_LDA(dst, b, h) do { _Pragma("unroll") for (int m = 0; m < 4; ++m) _Pragma("unroll") for (int k = 0; k < 2; ++k) dst[m][k] = *(const PG8_LAS bf16x8*)(lds + PG8_SA(b, h) + aoff + m * 2048 + k * 1024); } while (0)
; #define PG8_LDB(dst, b, h) do { _Pragma("unroll") for (int n = 0; n < 2; ++n) _Pragma("unroll") for (int k = 0; k < 2; ++k) dst[n][k] = *(const PG8_LAS bf16x8*)(lds + PG8_SB(b, h) + boff + n * 2048 + k * 1024); } while (0)
; #define PG8_MMA(ai, bj, At, Bt) do { __builtin_amdgcn_s_setprio(1); _Pragma("unroll") for (int m = 0; m < 4; ++m) _Pragma("unroll") for (int n = 0; n < 2; ++n) _Pragma("unroll") for (int k = 0; k < 2; ++k) \
;         acc[ai][bj][m][n] = __builtin_amdgcn_mfma_f32_16x16x32_bf16(Bt[n][k], At[m][k], acc[ai][bj][m][n], 0, 0, 0); __builtin_amdgcn_s_setprio(0); } while (0)
; #define PG8_WAIT_V(n) asm volatile("s_waitcnt vmcnt(" #n ")" ::: "memory")
; #define PG8_WAIT_L(n) asm volatile("s_waitcnt lgkmcnt(" #n ")" ::: "memory")
; #define PG8_BAR __builtin_amdgcn_s_barrier()
; #define PG8_SCHED __builtin_amdgcn_sched_barrier(0)
; template <class Epi, class Sched, bool ALIGN_EPI = false, bool SP2 = false>
; __device__ __forceinline__ void gemm_phase(PG8_LAS unsigned char* lds, const Gemm g, const Sched& S, const Epi& E) {
;     ...
;             PG8_WAIT_V(8); PG8_WAIT_L(0); PG8_BAR; PG8_MMA(1, 0, At, B0); PG8_MMA(1, 1, At, B1); PG8_BAR; PG8_SCHED;
;             PG8_LDB(B0, 1, 0); PG8_LDB(B1, 1, 1); PG8_SCHED; PG8_LDA(At, 1, 0); PG8_STAGE(PG8_SA(0, 1), a2 + hstep, voffA);
;             PG8_WAIT_V(8); PG8_WAIT_L(0); PG8_BAR; PG8_MMA(0, 0, At, B0); PG8_MMA(0, 1, At, B1); PG8_BAR; PG8_SCHED;
	s_setprio 1
	v_mfma_f32_16x16x32_bf16 v[60:63], v[146:149], v[182:185], v[60:63]
	v_mfma_f32_16x16x32_bf16 v[56:59], v[154:157], v[182:185], v[56:59]
	v_mfma_f32_16x16x32_bf16 v[52:55], v[146:149], v[190:193], v[52:55]
	v_mfma_f32_16x16x32_bf16 v[48:51], v[154:157], v[190:193], v[48:51]
	v_mfma_f32_16x16x32_bf16 v[36:39], v[146:149], v[200:203], v[36:39]
	v_mfma_f32_16x16x32_bf16 v[32:35], v[154:157], v[200:203], v[32:35]
	v_mfma_f32_16x16x32_bf16 v[20:23], v[146:149], v[208:211], v[20:23]
	v_mfma_f32_16x16x32_bf16 v[16:19], v[154:157], v[208:211], v[16:19]
	v_mfma_f32_16x16x32_bf16 v[60:63], v[150:153], v[186:189], v[60:63]
	v_mfma_f32_16x16x32_bf16 v[56:59], v[162:165], v[186:189], v[56:59]
	v_mfma_f32_16x16x32_bf16 v[52:55], v[150:153], v[196:199], v[52:55]
	v_mfma_f32_16x16x32_bf16 v[48:51], v[162:165], v[196:199], v[48:51]
	v_mfma_f32_16x16x32_bf16 v[36:39], v[150:153], v[204:207], v[36:39]
	v_mfma_f32_16x16x32_bf16 v[32:35], v[162:165], v[204:207], v[32:35]
	v_mfma_f32_16x16x32_bf16 v[20:23], v[150:153], v[212:215], v[20:23]
	v_mfma_f32_16x16x32_bf16 v[16:19], v[162:165], v[212:215], v[16:19]
	v_mfma_f32_16x16x32_bf16 v[44:47], v[166:169], v[182:185], v[44:47]
	v_mfma_f32_16x16x32_bf16 v[40:43], v[174:177], v[182:185], v[40:43]
	v_mfma_f32_16x16x32_bf16 v[28:31], v[166:169], v[190:193], v[28:31]
	v_mfma_f32_16x16x32_bf16 v[24:27], v[174:177], v[190:193], v[24:27]
	v_mfma_f32_16x16x32_bf16 v[12:15], v[166:169], v[200:203], v[12:15]
	v_mfma_f32_16x16x32_bf16 v[8:11], v[174:177], v[200:203], v[8:11]
	v_mfma_f32_16x16x32_bf16 v[4:7], v[166:169], v[208:211], v[4:7]
	v_mfma_f32_16x16x32_bf16 v[0:3], v[174:177], v[208:211], v[0:3]
	v_mfma_f32_16x16x32_bf16 v[44:47], v[170:173], v[186:189], v[44:47]
	v_mfma_f32_16x16x32_bf16 v[40:43], v[178:181], v[186:189], v[40:43]
	v_mfma_f32_16x16x32_bf16 v[28:31], v[170:173], v[196:199], v[28:31]
	v_mfma_f32_16x16x32_bf16 v[24:27], v[178:181], v[196:199], v[24:27]
	v_mfma_f32_16x16x32_bf16 v[12:15], v[170:173], v[204:207], v[12:15]
	v_mfma_f32_16x16x32_bf16 v[8:11], v[178:181], v[204:207], v[8:11]
	v_mfma_f32_16x16x32_bf16 v[4:7], v[170:173], v[212:215], v[4:7]
	v_mfma_f32_16x16x32_bf16 v[0:3], v[178:181], v[212:215], v[0:3]
	s_setprio 0
	s_barrier
	s_add_i32 s29, 0, 0x18000
	v_add_u32_e32 v145, s29, v143
	s_add_i32 s30, 0, 0x1c000
	ds_read_b128 v[146:149], v145
	ds_read_b128 v[150:153], v145 offset:1024
	ds_read_b128 v[154:157], v145 offset:2048
	ds_read_b128 v[162:165], v145 offset:3072
	v_add_u32_e32 v145, s30, v143
	ds_read_b128 v[166:169], v145
	ds_read_b128 v[170:173], v145 offset:1024
	ds_read_b128 v[174:177], v145 offset:2048
	ds_read_b128 v[178:181], v145 offset:3072
	s_add_u32 s18, s18, 0xb0000
	s_addc_u32 s19, s19, 0
	s_mov_b32 m0, s23
	v_lshl_add_u64 v[232:233], s[18:19], 0, v[128:129]
	ds_read_b128 v[182:185], v144 offset:32768
	ds_read_b128 v[186:189], v144 offset:33792
	ds_read_b128 v[190:193], v144 offset:34816
	ds_read_b128 v[196:199], v144 offset:35840
	ds_read_b128 v[200:203], v144 offset:36864
	ds_read_b128 v[204:207], v144 offset:37888
	ds_read_b128 v[208:211], v144 offset:38912
	ds_read_b128 v[212:215], v144 offset:39936
	global_load_lds_dwordx4 v[232:233], off
	v_lshl_add_u64 v[232:233], s[18:19], 0, v[130:131]
	s_mov_b32 m0, s24
	s_nop 0
	global_load_lds_dwordx4 v[232:233], off
	s_waitcnt vmcnt(8)
	s_waitcnt lgkmcnt(0)
	s_barrier
	s_setprio 1
	v_mfma_f32_16x16x32_bf16 v[124:127], v[146:149], v[182:185], v[124:127]
	v_mfma_f32_16x16x32_bf16 v[120:123], v[154:157], v[182:185], v[120:123]
	v_mfma_f32_16x16x32_bf16 v[116:119], v[146:149], v[190:193], v[116:119]
	v_mfma_f32_16x16x32_bf16 v[112:115], v[154:157], v[190:193], v[112:115]
	v_mfma_f32_16x16x32_bf16 v[100:103], v[146:149], v[200:203], v[100:103]
	v_mfma_f32_16x16x32_bf16 v[96:99], v[154:157], v[200:203], v[96:99]
	v_mfma_f32_16x16x32_bf16 v[84:87], v[146:149], v[208:211], v[84:87]
	v_mfma_f32_16x16x32_bf16 v[80:83], v[154:157], v[208:211], v[80:83]
	v_mfma_f32_16x16x32_bf16 v[124:127], v[150:153], v[186:189], v[124:127]
	v_mfma_f32_16x16x32_bf16 v[120:123], v[162:165], v[186:189], v[120:123]
	v_mfma_f32_16x16x32_bf16 v[116:119], v[150:153], v[196:199], v[116:119]
	v_mfma_f32_16x16x32_bf16 v[112:115], v[162:165], v[196:199], v[112:115]
	v_mfma_f32_16x16x32_bf16 v[100:103], v[150:153], v[204:207], v[100:103]
	v_mfma_f32_16x16x32_bf16 v[96:99], v[162:165], v[204:207], v[96:99]
	v_mfma_f32_16x16x32_bf16 v[84:87], v[150:153], v[212:215], v[84:87]
	v_mfma_f32_16x16x32_bf16 v[80:83], v[162:165], v[212:215], v[80:83]
	v_mfma_f32_16x16x32_bf16 v[108:111], v[166:169], v[182:185], v[108:111]
	v_mfma_f32_16x16x32_bf16 v[104:107], v[174:177], v[182:185], v[104:107]
	v_mfma_f32_16x16x32_bf16 v[92:95], v[166:169], v[190:193], v[92:95]
	v_mfma_f32_16x16x32_bf16 v[88:91], v[174:177], v[190:193], v[88:91]
	v_mfma_f32_16x16x32_bf16 v[76:79], v[166:169], v[200:203], v[76:79]
	v_mfma_f32_16x16x32_bf16 v[72:75], v[174:177], v[200:203], v[72:75]
	v_mfma_f32_16x16x32_bf16 v[68:71], v[166:169], v[208:211], v[68:71]
	v_mfma_f32_16x16x32_bf16 v[64:67], v[174:177], v[208:211], v[64:67]
	v_mfma_f32_16x16x32_bf16 v[108:111], v[170:173], v[186:189], v[108:111]
	v_mfma_f32_16x16x32_bf16 v[104:107], v[178:181], v[186:189], v[104:107]
	v_mfma_f32_16x16x32_bf16 v[92:95], v[170:173], v[196:199], v[92:95]
	v_mfma_f32_16x16x32_bf16 v[88:91], v[178:181], v[196:199], v[88:91]
	v_mfma_f32_16x16x32_bf16 v[76:79], v[170:173], v[204:207], v[76:79]
	v_mfma_f32_16x16x32_bf16 v[72:75], v[178:181], v[204:207], v[72:75]
	v_mfma_f32_16x16x32_bf16 v[68:71], v[170:173], v[212:215], v[68:71]
	v_mfma_f32_16x16x32_bf16 v[64:67], v[178:181], v[212:215], v[64:67]
	s_setprio 0
	s_barrier
; #define PG8_STAGE(bufoff, gbase, voff) do { _Pragma("unroll") for (int _i = 0; _i < 2; ++_i) \
;         __builtin_amdgcn_global_load_lds((const unsigned*)((const char*)(gbase) + (voff)[_i]), (PG8_LAS unsigned*)(lds + (bufoff) + ldsw + _i * 8192), 16, 0, 0); } while (0)
; #define PG8_LDA(dst, b, h) do { _Pragma("unroll") for (int m = 0; m < 4; ++m) _Pragma("unroll") for (int k = 0; k < 2; ++k) dst[m][k] = *(const PG8_LAS bf16x8*)(lds + PG8_SA(b, h) + aoff + m * 2048 + k * 1024); } while (0)
; #define PG8_MMA(ai, bj, At, Bt) do { __builtin_amdgcn_s_setprio(1); _Pragma("unroll") for (int m = 0; m < 4; ++m) _Pragma("unroll") for (int n = 0; n < 2; ++n) _Pragma("unroll") for (int k = 0; k < 2; ++k) \
;         acc[ai][bj][m][n] = __builtin_amdgcn_mfma_f32_16x16x32_bf16(Bt[n][k], At[m][k], acc[ai][bj][m][n], 0, 0, 0); __builtin_amdgcn_s_setprio(0); } while (0)
; #define PG8_WAIT_V(n) asm volatile("s_waitcnt vmcnt(" #n ")" ::: "memory")
; #define PG8_WAIT_L(n) asm volatile("s_waitcnt lgkmcnt(" #n ")" ::: "memory")
; #define PG8_BAR __builtin_amdgcn_s_barrier()
; #define PG8_SCHED __builtin_amdgcn_sched_barrier(0)
; template <class Epi, class Sched, bool ALIGN_EPI = false, bool SP2 = false>
; __device__ __forceinline__ void gemm_phase(PG8_LAS unsigned char* lds, const Gemm g, const Sched& S, const Epi& E) {
;     ...
;             PG8_LDA(At, 1, 1); PG8_STAGE(PG8_SB(1, 0), b3, voffB); PG8_STAGE(PG8_SB(1, 1), b3 + hstep, voffB); PG8_STAGE(PG8_SA(1, 0), a3, voffA);
;             PG8_WAIT_V(8); PG8_WAIT_L(0); PG8_BAR; PG8_MMA(1, 0, At, B0); PG8_MMA(1, 1, At, B1); PG8_BAR; PG8_SCHED;
;     ...
;         if constexpr (ALIGN_EPI) { if (wr == 0) PG8_BAR; }
	s_add_i32 s18, s29, s20
	v_lshl_add_u64 v[158:159], v[158:159], 0, s[42:43]
	s_mov_b32 m0, s18
	ds_read_b128 v[182:185], v144 offset:49152
	ds_read_b128 v[186:189], v144 offset:50176
	ds_read_b128 v[190:193], v144 offset:51200
	ds_read_b128 v[196:199], v144 offset:52224
	ds_read_b128 v[200:203], v144 offset:53248
	ds_read_b128 v[204:207], v144 offset:54272
	ds_read_b128 v[208:211], v144 offset:55296
	ds_read_b128 v[212:215], v144 offset:56320
	global_load_lds_dwordx4 v[158:159], off
	s_add_i32 m0, s18, 0x2000
	s_add_u32 s16, s16, 0xb0080
	v_lshl_add_u64 v[158:159], v[216:217], 0, s[42:43]
	s_addc_u32 s17, s17, 0
	s_add_i32 s18, s30, s20
	global_load_lds_dwordx4 v[158:159], off
	v_lshl_add_u64 v[158:159], s[16:17], 0, v[160:161]
	s_mov_b32 m0, s18
	s_nop 0
	global_load_lds_dwordx4 v[158:159], off
	v_lshl_add_u64 v[158:159], s[16:17], 0, v[132:133]
	s_add_i32 m0, s18, 0x2000
	s_nop 0
	global_load_lds_dwordx4 v[158:159], off
	v_lshl_add_u64 v[158:159], v[228:229], 0, s[42:43]
	s_mov_b32 m0, s26
	s_nop 0
	global_load_lds_dwordx4 v[158:159], off
	v_lshl_add_u64 v[158:159], v[230:231], 0, s[42:43]
	s_mov_b32 m0, s27
	s_nop 0
	global_load_lds_dwordx4 v[158:159], off
	s_waitcnt vmcnt(8)
	s_waitcnt lgkmcnt(0)
	s_barrier
	s_setprio 1
	v_mfma_f32_16x16x32_bf16 v[60:63], v[146:149], v[182:185], v[60:63]
	v_mfma_f32_16x16x32_bf16 v[56:59], v[154:157], v[182:185], v[56:59]
	v_mfma_f32_16x16x32_bf16 v[52:55], v[146:149], v[190:193], v[52:55]
	v_mfma_f32_16x16x32_bf16 v[48:51], v[154:157], v[190:193], v[48:51]
	v_mfma_f32_16x16x32_bf16 v[36:39], v[146:149], v[200:203], v[36:39]
	v_mfma_f32_16x16x32_bf16 v[32:35], v[154:157], v[200:203], v[32:35]
	v_mfma_f32_16x16x32_bf16 v[20:23], v[146:149], v[208:211], v[20:23]
	v_mfma_f32_16x16x32_bf16 v[16:19], v[154:157], v[208:211], v[16:19]
	v_mfma_f32_16x16x32_bf16 v[60:63], v[150:153], v[186:189], v[60:63]
	v_mfma_f32_16x16x32_bf16 v[56:59], v[162:165], v[186:189], v[56:59]
	v_mfma_f32_16x16x32_bf16 v[52:55], v[150:153], v[196:199], v[52:55]
	v_mfma_f32_16x16x32_bf16 v[48:51], v[162:165], v[196:199], v[48:51]
	v_mfma_f32_16x16x32_bf16 v[36:39], v[150:153], v[204:207], v[36:39]
	v_mfma_f32_16x16x32_bf16 v[32:35], v[162:165], v[204:207], v[32:35]
	v_mfma_f32_16x16x32_bf16 v[20:23], v[150:153], v[212:215], v[20:23]
	v_mfma_f32_16x16x32_bf16 v[16:19], v[162:165], v[212:215], v[16:19]
	v_mfma_f32_16x16x32_bf16 v[44:47], v[166:169], v[182:185], v[44:47]
	v_mfma_f32_16x16x32_bf16 v[40:43], v[174:177], v[182:185], v[40:43]
	v_mfma_f32_16x16x32_bf16 v[28:31], v[166:169], v[190:193], v[28:31]
	v_mfma_f32_16x16x32_bf16 v[24:27], v[174:177], v[190:193], v[24:27]
	v_mfma_f32_16x16x32_bf16 v[12:15], v[166:169], v[200:203], v[12:15]
	v_mfma_f32_16x16x32_bf16 v[8:11], v[174:177], v[200:203], v[8:11]
	v_mfma_f32_16x16x32_bf16 v[4:7], v[166:169], v[208:211], v[4:7]
	v_mfma_f32_16x16x32_bf16 v[0:3], v[174:177], v[208:211], v[0:3]
	v_mfma_f32_16x16x32_bf16 v[44:47], v[170:173], v[186:189], v[44:47]
	v_mfma_f32_16x16x32_bf16 v[40:43], v[178:181], v[186:189], v[40:43]
	v_mfma_f32_16x16x32_bf16 v[28:31], v[170:173], v[196:199], v[28:31]
	v_mfma_f32_16x16x32_bf16 v[24:27], v[178:181], v[196:199], v[24:27]
	v_mfma_f32_16x16x32_bf16 v[12:15], v[170:173], v[204:207], v[12:15]
	v_mfma_f32_16x16x32_bf16 v[8:11], v[178:181], v[204:207], v[8:11]
	v_mfma_f32_16x16x32_bf16 v[4:7], v[170:173], v[212:215], v[4:7]
	v_mfma_f32_16x16x32_bf16 v[0:3], v[178:181], v[212:215], v[0:3]
	s_setprio 0
	s_barrier
	s_add_i32 s28, s28, 2
	s_add_u32 s6, s6, 0x100
	s_addc_u32 s7, s7, 0
	s_cmp_gt_u32 s28, 41
	s_cbranch_scc0 .LBB0_924
	s_cmpk_lt_u32 s2, 0x100
	s_cbranch_scc0 .LBB0_927
	s_barrier
